# no s_setprio toggling in the GEMM K-loops (88 scalar instructions removed), on cvb
# speedup vs baseline: 1.0049x; 1.0049x over previous
;     __host__ __device__ bool next(int i, Unit& u) const { const long L = (long)i * G + c; if (L >= nwg) return false; return unit_of((int)L, u); }
;     __host__ __device__ bool next(int i, Unit& u) const { const int L = i == 0 ? l0 : (i == 1 ? l1 : (i == 2 ? l2 : -1)); if (L < 0 || L >= s.nwg) return false; return s.unit_of(L, u); }
;     __host__ __device__ bool next(int i, Unit& u) const { const bool ok = s.next(i >> 1, u); u.kh = i & 1; return ok; }
; #define PG8_STAGE(bufoff, gbase, voff) do { _Pragma("unroll") for (int _i = 0; _i < 2; ++_i) \
;         __builtin_amdgcn_global_load_lds((const unsigned*)((const char*)(gbase) + (voff)[_i]), (PG8_LAS unsigned*)(lds + (bufoff) + ldsw + _i * 8192), 16, 0, 0); } while (0)
; #define PG8_LDA(dst, b, h) do { _Pragma("unroll") for (int m = 0; m < 4; ++m) _Pragma("unroll") for (int k = 0; k < 2; ++k) dst[m][k] = *(const PG8_LAS bf16x8*)(lds + PG8_SA(b, h) + aoff + m * 2048 + k * 1024); } while (0)
; template <class Epi, class Sched, bool ALIGN_EPI = false, bool SP2 = false>
; __device__ __forceinline__ void gemm_phase(PG8_LAS unsigned char* lds, const Gemm g, const Sched& S, const Epi& E) {
;     ...
;         const bool has_next = S.next(ui + 1, nxt);
;         const char* nA = has_next ? (const char*)g.A + (size_t)nxt.pm * tstep + nxt.kh * khb : cA; const char* nB = has_next ? (const char*)g.Bt + (size_t)nxt.pn * tstep + nxt.kh * khb : cB;
;         for (int t = 0; t < nt; t += 2) {
;             const bool last = (t == nt - 2);
;             const char* a1 = cA + (size_t)(t + 1) * kstep;
;             const char* a2 = last ? nA : cA + (size_t)(t + 2) * kstep; const char* b2 = last ? nB : cB + (size_t)(t + 2) * kstep;
;             const char* a3 = a2 + kstep; const char* b3 = b2 + kstep;
;             if (last && has_next) S.a_ready(nxt);
;             if constexpr (SP2) {
;             PG8_LDB(B0, 0, 0); PG8_LDB(B1, 0, 1); PG8_SCHED; PG8_LDA(At, 0, 0); PG8_STAGE(PG8_SA(1, 1), a1 + hstep, voffA);
;             PG8_WAIT_V(8); PG8_WAIT_L(0); PG8_BAR; PG8_MMA(0, 0, At, B0); PG8_MMA(0, 1, At, B1); PG8_BAR; PG8_SCHED;
;             PG8_LDA(At, 0, 1); PG8_STAGE(PG8_SB(0, 0), b2, voffB); PG8_STAGE(PG8_SB(0, 1), b2 + hstep, voffB); PG8_STAGE(PG8_SA(0, 0), a2, voffA);
;             PG8_WAIT_V(8); PG8_WAIT_L(0); PG8_BAR; PG8_MMA(1, 0, At, B0); PG8_MMA(1, 1, At, B1); PG8_BAR; PG8_SCHED;
.LBB0_95:
	s_waitcnt lgkmcnt(0)
	s_ashr_i32 s55, s54, 31
	s_lshl_b64 s[34:35], s[54:55], 19
	s_add_u32 s76, s50, s34
	s_addc_u32 s77, s51, s35
	s_and_b64 s[34:35], s[2:3], exec
	s_cselect_b32 s8, s77, s81
	s_cselect_b32 s55, s76, s80
	s_ashr_i32 s49, s48, 31
	s_lshl_b64 s[34:35], s[48:49], 19
	s_add_u32 s78, s88, s34
	s_addc_u32 s79, s89, s35
	s_and_b64 s[34:35], s[2:3], exec
	s_cselect_b32 s49, s79, s83
	s_cselect_b32 vcc_lo, s78, s82
	s_add_u32 s80, s80, 0x40080
	s_addc_u32 s81, s81, 0
	s_add_u32 vcc_hi, s82, 0x100
	s_addc_u32 s34, s83, 0
	s_mov_b32 s35, -2
	ds_read_b128 v[128:131], v178
	ds_read_b128 v[132:135], v178 offset:1024
	ds_read_b128 v[136:139], v178 offset:2048
	ds_read_b128 v[140:143], v178 offset:3072
	ds_read_b128 v[166:169], v179
	ds_read_b128 v[170:173], v179 offset:1024
	ds_read_b128 v[190:193], v179 offset:2048
	ds_read_b128 v[194:197], v179 offset:3072
	s_add_u32 s36, s80, 0xfffc0080
	s_addc_u32 s37, s81, -1
	s_cmp_eq_u32 s35, 12
	s_cselect_b32 s87, s8, s37
	s_cselect_b32 s86, s55, s36
	s_cselect_b32 s83, s49, s34
	s_cselect_b32 s82, vcc_lo, vcc_hi
	s_add_i32 m0, s93, 0xc000
	ds_read_b128 v[198:201], v181
	ds_read_b128 v[202:205], v181 offset:1024
	ds_read_b128 v[206:209], v181 offset:2048
	ds_read_b128 v[210:213], v181 offset:3072
	ds_read_b128 v[214:217], v181 offset:4096
	ds_read_b128 v[218:221], v181 offset:5120
	ds_read_b128 v[222:225], v181 offset:6144
	ds_read_b128 v[226:229], v181 offset:7168
	global_load_lds_dwordx4 v158, s[80:81]
	s_add_i32 m0, s93, 0xe000
	s_nop 0
	global_load_lds_dwordx4 v160, s[80:81]
	s_waitcnt vmcnt(8)
	s_waitcnt lgkmcnt(0)
	s_barrier
	v_mfma_f32_16x16x32_bf16 v[124:127], v[128:131], v[198:201], 0
	v_mfma_f32_16x16x32_bf16 v[120:123], v[136:139], v[198:201], 0
	v_mfma_f32_16x16x32_bf16 v[108:111], v[128:131], v[206:209], 0
	v_mfma_f32_16x16x32_bf16 v[104:107], v[136:139], v[206:209], 0
	v_mfma_f32_16x16x32_bf16 v[92:95], v[128:131], v[214:217], 0
	v_mfma_f32_16x16x32_bf16 v[88:91], v[136:139], v[214:217], 0
	v_mfma_f32_16x16x32_bf16 v[76:79], v[128:131], v[222:225], 0
	v_mfma_f32_16x16x32_bf16 v[72:75], v[136:139], v[222:225], 0
	v_mfma_f32_16x16x32_bf16 v[124:127], v[132:135], v[202:205], v[124:127]
	v_mfma_f32_16x16x32_bf16 v[120:123], v[140:143], v[202:205], v[120:123]
	v_mfma_f32_16x16x32_bf16 v[108:111], v[132:135], v[210:213], v[108:111]
	v_mfma_f32_16x16x32_bf16 v[104:107], v[140:143], v[210:213], v[104:107]
	v_mfma_f32_16x16x32_bf16 v[92:95], v[132:135], v[218:221], v[92:95]
	v_mfma_f32_16x16x32_bf16 v[88:91], v[140:143], v[218:221], v[88:91]
	v_mfma_f32_16x16x32_bf16 v[76:79], v[132:135], v[226:229], v[76:79]
	v_mfma_f32_16x16x32_bf16 v[72:75], v[140:143], v[226:229], v[72:75]
	v_mfma_f32_16x16x32_bf16 v[116:119], v[166:169], v[198:201], 0
	v_mfma_f32_16x16x32_bf16 v[112:115], v[190:193], v[198:201], 0
	v_mfma_f32_16x16x32_bf16 v[100:103], v[166:169], v[206:209], 0
	v_mfma_f32_16x16x32_bf16 v[96:99], v[190:193], v[206:209], 0
	v_mfma_f32_16x16x32_bf16 v[84:87], v[166:169], v[214:217], 0
	v_mfma_f32_16x16x32_bf16 v[80:83], v[190:193], v[214:217], 0
	v_mfma_f32_16x16x32_bf16 v[68:71], v[166:169], v[222:225], 0
	v_mfma_f32_16x16x32_bf16 v[64:67], v[190:193], v[222:225], 0
	v_mfma_f32_16x16x32_bf16 v[116:119], v[170:173], v[202:205], v[116:119]
	v_mfma_f32_16x16x32_bf16 v[112:115], v[194:197], v[202:205], v[112:115]
	v_mfma_f32_16x16x32_bf16 v[100:103], v[170:173], v[210:213], v[100:103]
	v_mfma_f32_16x16x32_bf16 v[96:99], v[194:197], v[210:213], v[96:99]
	v_mfma_f32_16x16x32_bf16 v[84:87], v[170:173], v[218:221], v[84:87]
	v_mfma_f32_16x16x32_bf16 v[80:83], v[194:197], v[218:221], v[80:83]
	v_mfma_f32_16x16x32_bf16 v[68:71], v[170:173], v[226:229], v[68:71]
	v_mfma_f32_16x16x32_bf16 v[64:67], v[194:197], v[226:229], v[64:67]
	s_barrier
	s_add_u32 s98, s82, s26
	s_addc_u32 s99, s83, s27
	s_add_u32 s100, s86, s26
	s_addc_u32 s101, s87, s27
	s_add_i32 s36, s23, s90
	s_mov_b32 m0, s36
	ds_read_b128 v[198:201], v181 offset:16384
	ds_read_b128 v[202:205], v181 offset:17408
	ds_read_b128 v[206:209], v181 offset:18432
	ds_read_b128 v[210:213], v181 offset:19456
	ds_read_b128 v[214:217], v181 offset:20480
	ds_read_b128 v[218:221], v181 offset:21504
	ds_read_b128 v[222:225], v181 offset:22528
	ds_read_b128 v[226:229], v181 offset:23552
	global_load_lds_dwordx4 v148, s[82:83]
	s_add_i32 m0, s36, 0x2000
	s_add_u32 s36, s82, 0x40000
	s_addc_u32 s37, s83, 0
	s_add_i32 s20, s41, s90
	global_load_lds_dwordx4 v144, s[82:83]
	s_mov_b32 m0, s20
	s_nop 0
	global_load_lds_dwordx4 v148, s[36:37]
	s_add_i32 m0, s20, 0x2000
	s_nop 0
	global_load_lds_dwordx4 v144, s[36:37]
	s_mov_b32 m0, s93
	s_nop 0
	global_load_lds_dwordx4 v150, s[86:87]
	s_mov_b32 m0, s94
	s_nop 0
	global_load_lds_dwordx4 v146, s[86:87]
	s_waitcnt vmcnt(8)
	s_waitcnt lgkmcnt(0)
	s_barrier
	v_mfma_f32_16x16x32_bf16 v[60:63], v[128:131], v[198:201], 0
	v_mfma_f32_16x16x32_bf16 v[56:59], v[136:139], v[198:201], 0
	v_mfma_f32_16x16x32_bf16 v[44:47], v[128:131], v[206:209], 0
	v_mfma_f32_16x16x32_bf16 v[40:43], v[136:139], v[206:209], 0
	v_mfma_f32_16x16x32_bf16 v[28:31], v[128:131], v[214:217], 0
	v_mfma_f32_16x16x32_bf16 v[24:27], v[136:139], v[214:217], 0
	v_mfma_f32_16x16x32_bf16 v[12:15], v[128:131], v[222:225], 0
	v_mfma_f32_16x16x32_bf16 v[8:11], v[136:139], v[222:225], 0
	v_mfma_f32_16x16x32_bf16 v[60:63], v[132:135], v[202:205], v[60:63]
	v_mfma_f32_16x16x32_bf16 v[56:59], v[140:143], v[202:205], v[56:59]
	v_mfma_f32_16x16x32_bf16 v[44:47], v[132:135], v[210:213], v[44:47]
	v_mfma_f32_16x16x32_bf16 v[40:43], v[140:143], v[210:213], v[40:43]
	v_mfma_f32_16x16x32_bf16 v[28:31], v[132:135], v[218:221], v[28:31]
	v_mfma_f32_16x16x32_bf16 v[24:27], v[140:143], v[218:221], v[24:27]
	v_mfma_f32_16x16x32_bf16 v[12:15], v[132:135], v[226:229], v[12:15]
	v_mfma_f32_16x16x32_bf16 v[8:11], v[140:143], v[226:229], v[8:11]
	v_mfma_f32_16x16x32_bf16 v[52:55], v[166:169], v[198:201], 0
	v_mfma_f32_16x16x32_bf16 v[48:51], v[190:193], v[198:201], 0
	v_mfma_f32_16x16x32_bf16 v[36:39], v[166:169], v[206:209], 0
	v_mfma_f32_16x16x32_bf16 v[32:35], v[190:193], v[206:209], 0
	v_mfma_f32_16x16x32_bf16 v[20:23], v[166:169], v[214:217], 0
	v_mfma_f32_16x16x32_bf16 v[16:19], v[190:193], v[214:217], 0
	v_mfma_f32_16x16x32_bf16 v[4:7], v[166:169], v[222:225], 0
	v_mfma_f32_16x16x32_bf16 v[0:3], v[190:193], v[222:225], 0
	v_mfma_f32_16x16x32_bf16 v[52:55], v[170:173], v[202:205], v[52:55]
	v_mfma_f32_16x16x32_bf16 v[48:51], v[194:197], v[202:205], v[48:51]
	v_mfma_f32_16x16x32_bf16 v[36:39], v[170:173], v[210:213], v[36:39]
	v_mfma_f32_16x16x32_bf16 v[32:35], v[194:197], v[210:213], v[32:35]
	v_mfma_f32_16x16x32_bf16 v[20:23], v[170:173], v[218:221], v[20:23]
	v_mfma_f32_16x16x32_bf16 v[16:19], v[194:197], v[218:221], v[16:19]
	v_mfma_f32_16x16x32_bf16 v[4:7], v[170:173], v[226:229], v[4:7]
	v_mfma_f32_16x16x32_bf16 v[0:3], v[194:197], v[226:229], v[0:3]
	s_barrier
	s_branch .Lmy_peel_96_mid
; #define PG8_STAGE(bufoff, gbase, voff) do { _Pragma("unroll") for (int _i = 0; _i < 2; ++_i) \
;         __builtin_amdgcn_global_load_lds((const unsigned*)((const char*)(gbase) + (voff)[_i]), (PG8_LAS unsigned*)(lds + (bufoff) + ldsw + _i * 8192), 16, 0, 0); } while (0)
; #define PG8_LDA(dst, b, h) do { _Pragma("unroll") for (int m = 0; m < 4; ++m) _Pragma("unroll") for (int k = 0; k < 2; ++k) dst[m][k] = *(const PG8_LAS bf16x8*)(lds + PG8_SA(b, h) + aoff + m * 2048 + k * 1024); } while (0)
; #define PG8_LDB(dst, b, h) do { _Pragma("unroll") for (int n = 0; n < 2; ++n) _Pragma("unroll") for (int k = 0; k < 2; ++k) dst[n][k] = *(const PG8_LAS bf16x8*)(lds + PG8_SB(b, h) + boff + n * 2048 + k * 1024); } while (0)
; #define PG8_MMA(ai, bj, At, Bt) do { __builtin_amdgcn_s_setprio(1); _Pragma("unroll") for (int m = 0; m < 4; ++m) _Pragma("unroll") for (int n = 0; n < 2; ++n) _Pragma("unroll") for (int k = 0; k < 2; ++k) \
;         acc[ai][bj][m][n] = __builtin_amdgcn_mfma_f32_16x16x32_bf16(Bt[n][k], At[m][k], acc[ai][bj][m][n], 0, 0, 0); __builtin_amdgcn_s_setprio(0); } while (0)
; #define PG8_WAIT_V(n) asm volatile("s_waitcnt vmcnt(" #n ")" ::: "memory")
; #define PG8_WAIT_L(n) asm volatile("s_waitcnt lgkmcnt(" #n ")" ::: "memory")
; #define PG8_BAR __builtin_amdgcn_s_barrier()
; #define PG8_SCHED __builtin_amdgcn_sched_barrier(0)
; template <class Epi, class Sched, bool ALIGN_EPI = false, bool SP2 = false>
; __device__ __forceinline__ void gemm_phase(PG8_LAS unsigned char* lds, const Gemm g, const Sched& S, const Epi& E) {
;     ...
;             PG8_LDB(B0, 0, 0); PG8_LDB(B1, 0, 1); PG8_SCHED; PG8_LDA(At, 0, 0); PG8_STAGE(PG8_SA(1, 1), a1 + hstep, voffA);
;             PG8_WAIT_V(8); PG8_WAIT_L(0); PG8_BAR; PG8_MMA(0, 0, At, B0); PG8_MMA(0, 1, At, B1); PG8_BAR; PG8_SCHED;
;             PG8_LDA(At, 0, 1); PG8_STAGE(PG8_SB(0, 0), b2, voffB); PG8_STAGE(PG8_SB(0, 1), b2 + hstep, voffB); PG8_STAGE(PG8_SA(0, 0), a2, voffA);
;             PG8_WAIT_V(8); PG8_WAIT_L(0); PG8_BAR; PG8_MMA(1, 0, At, B0); PG8_MMA(1, 1, At, B1); PG8_BAR; PG8_SCHED;
.LBB0_96:
	ds_read_b128 v[128:131], v178
	ds_read_b128 v[132:135], v178 offset:1024
	ds_read_b128 v[136:139], v178 offset:2048
	ds_read_b128 v[140:143], v178 offset:3072
	ds_read_b128 v[166:169], v179
	ds_read_b128 v[170:173], v179 offset:1024
	ds_read_b128 v[190:193], v179 offset:2048
	ds_read_b128 v[194:197], v179 offset:3072
	s_add_u32 s36, s80, 0xfffc0080
	s_addc_u32 s37, s81, -1
	s_cmp_eq_u32 s35, 12
	s_cselect_b32 s87, s8, s37
	s_cselect_b32 s86, s55, s36
	s_cselect_b32 s83, s49, s34
	s_cselect_b32 s82, vcc_lo, vcc_hi
	s_add_i32 m0, s93, 0xc000
	ds_read_b128 v[198:201], v181
	ds_read_b128 v[202:205], v181 offset:1024
	ds_read_b128 v[206:209], v181 offset:2048
	ds_read_b128 v[210:213], v181 offset:3072
	ds_read_b128 v[214:217], v181 offset:4096
	ds_read_b128 v[218:221], v181 offset:5120
	ds_read_b128 v[222:225], v181 offset:6144
	ds_read_b128 v[226:229], v181 offset:7168
	global_load_lds_dwordx4 v158, s[80:81]
	s_add_i32 m0, s93, 0xe000
	s_nop 0
	global_load_lds_dwordx4 v160, s[80:81]
	s_waitcnt vmcnt(8)
	s_waitcnt lgkmcnt(0)
	s_barrier
	v_mfma_f32_16x16x32_bf16 v[124:127], v[128:131], v[198:201], v[124:127]
	v_mfma_f32_16x16x32_bf16 v[120:123], v[136:139], v[198:201], v[120:123]
	v_mfma_f32_16x16x32_bf16 v[108:111], v[128:131], v[206:209], v[108:111]
	v_mfma_f32_16x16x32_bf16 v[104:107], v[136:139], v[206:209], v[104:107]
	v_mfma_f32_16x16x32_bf16 v[92:95], v[128:131], v[214:217], v[92:95]
	v_mfma_f32_16x16x32_bf16 v[88:91], v[136:139], v[214:217], v[88:91]
	v_mfma_f32_16x16x32_bf16 v[76:79], v[128:131], v[222:225], v[76:79]
	v_mfma_f32_16x16x32_bf16 v[72:75], v[136:139], v[222:225], v[72:75]
	v_mfma_f32_16x16x32_bf16 v[124:127], v[132:135], v[202:205], v[124:127]
	v_mfma_f32_16x16x32_bf16 v[120:123], v[140:143], v[202:205], v[120:123]
	v_mfma_f32_16x16x32_bf16 v[108:111], v[132:135], v[210:213], v[108:111]
	v_mfma_f32_16x16x32_bf16 v[104:107], v[140:143], v[210:213], v[104:107]
	v_mfma_f32_16x16x32_bf16 v[92:95], v[132:135], v[218:221], v[92:95]
	v_mfma_f32_16x16x32_bf16 v[88:91], v[140:143], v[218:221], v[88:91]
	v_mfma_f32_16x16x32_bf16 v[76:79], v[132:135], v[226:229], v[76:79]
	v_mfma_f32_16x16x32_bf16 v[72:75], v[140:143], v[226:229], v[72:75]
	v_mfma_f32_16x16x32_bf16 v[116:119], v[166:169], v[198:201], v[116:119]
	v_mfma_f32_16x16x32_bf16 v[112:115], v[190:193], v[198:201], v[112:115]
	v_mfma_f32_16x16x32_bf16 v[100:103], v[166:169], v[206:209], v[100:103]
	v_mfma_f32_16x16x32_bf16 v[96:99], v[190:193], v[206:209], v[96:99]
	v_mfma_f32_16x16x32_bf16 v[84:87], v[166:169], v[214:217], v[84:87]
	v_mfma_f32_16x16x32_bf16 v[80:83], v[190:193], v[214:217], v[80:83]
	v_mfma_f32_16x16x32_bf16 v[68:71], v[166:169], v[222:225], v[68:71]
	v_mfma_f32_16x16x32_bf16 v[64:67], v[190:193], v[222:225], v[64:67]
	v_mfma_f32_16x16x32_bf16 v[116:119], v[170:173], v[202:205], v[116:119]
	v_mfma_f32_16x16x32_bf16 v[112:115], v[194:197], v[202:205], v[112:115]
	v_mfma_f32_16x16x32_bf16 v[100:103], v[170:173], v[210:213], v[100:103]
	v_mfma_f32_16x16x32_bf16 v[96:99], v[194:197], v[210:213], v[96:99]
	v_mfma_f32_16x16x32_bf16 v[84:87], v[170:173], v[218:221], v[84:87]
	v_mfma_f32_16x16x32_bf16 v[80:83], v[194:197], v[218:221], v[80:83]
	v_mfma_f32_16x16x32_bf16 v[68:71], v[170:173], v[226:229], v[68:71]
	v_mfma_f32_16x16x32_bf16 v[64:67], v[194:197], v[226:229], v[64:67]
	s_barrier
	s_add_u32 s98, s82, s26
	s_addc_u32 s99, s83, s27
	s_add_u32 s100, s86, s26
	s_addc_u32 s101, s87, s27
	s_add_i32 s36, s23, s90
	s_mov_b32 m0, s36
	ds_read_b128 v[198:201], v181 offset:16384
	ds_read_b128 v[202:205], v181 offset:17408
	ds_read_b128 v[206:209], v181 offset:18432
	ds_read_b128 v[210:213], v181 offset:19456
	ds_read_b128 v[214:217], v181 offset:20480
	ds_read_b128 v[218:221], v181 offset:21504
	ds_read_b128 v[222:225], v181 offset:22528
	ds_read_b128 v[226:229], v181 offset:23552
	global_load_lds_dwordx4 v148, s[82:83]
	s_add_i32 m0, s36, 0x2000
	s_add_u32 s36, s82, 0x40000
	s_addc_u32 s37, s83, 0
	s_add_i32 s20, s41, s90
	global_load_lds_dwordx4 v144, s[82:83]
	s_mov_b32 m0, s20
	s_nop 0
	global_load_lds_dwordx4 v148, s[36:37]
	s_add_i32 m0, s20, 0x2000
	s_nop 0
	global_load_lds_dwordx4 v144, s[36:37]
	s_mov_b32 m0, s93
	s_nop 0
	global_load_lds_dwordx4 v150, s[86:87]
	s_mov_b32 m0, s94
	s_nop 0
	global_load_lds_dwordx4 v146, s[86:87]
	s_waitcnt vmcnt(8)
	s_waitcnt lgkmcnt(0)
	s_barrier
	v_mfma_f32_16x16x32_bf16 v[60:63], v[128:131], v[198:201], v[60:63]
	v_mfma_f32_16x16x32_bf16 v[56:59], v[136:139], v[198:201], v[56:59]
	v_mfma_f32_16x16x32_bf16 v[44:47], v[128:131], v[206:209], v[44:47]
	v_mfma_f32_16x16x32_bf16 v[40:43], v[136:139], v[206:209], v[40:43]
	v_mfma_f32_16x16x32_bf16 v[28:31], v[128:131], v[214:217], v[28:31]
	v_mfma_f32_16x16x32_bf16 v[24:27], v[136:139], v[214:217], v[24:27]
	v_mfma_f32_16x16x32_bf16 v[12:15], v[128:131], v[222:225], v[12:15]
	v_mfma_f32_16x16x32_bf16 v[8:11], v[136:139], v[222:225], v[8:11]
	v_mfma_f32_16x16x32_bf16 v[60:63], v[132:135], v[202:205], v[60:63]
	v_mfma_f32_16x16x32_bf16 v[56:59], v[140:143], v[202:205], v[56:59]
	v_mfma_f32_16x16x32_bf16 v[44:47], v[132:135], v[210:213], v[44:47]
	v_mfma_f32_16x16x32_bf16 v[40:43], v[140:143], v[210:213], v[40:43]
	v_mfma_f32_16x16x32_bf16 v[28:31], v[132:135], v[218:221], v[28:31]
	v_mfma_f32_16x16x32_bf16 v[24:27], v[140:143], v[218:221], v[24:27]
	v_mfma_f32_16x16x32_bf16 v[12:15], v[132:135], v[226:229], v[12:15]
	v_mfma_f32_16x16x32_bf16 v[8:11], v[140:143], v[226:229], v[8:11]
	v_mfma_f32_16x16x32_bf16 v[52:55], v[166:169], v[198:201], v[52:55]
	v_mfma_f32_16x16x32_bf16 v[48:51], v[190:193], v[198:201], v[48:51]
	v_mfma_f32_16x16x32_bf16 v[36:39], v[166:169], v[206:209], v[36:39]
	v_mfma_f32_16x16x32_bf16 v[32:35], v[190:193], v[206:209], v[32:35]
	v_mfma_f32_16x16x32_bf16 v[20:23], v[166:169], v[214:217], v[20:23]
	v_mfma_f32_16x16x32_bf16 v[16:19], v[190:193], v[214:217], v[16:19]
	v_mfma_f32_16x16x32_bf16 v[4:7], v[166:169], v[222:225], v[4:7]
	v_mfma_f32_16x16x32_bf16 v[0:3], v[190:193], v[222:225], v[0:3]
	v_mfma_f32_16x16x32_bf16 v[52:55], v[170:173], v[202:205], v[52:55]
	v_mfma_f32_16x16x32_bf16 v[48:51], v[194:197], v[202:205], v[48:51]
	v_mfma_f32_16x16x32_bf16 v[36:39], v[170:173], v[210:213], v[36:39]
	v_mfma_f32_16x16x32_bf16 v[32:35], v[194:197], v[210:213], v[32:35]
	v_mfma_f32_16x16x32_bf16 v[20:23], v[170:173], v[218:221], v[20:23]
	v_mfma_f32_16x16x32_bf16 v[16:19], v[194:197], v[218:221], v[16:19]
	v_mfma_f32_16x16x32_bf16 v[4:7], v[170:173], v[226:229], v[4:7]
	v_mfma_f32_16x16x32_bf16 v[0:3], v[194:197], v[226:229], v[0:3]
	s_barrier
; #define PG8_STAGE(bufoff, gbase, voff) do { _Pragma("unroll") for (int _i = 0; _i < 2; ++_i) \
;         __builtin_amdgcn_global_load_lds((const unsigned*)((const char*)(gbase) + (voff)[_i]), (PG8_LAS unsigned*)(lds + (bufoff) + ldsw + _i * 8192), 16, 0, 0); } while (0)
; #define PG8_LDA(dst, b, h) do { _Pragma("unroll") for (int m = 0; m < 4; ++m) _Pragma("unroll") for (int k = 0; k < 2; ++k) dst[m][k] = *(const PG8_LAS bf16x8*)(lds + PG8_SA(b, h) + aoff + m * 2048 + k * 1024); } while (0)
; #define PG8_LDB(dst, b, h) do { _Pragma("unroll") for (int n = 0; n < 2; ++n) _Pragma("unroll") for (int k = 0; k < 2; ++k) dst[n][k] = *(const PG8_LAS bf16x8*)(lds + PG8_SB(b, h) + boff + n * 2048 + k * 1024); } while (0)
; #define PG8_MMA(ai, bj, At, Bt) do { __builtin_amdgcn_s_setprio(1); _Pragma("unroll") for (int m = 0; m < 4; ++m) _Pragma("unroll") for (int n = 0; n < 2; ++n) _Pragma("unroll") for (int k = 0; k < 2; ++k) \
;         acc[ai][bj][m][n] = __builtin_amdgcn_mfma_f32_16x16x32_bf16(Bt[n][k], At[m][k], acc[ai][bj][m][n], 0, 0, 0); __builtin_amdgcn_s_setprio(0); } while (0)
; #define PG8_WAIT_V(n) asm volatile("s_waitcnt vmcnt(" #n ")" ::: "memory")
; #define PG8_WAIT_L(n) asm volatile("s_waitcnt lgkmcnt(" #n ")" ::: "memory")
; #define PG8_BAR __builtin_amdgcn_s_barrier()
; #define PG8_SCHED __builtin_amdgcn_sched_barrier(0)
; template <class Epi, class Sched, bool ALIGN_EPI = false, bool SP2 = false>
; __device__ __forceinline__ void gemm_phase(PG8_LAS unsigned char* lds, const Gemm g, const Sched& S, const Epi& E) {
;     ...
;             PG8_LDB(B0, 1, 0); PG8_LDB(B1, 1, 1); PG8_SCHED; PG8_LDA(At, 1, 0); PG8_STAGE(PG8_SA(0, 1), a2 + hstep, voffA);
;             PG8_WAIT_V(8); PG8_WAIT_L(0); PG8_BAR; PG8_MMA(0, 0, At, B0); PG8_MMA(0, 1, At, B1); PG8_BAR; PG8_SCHED;
;             PG8_LDA(At, 1, 1); PG8_STAGE(PG8_SB(1, 0), b3, voffB); PG8_STAGE(PG8_SB(1, 1), b3 + hstep, voffB); PG8_STAGE(PG8_SA(1, 0), a3, voffA);
;             PG8_WAIT_V(8); PG8_WAIT_L(0); PG8_BAR; PG8_MMA(1, 0, At, B0); PG8_MMA(1, 1, At, B1); PG8_BAR; PG8_SCHED;
;     ...
;         if constexpr (ALIGN_EPI) { if (wr == 0) PG8_BAR; }
.Lmy_peel_96_mid:
	s_add_i32 s20, 0, 0x18000
	s_add_i32 s21, 0, 0x1c000
	v_add_u32_e32 v140, s20, v176
	v_add_u32_e32 v152, s21, v176
	ds_read_b128 v[128:131], v140
	ds_read_b128 v[132:135], v140 offset:1024
	ds_read_b128 v[136:139], v140 offset:2048
	ds_read_b128 v[140:143], v140 offset:3072
	ds_read_b128 v[166:169], v152
	ds_read_b128 v[170:173], v152 offset:1024
	ds_read_b128 v[190:193], v152 offset:2048
	ds_read_b128 v[194:197], v152 offset:3072
	s_add_u32 s36, s86, 0x40000
	s_addc_u32 s37, s87, 0
	s_mov_b32 m0, s95
	ds_read_b128 v[198:201], v181 offset:32768
	ds_read_b128 v[202:205], v181 offset:33792
	ds_read_b128 v[206:209], v181 offset:34816
	ds_read_b128 v[210:213], v181 offset:35840
	ds_read_b128 v[214:217], v181 offset:36864
	ds_read_b128 v[218:221], v181 offset:37888
	ds_read_b128 v[222:225], v181 offset:38912
	ds_read_b128 v[226:229], v181 offset:39936
	global_load_lds_dwordx4 v150, s[36:37]
	s_mov_b32 m0, s97
	s_nop 0
	global_load_lds_dwordx4 v146, s[36:37]
	s_waitcnt vmcnt(8)
	s_waitcnt lgkmcnt(0)
	s_barrier
	v_mfma_f32_16x16x32_bf16 v[124:127], v[128:131], v[198:201], v[124:127]
	v_mfma_f32_16x16x32_bf16 v[120:123], v[136:139], v[198:201], v[120:123]
	v_mfma_f32_16x16x32_bf16 v[108:111], v[128:131], v[206:209], v[108:111]
	v_mfma_f32_16x16x32_bf16 v[104:107], v[136:139], v[206:209], v[104:107]
	v_mfma_f32_16x16x32_bf16 v[92:95], v[128:131], v[214:217], v[92:95]
	v_mfma_f32_16x16x32_bf16 v[88:91], v[136:139], v[214:217], v[88:91]
	v_mfma_f32_16x16x32_bf16 v[76:79], v[128:131], v[222:225], v[76:79]
	v_mfma_f32_16x16x32_bf16 v[72:75], v[136:139], v[222:225], v[72:75]
	v_mfma_f32_16x16x32_bf16 v[124:127], v[132:135], v[202:205], v[124:127]
	v_mfma_f32_16x16x32_bf16 v[120:123], v[140:143], v[202:205], v[120:123]
	v_mfma_f32_16x16x32_bf16 v[108:111], v[132:135], v[210:213], v[108:111]
	v_mfma_f32_16x16x32_bf16 v[104:107], v[140:143], v[210:213], v[104:107]
	v_mfma_f32_16x16x32_bf16 v[92:95], v[132:135], v[218:221], v[92:95]
	v_mfma_f32_16x16x32_bf16 v[88:91], v[140:143], v[218:221], v[88:91]
	v_mfma_f32_16x16x32_bf16 v[76:79], v[132:135], v[226:229], v[76:79]
	v_mfma_f32_16x16x32_bf16 v[72:75], v[140:143], v[226:229], v[72:75]
	v_mfma_f32_16x16x32_bf16 v[116:119], v[166:169], v[198:201], v[116:119]
	v_mfma_f32_16x16x32_bf16 v[112:115], v[190:193], v[198:201], v[112:115]
	v_mfma_f32_16x16x32_bf16 v[100:103], v[166:169], v[206:209], v[100:103]
	v_mfma_f32_16x16x32_bf16 v[96:99], v[190:193], v[206:209], v[96:99]
	v_mfma_f32_16x16x32_bf16 v[84:87], v[166:169], v[214:217], v[84:87]
	v_mfma_f32_16x16x32_bf16 v[80:83], v[190:193], v[214:217], v[80:83]
	v_mfma_f32_16x16x32_bf16 v[68:71], v[166:169], v[222:225], v[68:71]
	v_mfma_f32_16x16x32_bf16 v[64:67], v[190:193], v[222:225], v[64:67]
	v_mfma_f32_16x16x32_bf16 v[116:119], v[170:173], v[202:205], v[116:119]
	v_mfma_f32_16x16x32_bf16 v[112:115], v[194:197], v[202:205], v[112:115]
	v_mfma_f32_16x16x32_bf16 v[100:103], v[170:173], v[210:213], v[100:103]
	v_mfma_f32_16x16x32_bf16 v[96:99], v[194:197], v[210:213], v[96:99]
	v_mfma_f32_16x16x32_bf16 v[84:87], v[170:173], v[218:221], v[84:87]
	v_mfma_f32_16x16x32_bf16 v[80:83], v[194:197], v[218:221], v[80:83]
	v_mfma_f32_16x16x32_bf16 v[68:71], v[170:173], v[226:229], v[68:71]
	v_mfma_f32_16x16x32_bf16 v[64:67], v[194:197], v[226:229], v[64:67]
	s_barrier
	s_add_i32 s20, s20, s90
	s_mov_b32 m0, s20
	ds_read_b128 v[198:201], v181 offset:49152
	ds_read_b128 v[202:205], v181 offset:50176
	ds_read_b128 v[206:209], v181 offset:51200
	ds_read_b128 v[210:213], v181 offset:52224
	ds_read_b128 v[214:217], v181 offset:53248
	ds_read_b128 v[218:221], v181 offset:54272
	ds_read_b128 v[222:225], v181 offset:55296
	ds_read_b128 v[226:229], v181 offset:56320
	global_load_lds_dwordx4 v148, s[98:99]
	s_add_i32 m0, s20, 0x2000
	s_add_u32 s36, s82, 0x40080
	s_addc_u32 s37, s83, 0
	s_add_i32 s20, s21, s90
	global_load_lds_dwordx4 v144, s[98:99]
	s_mov_b32 m0, s20
	s_nop 0
	global_load_lds_dwordx4 v148, s[36:37]
	s_add_i32 m0, s20, 0x2000
	s_nop 0
	global_load_lds_dwordx4 v144, s[36:37]
	s_mov_b32 m0, s42
	s_nop 0
	global_load_lds_dwordx4 v150, s[100:101]
	s_mov_b32 m0, s43
	s_nop 0
	global_load_lds_dwordx4 v146, s[100:101]
	s_waitcnt vmcnt(8)
	s_waitcnt lgkmcnt(0)
	s_barrier
	v_mfma_f32_16x16x32_bf16 v[60:63], v[128:131], v[198:201], v[60:63]
	v_mfma_f32_16x16x32_bf16 v[56:59], v[136:139], v[198:201], v[56:59]
	v_mfma_f32_16x16x32_bf16 v[44:47], v[128:131], v[206:209], v[44:47]
	v_mfma_f32_16x16x32_bf16 v[40:43], v[136:139], v[206:209], v[40:43]
	v_mfma_f32_16x16x32_bf16 v[28:31], v[128:131], v[214:217], v[28:31]
	v_mfma_f32_16x16x32_bf16 v[24:27], v[136:139], v[214:217], v[24:27]
	v_mfma_f32_16x16x32_bf16 v[12:15], v[128:131], v[222:225], v[12:15]
	v_mfma_f32_16x16x32_bf16 v[8:11], v[136:139], v[222:225], v[8:11]
	v_mfma_f32_16x16x32_bf16 v[60:63], v[132:135], v[202:205], v[60:63]
	v_mfma_f32_16x16x32_bf16 v[56:59], v[140:143], v[202:205], v[56:59]
	v_mfma_f32_16x16x32_bf16 v[44:47], v[132:135], v[210:213], v[44:47]
	v_mfma_f32_16x16x32_bf16 v[40:43], v[140:143], v[210:213], v[40:43]
	v_mfma_f32_16x16x32_bf16 v[28:31], v[132:135], v[218:221], v[28:31]
	v_mfma_f32_16x16x32_bf16 v[24:27], v[140:143], v[218:221], v[24:27]
	v_mfma_f32_16x16x32_bf16 v[12:15], v[132:135], v[226:229], v[12:15]
	v_mfma_f32_16x16x32_bf16 v[8:11], v[140:143], v[226:229], v[8:11]
	v_mfma_f32_16x16x32_bf16 v[52:55], v[166:169], v[198:201], v[52:55]
	v_mfma_f32_16x16x32_bf16 v[48:51], v[190:193], v[198:201], v[48:51]
	v_mfma_f32_16x16x32_bf16 v[36:39], v[166:169], v[206:209], v[36:39]
	v_mfma_f32_16x16x32_bf16 v[32:35], v[190:193], v[206:209], v[32:35]
	v_mfma_f32_16x16x32_bf16 v[20:23], v[166:169], v[214:217], v[20:23]
	v_mfma_f32_16x16x32_bf16 v[16:19], v[190:193], v[214:217], v[16:19]
	v_mfma_f32_16x16x32_bf16 v[4:7], v[166:169], v[222:225], v[4:7]
	v_mfma_f32_16x16x32_bf16 v[0:3], v[190:193], v[222:225], v[0:3]
	v_mfma_f32_16x16x32_bf16 v[52:55], v[170:173], v[202:205], v[52:55]
	v_mfma_f32_16x16x32_bf16 v[48:51], v[194:197], v[202:205], v[48:51]
	v_mfma_f32_16x16x32_bf16 v[36:39], v[170:173], v[210:213], v[36:39]
	v_mfma_f32_16x16x32_bf16 v[32:35], v[194:197], v[210:213], v[32:35]
	v_mfma_f32_16x16x32_bf16 v[20:23], v[170:173], v[218:221], v[20:23]
	v_mfma_f32_16x16x32_bf16 v[16:19], v[194:197], v[218:221], v[16:19]
	v_mfma_f32_16x16x32_bf16 v[4:7], v[170:173], v[226:229], v[4:7]
	v_mfma_f32_16x16x32_bf16 v[0:3], v[194:197], v[226:229], v[0:3]
	s_barrier
	s_add_i32 s35, s35, 2
	s_add_u32 s80, s80, 0x100
	s_addc_u32 s81, s81, 0
	s_add_u32 vcc_hi, vcc_hi, 0x100
	s_addc_u32 s34, s34, 0
	s_cmp_gt_u32 s35, 13
	s_cbranch_scc0 .LBB0_96
	s_and_b64 vcc, exec, s[28:29]
	s_cbranch_vccz .LBB0_99
	s_barrier

;     __host__ __device__ bool next(int i, Unit& u) const { const long L = (long)i * G + c; if (L >= nwg) return false; return unit_of((int)L, u); }
;     __host__ __device__ bool next(int i, Unit& u) const { const int L = i == 0 ? l0 : (i == 1 ? l1 : (i == 2 ? l2 : -1)); if (L < 0 || L >= s.nwg) return false; return s.unit_of(L, u); }
;     __host__ __device__ bool next(int i, Unit& u) const { const bool ok = s.next(i >> 1, u); u.kh = i & 1; return ok; }
; #define PG8_STAGE(bufoff, gbase, voff) do { _Pragma("unroll") for (int _i = 0; _i < 2; ++_i) \
;         __builtin_amdgcn_global_load_lds((const unsigned*)((const char*)(gbase) + (voff)[_i]), (PG8_LAS unsigned*)(lds + (bufoff) + ldsw + _i * 8192), 16, 0, 0); } while (0)
; #define PG8_LDA(dst, b, h) do { _Pragma("unroll") for (int m = 0; m < 4; ++m) _Pragma("unroll") for (int k = 0; k < 2; ++k) dst[m][k] = *(const PG8_LAS bf16x8*)(lds + PG8_SA(b, h) + aoff + m * 2048 + k * 1024); } while (0)
; template <class Epi, class Sched, bool ALIGN_EPI = false, bool SP2 = false>
; __device__ __forceinline__ void gemm_phase(PG8_LAS unsigned char* lds, const Gemm g, const Sched& S, const Epi& E) {
;     ...
;         const bool has_next = S.next(ui + 1, nxt);
;         const char* nA = has_next ? (const char*)g.A + (size_t)nxt.pm * tstep + nxt.kh * khb : cA; const char* nB = has_next ? (const char*)g.Bt + (size_t)nxt.pn * tstep + nxt.kh * khb : cB;
;         for (int t = 0; t < nt; t += 2) {
;             const bool last = (t == nt - 2);
;             const char* a1 = cA + (size_t)(t + 1) * kstep;
;             const char* a2 = last ? nA : cA + (size_t)(t + 2) * kstep; const char* b2 = last ? nB : cB + (size_t)(t + 2) * kstep;
;             const char* a3 = a2 + kstep; const char* b3 = b2 + kstep;
;             if (last && has_next) S.a_ready(nxt);
;             if constexpr (SP2) {
;             PG8_LDB(B0, 0, 0); PG8_LDB(B1, 0, 1); PG8_SCHED; PG8_LDA(At, 0, 0); PG8_STAGE(PG8_SA(1, 1), a1 + hstep, voffA);
;             PG8_WAIT_V(8); PG8_WAIT_L(0); PG8_BAR; PG8_MMA(0, 0, At, B0); PG8_MMA(0, 1, At, B1); PG8_BAR; PG8_SCHED;
;             PG8_LDA(At, 0, 1); PG8_STAGE(PG8_SB(0, 0), b2, voffB); PG8_STAGE(PG8_SB(0, 1), b2 + hstep, voffB); PG8_STAGE(PG8_SA(0, 0), a2, voffA);
;             PG8_WAIT_V(8); PG8_WAIT_L(0); PG8_BAR; PG8_MMA(1, 0, At, B0); PG8_MMA(1, 1, At, B1); PG8_BAR; PG8_SCHED;
.LBB0_149:
	s_ashr_i32 s17, s16, 31
	s_lshl_b64 s[18:19], s[16:17], 19
	s_add_u32 s18, s29, s18
	s_addc_u32 s19, s30, s19
	s_and_b64 s[20:21], s[2:3], exec
	s_cselect_b32 s17, s19, s23
	s_cselect_b32 s45, s18, s22
	s_ashr_i32 s15, s14, 31
	s_lshl_b64 s[20:21], s[14:15], 19
	s_add_u32 s20, s50, s20
	s_addc_u32 s21, s51, s21
	s_and_b64 s[26:27], s[2:3], exec
	s_cselect_b32 s15, s21, s25
	s_cselect_b32 s46, s20, s24
	s_add_u32 s22, s22, 0x40080
	s_addc_u32 s23, s23, 0
	s_add_u32 s47, s24, 0x100
	s_addc_u32 s48, s25, 0
	s_mov_b32 s49, -2
	s_add_u32 s24, s22, 0xfffc0080
	s_addc_u32 s25, s23, -1
	s_waitcnt lgkmcnt(0)
	s_add_i32 s54, 0, 0x10000
	v_add_u32_e32 v147, s54, v152
	ds_read_b128 v[156:159], v147
	ds_read_b128 v[160:163], v147 offset:1024
	ds_read_b128 v[164:167], v147 offset:2048
	ds_read_b128 v[168:171], v147 offset:3072
	ds_read_b128 v[172:175], v154
	ds_read_b128 v[176:179], v154 offset:1024
	ds_read_b128 v[182:185], v154 offset:2048
	ds_read_b128 v[190:193], v154 offset:3072
	s_cmp_eq_u32 s49, 12
	s_cselect_b32 s27, s17, s25
	s_cselect_b32 s26, s45, s24
	s_cselect_b32 s25, s15, s48
	s_cselect_b32 s24, s46, s47
	s_add_i32 m0, s13, 0xc000
	ds_read_b128 v[194:197], v155
	ds_read_b128 v[198:201], v155 offset:1024
	ds_read_b128 v[202:205], v155 offset:2048
	ds_read_b128 v[206:209], v155 offset:3072
	ds_read_b128 v[210:213], v155 offset:4096
	ds_read_b128 v[214:217], v155 offset:5120
	ds_read_b128 v[218:221], v155 offset:6144
	ds_read_b128 v[222:225], v155 offset:7168
	global_load_lds_dwordx4 v138, s[22:23]
	s_add_i32 m0, s13, 0xe000
	s_nop 0
	global_load_lds_dwordx4 v140, s[22:23]
	s_waitcnt vmcnt(8)
	s_waitcnt lgkmcnt(0)
	s_barrier
	v_mfma_f32_16x16x32_bf16 v[124:127], v[156:159], v[194:197], 0
	v_mfma_f32_16x16x32_bf16 v[120:123], v[164:167], v[194:197], 0
	v_mfma_f32_16x16x32_bf16 v[116:119], v[156:159], v[202:205], 0
	v_mfma_f32_16x16x32_bf16 v[112:115], v[164:167], v[202:205], 0
	v_mfma_f32_16x16x32_bf16 v[100:103], v[156:159], v[210:213], 0
	v_mfma_f32_16x16x32_bf16 v[96:99], v[164:167], v[210:213], 0
	v_mfma_f32_16x16x32_bf16 v[84:87], v[156:159], v[218:221], 0
	v_mfma_f32_16x16x32_bf16 v[80:83], v[164:167], v[218:221], 0
	v_mfma_f32_16x16x32_bf16 v[124:127], v[160:163], v[198:201], v[124:127]
	v_mfma_f32_16x16x32_bf16 v[120:123], v[168:171], v[198:201], v[120:123]
	v_mfma_f32_16x16x32_bf16 v[116:119], v[160:163], v[206:209], v[116:119]
	v_mfma_f32_16x16x32_bf16 v[112:115], v[168:171], v[206:209], v[112:115]
	v_mfma_f32_16x16x32_bf16 v[100:103], v[160:163], v[214:217], v[100:103]
	v_mfma_f32_16x16x32_bf16 v[96:99], v[168:171], v[214:217], v[96:99]
	v_mfma_f32_16x16x32_bf16 v[84:87], v[160:163], v[222:225], v[84:87]
	v_mfma_f32_16x16x32_bf16 v[80:83], v[168:171], v[222:225], v[80:83]
	v_mfma_f32_16x16x32_bf16 v[108:111], v[172:175], v[194:197], 0
	v_mfma_f32_16x16x32_bf16 v[104:107], v[182:185], v[194:197], 0
	v_mfma_f32_16x16x32_bf16 v[92:95], v[172:175], v[202:205], 0
	v_mfma_f32_16x16x32_bf16 v[88:91], v[182:185], v[202:205], 0
	v_mfma_f32_16x16x32_bf16 v[76:79], v[172:175], v[210:213], 0
	v_mfma_f32_16x16x32_bf16 v[72:75], v[182:185], v[210:213], 0
	v_mfma_f32_16x16x32_bf16 v[68:71], v[172:175], v[218:221], 0
	v_mfma_f32_16x16x32_bf16 v[64:67], v[182:185], v[218:221], 0
	v_mfma_f32_16x16x32_bf16 v[108:111], v[176:179], v[198:201], v[108:111]
	v_mfma_f32_16x16x32_bf16 v[104:107], v[190:193], v[198:201], v[104:107]
	v_mfma_f32_16x16x32_bf16 v[92:95], v[176:179], v[206:209], v[92:95]
	v_mfma_f32_16x16x32_bf16 v[88:91], v[190:193], v[206:209], v[88:91]
	v_mfma_f32_16x16x32_bf16 v[76:79], v[176:179], v[214:217], v[76:79]
	v_mfma_f32_16x16x32_bf16 v[72:75], v[190:193], v[214:217], v[72:75]
	v_mfma_f32_16x16x32_bf16 v[68:71], v[176:179], v[222:225], v[68:71]
	v_mfma_f32_16x16x32_bf16 v[64:67], v[190:193], v[222:225], v[64:67]
	s_barrier
	s_add_u32 s98, s24, s8
	s_addc_u32 s99, s25, s9
	s_add_u32 s100, s26, s8
	s_addc_u32 s101, s27, s9
	s_add_i32 s54, s54, s31
	s_mov_b32 m0, s54
	ds_read_b128 v[194:197], v155 offset:16384
	ds_read_b128 v[198:201], v155 offset:17408
	ds_read_b128 v[202:205], v155 offset:18432
	ds_read_b128 v[206:209], v155 offset:19456
	ds_read_b128 v[210:213], v155 offset:20480
	ds_read_b128 v[214:217], v155 offset:21504
	ds_read_b128 v[218:221], v155 offset:22528
	ds_read_b128 v[222:225], v155 offset:23552
	global_load_lds_dwordx4 v130, s[24:25]
	s_add_i32 m0, s54, 0x2000
	s_add_u32 s54, s24, 0x40000
	s_addc_u32 s55, s25, 0
	s_add_i32 s76, s43, s31
	global_load_lds_dwordx4 v134, s[24:25]
	s_mov_b32 m0, s76
	s_nop 0
	global_load_lds_dwordx4 v130, s[54:55]
	s_add_i32 m0, s76, 0x2000
	s_nop 0
	global_load_lds_dwordx4 v134, s[54:55]
	s_mov_b32 m0, s13
	s_nop 0
	global_load_lds_dwordx4 v128, s[26:27]
	s_mov_b32 m0, s34
	s_nop 0
	global_load_lds_dwordx4 v132, s[26:27]
	s_waitcnt vmcnt(8)
	s_waitcnt lgkmcnt(0)
	s_barrier
	v_mfma_f32_16x16x32_bf16 v[60:63], v[156:159], v[194:197], 0
	v_mfma_f32_16x16x32_bf16 v[56:59], v[164:167], v[194:197], 0
	v_mfma_f32_16x16x32_bf16 v[52:55], v[156:159], v[202:205], 0
	v_mfma_f32_16x16x32_bf16 v[48:51], v[164:167], v[202:205], 0
	v_mfma_f32_16x16x32_bf16 v[36:39], v[156:159], v[210:213], 0
	v_mfma_f32_16x16x32_bf16 v[32:35], v[164:167], v[210:213], 0
	v_mfma_f32_16x16x32_bf16 v[20:23], v[156:159], v[218:221], 0
	v_mfma_f32_16x16x32_bf16 v[16:19], v[164:167], v[218:221], 0
	v_mfma_f32_16x16x32_bf16 v[60:63], v[160:163], v[198:201], v[60:63]
	v_mfma_f32_16x16x32_bf16 v[56:59], v[168:171], v[198:201], v[56:59]
	v_mfma_f32_16x16x32_bf16 v[52:55], v[160:163], v[206:209], v[52:55]
	v_mfma_f32_16x16x32_bf16 v[48:51], v[168:171], v[206:209], v[48:51]
	v_mfma_f32_16x16x32_bf16 v[36:39], v[160:163], v[214:217], v[36:39]
	v_mfma_f32_16x16x32_bf16 v[32:35], v[168:171], v[214:217], v[32:35]
	v_mfma_f32_16x16x32_bf16 v[20:23], v[160:163], v[222:225], v[20:23]
	v_mfma_f32_16x16x32_bf16 v[16:19], v[168:171], v[222:225], v[16:19]
	v_mfma_f32_16x16x32_bf16 v[44:47], v[172:175], v[194:197], 0
	v_mfma_f32_16x16x32_bf16 v[40:43], v[182:185], v[194:197], 0
	v_mfma_f32_16x16x32_bf16 v[28:31], v[172:175], v[202:205], 0
	v_mfma_f32_16x16x32_bf16 v[24:27], v[182:185], v[202:205], 0
	v_mfma_f32_16x16x32_bf16 v[12:15], v[172:175], v[210:213], 0
	v_mfma_f32_16x16x32_bf16 v[8:11], v[182:185], v[210:213], 0
	v_mfma_f32_16x16x32_bf16 v[4:7], v[172:175], v[218:221], 0
	v_mfma_f32_16x16x32_bf16 v[0:3], v[182:185], v[218:221], 0
	v_mfma_f32_16x16x32_bf16 v[44:47], v[176:179], v[198:201], v[44:47]
	v_mfma_f32_16x16x32_bf16 v[40:43], v[190:193], v[198:201], v[40:43]
	v_mfma_f32_16x16x32_bf16 v[28:31], v[176:179], v[206:209], v[28:31]
	v_mfma_f32_16x16x32_bf16 v[24:27], v[190:193], v[206:209], v[24:27]
	v_mfma_f32_16x16x32_bf16 v[12:15], v[176:179], v[214:217], v[12:15]
	v_mfma_f32_16x16x32_bf16 v[8:11], v[190:193], v[214:217], v[8:11]
	v_mfma_f32_16x16x32_bf16 v[4:7], v[176:179], v[222:225], v[4:7]
	v_mfma_f32_16x16x32_bf16 v[0:3], v[190:193], v[222:225], v[0:3]
	s_barrier
	s_branch .Lmy_peel_150_mid
; #define PG8_STAGE(bufoff, gbase, voff) do { _Pragma("unroll") for (int _i = 0; _i < 2; ++_i) \
;         __builtin_amdgcn_global_load_lds((const unsigned*)((const char*)(gbase) + (voff)[_i]), (PG8_LAS unsigned*)(lds + (bufoff) + ldsw + _i * 8192), 16, 0, 0); } while (0)
; #define PG8_LDA(dst, b, h) do { _Pragma("unroll") for (int m = 0; m < 4; ++m) _Pragma("unroll") for (int k = 0; k < 2; ++k) dst[m][k] = *(const PG8_LAS bf16x8*)(lds + PG8_SA(b, h) + aoff + m * 2048 + k * 1024); } while (0)
; #define PG8_LDB(dst, b, h) do { _Pragma("unroll") for (int n = 0; n < 2; ++n) _Pragma("unroll") for (int k = 0; k < 2; ++k) dst[n][k] = *(const PG8_LAS bf16x8*)(lds + PG8_SB(b, h) + boff + n * 2048 + k * 1024); } while (0)
; #define PG8_MMA(ai, bj, At, Bt) do { __builtin_amdgcn_s_setprio(1); _Pragma("unroll") for (int m = 0; m < 4; ++m) _Pragma("unroll") for (int n = 0; n < 2; ++n) _Pragma("unroll") for (int k = 0; k < 2; ++k) \
;         acc[ai][bj][m][n] = __builtin_amdgcn_mfma_f32_16x16x32_bf16(Bt[n][k], At[m][k], acc[ai][bj][m][n], 0, 0, 0); __builtin_amdgcn_s_setprio(0); } while (0)
; #define PG8_WAIT_V(n) asm volatile("s_waitcnt vmcnt(" #n ")" ::: "memory")
; #define PG8_WAIT_L(n) asm volatile("s_waitcnt lgkmcnt(" #n ")" ::: "memory")
; template <class Epi, class Sched, bool ALIGN_EPI = false, bool SP2 = false>
; __device__ __forceinline__ void gemm_phase(PG8_LAS unsigned char* lds, const Gemm g, const Sched& S, const Epi& E) {
;     ...
;             const bool last = (t == nt - 2);
;             const char* a1 = cA + (size_t)(t + 1) * kstep;
;             const char* a2 = last ? nA : cA + (size_t)(t + 2) * kstep; const char* b2 = last ? nB : cB + (size_t)(t + 2) * kstep;
;             const char* a3 = a2 + kstep; const char* b3 = b2 + kstep;
;             if (last && has_next) S.a_ready(nxt);
;             if constexpr (SP2) {
;             PG8_LDB(B0, 0, 0); PG8_LDB(B1, 0, 1); PG8_SCHED; PG8_LDA(At, 0, 0); PG8_STAGE(PG8_SA(1, 1), a1 + hstep, voffA);
;             PG8_WAIT_V(8); PG8_WAIT_L(0); PG8_BAR; PG8_MMA(0, 0, At, B0); PG8_MMA(0, 1, At, B1); PG8_BAR; PG8_SCHED;
;             PG8_LDA(At, 0, 1); PG8_STAGE(PG8_SB(0, 0), b2, voffB); PG8_STAGE(PG8_SB(0, 1), b2 + hstep, voffB); PG8_STAGE(PG8_SA(0, 0), a2, voffA);
;             PG8_WAIT_V(8); PG8_WAIT_L(0); PG8_BAR; PG8_MMA(1, 0, At, B0); PG8_MMA(1, 1, At, B1); PG8_BAR; PG8_SCHED;
.LBB0_150:
	s_add_u32 s24, s22, 0xfffc0080
	s_addc_u32 s25, s23, -1
	s_waitcnt lgkmcnt(0)
	s_add_i32 s54, 0, 0x10000
	v_add_u32_e32 v147, s54, v152
	ds_read_b128 v[156:159], v147
	ds_read_b128 v[160:163], v147 offset:1024
	ds_read_b128 v[164:167], v147 offset:2048
	ds_read_b128 v[168:171], v147 offset:3072
	ds_read_b128 v[172:175], v154
	ds_read_b128 v[176:179], v154 offset:1024
	ds_read_b128 v[182:185], v154 offset:2048
	ds_read_b128 v[190:193], v154 offset:3072
	s_cmp_eq_u32 s49, 12
	s_cselect_b32 s27, s17, s25
	s_cselect_b32 s26, s45, s24
	s_cselect_b32 s25, s15, s48
	s_cselect_b32 s24, s46, s47
	s_add_i32 m0, s13, 0xc000
	ds_read_b128 v[194:197], v155
	ds_read_b128 v[198:201], v155 offset:1024
	ds_read_b128 v[202:205], v155 offset:2048
	ds_read_b128 v[206:209], v155 offset:3072
	ds_read_b128 v[210:213], v155 offset:4096
	ds_read_b128 v[214:217], v155 offset:5120
	ds_read_b128 v[218:221], v155 offset:6144
	ds_read_b128 v[222:225], v155 offset:7168
	global_load_lds_dwordx4 v138, s[22:23]
	s_add_i32 m0, s13, 0xe000
	s_nop 0
	global_load_lds_dwordx4 v140, s[22:23]
	s_waitcnt vmcnt(8)
	s_waitcnt lgkmcnt(0)
	s_barrier
	v_mfma_f32_16x16x32_bf16 v[124:127], v[156:159], v[194:197], v[124:127]
	v_mfma_f32_16x16x32_bf16 v[120:123], v[164:167], v[194:197], v[120:123]
	v_mfma_f32_16x16x32_bf16 v[116:119], v[156:159], v[202:205], v[116:119]
	v_mfma_f32_16x16x32_bf16 v[112:115], v[164:167], v[202:205], v[112:115]
	v_mfma_f32_16x16x32_bf16 v[100:103], v[156:159], v[210:213], v[100:103]
	v_mfma_f32_16x16x32_bf16 v[96:99], v[164:167], v[210:213], v[96:99]
	v_mfma_f32_16x16x32_bf16 v[84:87], v[156:159], v[218:221], v[84:87]
	v_mfma_f32_16x16x32_bf16 v[80:83], v[164:167], v[218:221], v[80:83]
	v_mfma_f32_16x16x32_bf16 v[124:127], v[160:163], v[198:201], v[124:127]
	v_mfma_f32_16x16x32_bf16 v[120:123], v[168:171], v[198:201], v[120:123]
	v_mfma_f32_16x16x32_bf16 v[116:119], v[160:163], v[206:209], v[116:119]
	v_mfma_f32_16x16x32_bf16 v[112:115], v[168:171], v[206:209], v[112:115]
	v_mfma_f32_16x16x32_bf16 v[100:103], v[160:163], v[214:217], v[100:103]
	v_mfma_f32_16x16x32_bf16 v[96:99], v[168:171], v[214:217], v[96:99]
	v_mfma_f32_16x16x32_bf16 v[84:87], v[160:163], v[222:225], v[84:87]
	v_mfma_f32_16x16x32_bf16 v[80:83], v[168:171], v[222:225], v[80:83]
	v_mfma_f32_16x16x32_bf16 v[108:111], v[172:175], v[194:197], v[108:111]
	v_mfma_f32_16x16x32_bf16 v[104:107], v[182:185], v[194:197], v[104:107]
	v_mfma_f32_16x16x32_bf16 v[92:95], v[172:175], v[202:205], v[92:95]
	v_mfma_f32_16x16x32_bf16 v[88:91], v[182:185], v[202:205], v[88:91]
	v_mfma_f32_16x16x32_bf16 v[76:79], v[172:175], v[210:213], v[76:79]
	v_mfma_f32_16x16x32_bf16 v[72:75], v[182:185], v[210:213], v[72:75]
	v_mfma_f32_16x16x32_bf16 v[68:71], v[172:175], v[218:221], v[68:71]
	v_mfma_f32_16x16x32_bf16 v[64:67], v[182:185], v[218:221], v[64:67]
	v_mfma_f32_16x16x32_bf16 v[108:111], v[176:179], v[198:201], v[108:111]
	v_mfma_f32_16x16x32_bf16 v[104:107], v[190:193], v[198:201], v[104:107]
	v_mfma_f32_16x16x32_bf16 v[92:95], v[176:179], v[206:209], v[92:95]
	v_mfma_f32_16x16x32_bf16 v[88:91], v[190:193], v[206:209], v[88:91]
	v_mfma_f32_16x16x32_bf16 v[76:79], v[176:179], v[214:217], v[76:79]
	v_mfma_f32_16x16x32_bf16 v[72:75], v[190:193], v[214:217], v[72:75]
	v_mfma_f32_16x16x32_bf16 v[68:71], v[176:179], v[222:225], v[68:71]
	v_mfma_f32_16x16x32_bf16 v[64:67], v[190:193], v[222:225], v[64:67]
	s_barrier
	s_add_u32 s98, s24, s8
	s_addc_u32 s99, s25, s9
	s_add_u32 s100, s26, s8
	s_addc_u32 s101, s27, s9
	s_add_i32 s54, s54, s31
	s_mov_b32 m0, s54
	ds_read_b128 v[194:197], v155 offset:16384
	ds_read_b128 v[198:201], v155 offset:17408
	ds_read_b128 v[202:205], v155 offset:18432
	ds_read_b128 v[206:209], v155 offset:19456
	ds_read_b128 v[210:213], v155 offset:20480
	ds_read_b128 v[214:217], v155 offset:21504
	ds_read_b128 v[218:221], v155 offset:22528
	ds_read_b128 v[222:225], v155 offset:23552
	global_load_lds_dwordx4 v130, s[24:25]
	s_add_i32 m0, s54, 0x2000
	s_add_u32 s54, s24, 0x40000
	s_addc_u32 s55, s25, 0
	s_add_i32 s76, s43, s31
	global_load_lds_dwordx4 v134, s[24:25]
	s_mov_b32 m0, s76
	s_nop 0
	global_load_lds_dwordx4 v130, s[54:55]
	s_add_i32 m0, s76, 0x2000
	s_nop 0
	global_load_lds_dwordx4 v134, s[54:55]
	s_mov_b32 m0, s13
	s_nop 0
	global_load_lds_dwordx4 v128, s[26:27]
	s_mov_b32 m0, s34
	s_nop 0
	global_load_lds_dwordx4 v132, s[26:27]
	s_waitcnt vmcnt(8)
	s_waitcnt lgkmcnt(0)
	s_barrier
	v_mfma_f32_16x16x32_bf16 v[60:63], v[156:159], v[194:197], v[60:63]
	v_mfma_f32_16x16x32_bf16 v[56:59], v[164:167], v[194:197], v[56:59]
	v_mfma_f32_16x16x32_bf16 v[52:55], v[156:159], v[202:205], v[52:55]
	v_mfma_f32_16x16x32_bf16 v[48:51], v[164:167], v[202:205], v[48:51]
	v_mfma_f32_16x16x32_bf16 v[36:39], v[156:159], v[210:213], v[36:39]
	v_mfma_f32_16x16x32_bf16 v[32:35], v[164:167], v[210:213], v[32:35]
	v_mfma_f32_16x16x32_bf16 v[20:23], v[156:159], v[218:221], v[20:23]
	v_mfma_f32_16x16x32_bf16 v[16:19], v[164:167], v[218:221], v[16:19]
	v_mfma_f32_16x16x32_bf16 v[60:63], v[160:163], v[198:201], v[60:63]
	v_mfma_f32_16x16x32_bf16 v[56:59], v[168:171], v[198:201], v[56:59]
	v_mfma_f32_16x16x32_bf16 v[52:55], v[160:163], v[206:209], v[52:55]
	v_mfma_f32_16x16x32_bf16 v[48:51], v[168:171], v[206:209], v[48:51]
	v_mfma_f32_16x16x32_bf16 v[36:39], v[160:163], v[214:217], v[36:39]
	v_mfma_f32_16x16x32_bf16 v[32:35], v[168:171], v[214:217], v[32:35]
	v_mfma_f32_16x16x32_bf16 v[20:23], v[160:163], v[222:225], v[20:23]
	v_mfma_f32_16x16x32_bf16 v[16:19], v[168:171], v[222:225], v[16:19]
	v_mfma_f32_16x16x32_bf16 v[44:47], v[172:175], v[194:197], v[44:47]
	v_mfma_f32_16x16x32_bf16 v[40:43], v[182:185], v[194:197], v[40:43]
	v_mfma_f32_16x16x32_bf16 v[28:31], v[172:175], v[202:205], v[28:31]
	v_mfma_f32_16x16x32_bf16 v[24:27], v[182:185], v[202:205], v[24:27]
	v_mfma_f32_16x16x32_bf16 v[12:15], v[172:175], v[210:213], v[12:15]
	v_mfma_f32_16x16x32_bf16 v[8:11], v[182:185], v[210:213], v[8:11]
	v_mfma_f32_16x16x32_bf16 v[4:7], v[172:175], v[218:221], v[4:7]
	v_mfma_f32_16x16x32_bf16 v[0:3], v[182:185], v[218:221], v[0:3]
	v_mfma_f32_16x16x32_bf16 v[44:47], v[176:179], v[198:201], v[44:47]
	v_mfma_f32_16x16x32_bf16 v[40:43], v[190:193], v[198:201], v[40:43]
	v_mfma_f32_16x16x32_bf16 v[28:31], v[176:179], v[206:209], v[28:31]
	v_mfma_f32_16x16x32_bf16 v[24:27], v[190:193], v[206:209], v[24:27]
	v_mfma_f32_16x16x32_bf16 v[12:15], v[176:179], v[214:217], v[12:15]
	v_mfma_f32_16x16x32_bf16 v[8:11], v[190:193], v[214:217], v[8:11]
	v_mfma_f32_16x16x32_bf16 v[4:7], v[176:179], v[222:225], v[4:7]
	v_mfma_f32_16x16x32_bf16 v[0:3], v[190:193], v[222:225], v[0:3]
	s_barrier
; #define PG8_STAGE(bufoff, gbase, voff) do { _Pragma("unroll") for (int _i = 0; _i < 2; ++_i) \
;         __builtin_amdgcn_global_load_lds((const unsigned*)((const char*)(gbase) + (voff)[_i]), (PG8_LAS unsigned*)(lds + (bufoff) + ldsw + _i * 8192), 16, 0, 0); } while (0)
; #define PG8_LDA(dst, b, h) do { _Pragma("unroll") for (int m = 0; m < 4; ++m) _Pragma("unroll") for (int k = 0; k < 2; ++k) dst[m][k] = *(const PG8_LAS bf16x8*)(lds + PG8_SA(b, h) + aoff + m * 2048 + k * 1024); } while (0)
; #define PG8_LDB(dst, b, h) do { _Pragma("unroll") for (int n = 0; n < 2; ++n) _Pragma("unroll") for (int k = 0; k < 2; ++k) dst[n][k] = *(const PG8_LAS bf16x8*)(lds + PG8_SB(b, h) + boff + n * 2048 + k * 1024); } while (0)
; #define PG8_MMA(ai, bj, At, Bt) do { __builtin_amdgcn_s_setprio(1); _Pragma("unroll") for (int m = 0; m < 4; ++m) _Pragma("unroll") for (int n = 0; n < 2; ++n) _Pragma("unroll") for (int k = 0; k < 2; ++k) \
;         acc[ai][bj][m][n] = __builtin_amdgcn_mfma_f32_16x16x32_bf16(Bt[n][k], At[m][k], acc[ai][bj][m][n], 0, 0, 0); __builtin_amdgcn_s_setprio(0); } while (0)
; #define PG8_WAIT_V(n) asm volatile("s_waitcnt vmcnt(" #n ")" ::: "memory")
; #define PG8_WAIT_L(n) asm volatile("s_waitcnt lgkmcnt(" #n ")" ::: "memory")
; #define PG8_BAR __builtin_amdgcn_s_barrier()
; #define PG8_SCHED __builtin_amdgcn_sched_barrier(0)
; template <class Epi, class Sched, bool ALIGN_EPI = false, bool SP2 = false>
; __device__ __forceinline__ void gemm_phase(PG8_LAS unsigned char* lds, const Gemm g, const Sched& S, const Epi& E) {
;     ...
;             PG8_LDB(B0, 1, 0); PG8_LDB(B1, 1, 1); PG8_SCHED; PG8_LDA(At, 1, 0); PG8_STAGE(PG8_SA(0, 1), a2 + hstep, voffA);
;             PG8_WAIT_V(8); PG8_WAIT_L(0); PG8_BAR; PG8_MMA(0, 0, At, B0); PG8_MMA(0, 1, At, B1); PG8_BAR; PG8_SCHED;
;             PG8_LDA(At, 1, 1); PG8_STAGE(PG8_SB(1, 0), b3, voffB); PG8_STAGE(PG8_SB(1, 1), b3 + hstep, voffB); PG8_STAGE(PG8_SA(1, 0), a3, voffA);
;             PG8_WAIT_V(8); PG8_WAIT_L(0); PG8_BAR; PG8_MMA(1, 0, At, B0); PG8_MMA(1, 1, At, B1); PG8_BAR; PG8_SCHED;
.Lmy_peel_150_mid:
	s_add_i32 s54, 0, 0x18000
	v_add_u32_e32 v147, s54, v152
	s_add_i32 s55, 0, 0x1c000
	ds_read_b128 v[156:159], v147
	ds_read_b128 v[160:163], v147 offset:1024
	ds_read_b128 v[164:167], v147 offset:2048
	ds_read_b128 v[168:171], v147 offset:3072
	v_add_u32_e32 v147, s55, v152
	ds_read_b128 v[172:175], v147
	ds_read_b128 v[176:179], v147 offset:1024
	ds_read_b128 v[182:185], v147 offset:2048
	ds_read_b128 v[190:193], v147 offset:3072
	s_add_u32 s26, s26, 0x40000
	s_addc_u32 s27, s27, 0
	s_mov_b32 m0, s35
	ds_read_b128 v[194:197], v155 offset:32768
	ds_read_b128 v[198:201], v155 offset:33792
	ds_read_b128 v[202:205], v155 offset:34816
	ds_read_b128 v[206:209], v155 offset:35840
	ds_read_b128 v[210:213], v155 offset:36864
	ds_read_b128 v[214:217], v155 offset:37888
	ds_read_b128 v[218:221], v155 offset:38912
	ds_read_b128 v[222:225], v155 offset:39936
	global_load_lds_dwordx4 v128, s[26:27]
	s_mov_b32 m0, s36
	s_nop 0
	global_load_lds_dwordx4 v132, s[26:27]
	s_waitcnt vmcnt(8)
	s_waitcnt lgkmcnt(0)
	s_barrier
	v_mfma_f32_16x16x32_bf16 v[124:127], v[156:159], v[194:197], v[124:127]
	v_mfma_f32_16x16x32_bf16 v[120:123], v[164:167], v[194:197], v[120:123]
	v_mfma_f32_16x16x32_bf16 v[116:119], v[156:159], v[202:205], v[116:119]
	v_mfma_f32_16x16x32_bf16 v[112:115], v[164:167], v[202:205], v[112:115]
	v_mfma_f32_16x16x32_bf16 v[100:103], v[156:159], v[210:213], v[100:103]
	v_mfma_f32_16x16x32_bf16 v[96:99], v[164:167], v[210:213], v[96:99]
	v_mfma_f32_16x16x32_bf16 v[84:87], v[156:159], v[218:221], v[84:87]
	v_mfma_f32_16x16x32_bf16 v[80:83], v[164:167], v[218:221], v[80:83]
	v_mfma_f32_16x16x32_bf16 v[124:127], v[160:163], v[198:201], v[124:127]
	v_mfma_f32_16x16x32_bf16 v[120:123], v[168:171], v[198:201], v[120:123]
	v_mfma_f32_16x16x32_bf16 v[116:119], v[160:163], v[206:209], v[116:119]
	v_mfma_f32_16x16x32_bf16 v[112:115], v[168:171], v[206:209], v[112:115]
	v_mfma_f32_16x16x32_bf16 v[100:103], v[160:163], v[214:217], v[100:103]
	v_mfma_f32_16x16x32_bf16 v[96:99], v[168:171], v[214:217], v[96:99]
	v_mfma_f32_16x16x32_bf16 v[84:87], v[160:163], v[222:225], v[84:87]
	v_mfma_f32_16x16x32_bf16 v[80:83], v[168:171], v[222:225], v[80:83]
	v_mfma_f32_16x16x32_bf16 v[108:111], v[172:175], v[194:197], v[108:111]
	v_mfma_f32_16x16x32_bf16 v[104:107], v[182:185], v[194:197], v[104:107]
	v_mfma_f32_16x16x32_bf16 v[92:95], v[172:175], v[202:205], v[92:95]
	v_mfma_f32_16x16x32_bf16 v[88:91], v[182:185], v[202:205], v[88:91]
	v_mfma_f32_16x16x32_bf16 v[76:79], v[172:175], v[210:213], v[76:79]
	v_mfma_f32_16x16x32_bf16 v[72:75], v[182:185], v[210:213], v[72:75]
	v_mfma_f32_16x16x32_bf16 v[68:71], v[172:175], v[218:221], v[68:71]
	v_mfma_f32_16x16x32_bf16 v[64:67], v[182:185], v[218:221], v[64:67]
	v_mfma_f32_16x16x32_bf16 v[108:111], v[176:179], v[198:201], v[108:111]
	v_mfma_f32_16x16x32_bf16 v[104:107], v[190:193], v[198:201], v[104:107]
	v_mfma_f32_16x16x32_bf16 v[92:95], v[176:179], v[206:209], v[92:95]
	v_mfma_f32_16x16x32_bf16 v[88:91], v[190:193], v[206:209], v[88:91]
	v_mfma_f32_16x16x32_bf16 v[76:79], v[176:179], v[214:217], v[76:79]
	v_mfma_f32_16x16x32_bf16 v[72:75], v[190:193], v[214:217], v[72:75]
	v_mfma_f32_16x16x32_bf16 v[68:71], v[176:179], v[222:225], v[68:71]
	v_mfma_f32_16x16x32_bf16 v[64:67], v[190:193], v[222:225], v[64:67]
	s_barrier
	s_add_i32 s26, s54, s31
	s_mov_b32 m0, s26
	ds_read_b128 v[194:197], v155 offset:49152
	ds_read_b128 v[198:201], v155 offset:50176
	ds_read_b128 v[202:205], v155 offset:51200
	ds_read_b128 v[206:209], v155 offset:52224
	ds_read_b128 v[210:213], v155 offset:53248
	ds_read_b128 v[214:217], v155 offset:54272
	ds_read_b128 v[218:221], v155 offset:55296
	ds_read_b128 v[222:225], v155 offset:56320
	global_load_lds_dwordx4 v130, s[98:99]
	s_add_i32 m0, s26, 0x2000
	s_add_u32 s24, s24, 0x40080
	s_addc_u32 s25, s25, 0
	s_add_i32 s26, s55, s31
	global_load_lds_dwordx4 v134, s[98:99]
	s_mov_b32 m0, s26
	s_nop 0
	global_load_lds_dwordx4 v130, s[24:25]
	s_add_i32 m0, s26, 0x2000
	s_nop 0
	global_load_lds_dwordx4 v134, s[24:25]
	s_mov_b32 m0, s39
	s_nop 0
	global_load_lds_dwordx4 v128, s[100:101]
	s_mov_b32 m0, s40
	s_nop 0
	global_load_lds_dwordx4 v132, s[100:101]
	s_waitcnt vmcnt(8)
	s_waitcnt lgkmcnt(0)
	s_barrier
	v_mfma_f32_16x16x32_bf16 v[60:63], v[156:159], v[194:197], v[60:63]
	v_mfma_f32_16x16x32_bf16 v[56:59], v[164:167], v[194:197], v[56:59]
	v_mfma_f32_16x16x32_bf16 v[52:55], v[156:159], v[202:205], v[52:55]
	v_mfma_f32_16x16x32_bf16 v[48:51], v[164:167], v[202:205], v[48:51]
	v_mfma_f32_16x16x32_bf16 v[36:39], v[156:159], v[210:213], v[36:39]
	v_mfma_f32_16x16x32_bf16 v[32:35], v[164:167], v[210:213], v[32:35]
	v_mfma_f32_16x16x32_bf16 v[20:23], v[156:159], v[218:221], v[20:23]
	v_mfma_f32_16x16x32_bf16 v[16:19], v[164:167], v[218:221], v[16:19]
	v_mfma_f32_16x16x32_bf16 v[60:63], v[160:163], v[198:201], v[60:63]
	v_mfma_f32_16x16x32_bf16 v[56:59], v[168:171], v[198:201], v[56:59]
	v_mfma_f32_16x16x32_bf16 v[52:55], v[160:163], v[206:209], v[52:55]
	v_mfma_f32_16x16x32_bf16 v[48:51], v[168:171], v[206:209], v[48:51]
	v_mfma_f32_16x16x32_bf16 v[36:39], v[160:163], v[214:217], v[36:39]
	v_mfma_f32_16x16x32_bf16 v[32:35], v[168:171], v[214:217], v[32:35]
	v_mfma_f32_16x16x32_bf16 v[20:23], v[160:163], v[222:225], v[20:23]
	v_mfma_f32_16x16x32_bf16 v[16:19], v[168:171], v[222:225], v[16:19]
	v_mfma_f32_16x16x32_bf16 v[44:47], v[172:175], v[194:197], v[44:47]
	v_mfma_f32_16x16x32_bf16 v[40:43], v[182:185], v[194:197], v[40:43]
	v_mfma_f32_16x16x32_bf16 v[28:31], v[172:175], v[202:205], v[28:31]
	v_mfma_f32_16x16x32_bf16 v[24:27], v[182:185], v[202:205], v[24:27]
	v_mfma_f32_16x16x32_bf16 v[12:15], v[172:175], v[210:213], v[12:15]
	v_mfma_f32_16x16x32_bf16 v[8:11], v[182:185], v[210:213], v[8:11]
	v_mfma_f32_16x16x32_bf16 v[4:7], v[172:175], v[218:221], v[4:7]
	v_mfma_f32_16x16x32_bf16 v[0:3], v[182:185], v[218:221], v[0:3]
	v_mfma_f32_16x16x32_bf16 v[44:47], v[176:179], v[198:201], v[44:47]
	v_mfma_f32_16x16x32_bf16 v[40:43], v[190:193], v[198:201], v[40:43]
	v_mfma_f32_16x16x32_bf16 v[28:31], v[176:179], v[206:209], v[28:31]
	v_mfma_f32_16x16x32_bf16 v[24:27], v[190:193], v[206:209], v[24:27]
	v_mfma_f32_16x16x32_bf16 v[12:15], v[176:179], v[214:217], v[12:15]
	v_mfma_f32_16x16x32_bf16 v[8:11], v[190:193], v[214:217], v[8:11]
	v_mfma_f32_16x16x32_bf16 v[4:7], v[176:179], v[222:225], v[4:7]
	v_mfma_f32_16x16x32_bf16 v[0:3], v[190:193], v[222:225], v[0:3]
	s_barrier
	s_add_i32 s49, s49, 2
	s_add_u32 s22, s22, 0x100
	s_addc_u32 s23, s23, 0
	s_add_u32 s47, s47, 0x100
	s_addc_u32 s48, s48, 0
	s_cmp_gt_u32 s49, 13
	s_cbranch_scc0 .LBB0_150
	s_and_b64 vcc, exec, s[10:11]
	s_cbranch_vccz .LBB0_153
	s_barrier

;     __host__ __device__ bool next(int i, Unit& u) const { const long L = (long)i * G + c; if (L >= nwg) return false; return unit_of((int)L, u); }
;     __host__ __device__ bool next(int i, Unit& u) const { const int L = i == 0 ? l0 : (i == 1 ? l1 : (i == 2 ? l2 : -1)); if (L < 0 || L >= s.nwg) return false; return s.unit_of(L, u); }
;     __host__ __device__ bool next(int i, Unit& u) const { const bool ok = s.next(i >> 1, u); u.kh = i & 1; return ok; }
; #define PG8_STAGE(bufoff, gbase, voff) do { _Pragma("unroll") for (int _i = 0; _i < 2; ++_i) \
;         __builtin_amdgcn_global_load_lds((const unsigned*)((const char*)(gbase) + (voff)[_i]), (PG8_LAS unsigned*)(lds + (bufoff) + ldsw + _i * 8192), 16, 0, 0); } while (0)
; #define PG8_LDA(dst, b, h) do { _Pragma("unroll") for (int m = 0; m < 4; ++m) _Pragma("unroll") for (int k = 0; k < 2; ++k) dst[m][k] = *(const PG8_LAS bf16x8*)(lds + PG8_SA(b, h) + aoff + m * 2048 + k * 1024); } while (0)
; template <class Epi, class Sched, bool ALIGN_EPI = false, bool SP2 = false>
; __device__ __forceinline__ void gemm_phase(PG8_LAS unsigned char* lds, const Gemm g, const Sched& S, const Epi& E) {
;     ...
;         const bool has_next = S.next(ui + 1, nxt);
;         const char* nA = has_next ? (const char*)g.A + (size_t)nxt.pm * tstep + nxt.kh * khb : cA; const char* nB = has_next ? (const char*)g.Bt + (size_t)nxt.pn * tstep + nxt.kh * khb : cB;
;         for (int t = 0; t < nt; t += 2) {
;             const bool last = (t == nt - 2);
;             const char* a1 = cA + (size_t)(t + 1) * kstep;
;             const char* a2 = last ? nA : cA + (size_t)(t + 2) * kstep; const char* b2 = last ? nB : cB + (size_t)(t + 2) * kstep;
;             const char* a3 = a2 + kstep; const char* b3 = b2 + kstep;
;             if (last && has_next) S.a_ready(nxt);
;             if constexpr (SP2) {
;             PG8_LDB(B0, 0, 0); PG8_LDB(B1, 0, 1); PG8_SCHED; PG8_LDA(At, 0, 0); PG8_STAGE(PG8_SA(1, 1), a1 + hstep, voffA);
;             PG8_WAIT_V(8); PG8_WAIT_L(0); PG8_BAR; PG8_MMA(0, 0, At, B0); PG8_MMA(0, 1, At, B1); PG8_BAR; PG8_SCHED;
;             PG8_LDA(At, 0, 1); PG8_STAGE(PG8_SB(0, 0), b2, voffB); PG8_STAGE(PG8_SB(0, 1), b2 + hstep, voffB); PG8_STAGE(PG8_SA(0, 0), a2, voffA);
;             PG8_WAIT_V(8); PG8_WAIT_L(0); PG8_BAR; PG8_MMA(1, 0, At, B0); PG8_MMA(1, 1, At, B1); PG8_BAR; PG8_SCHED;
.LBB0_683:
	s_ashr_i32 s3, s2, 31
	s_lshl_b64 s[12:13], s[2:3], 19
	v_readlane_b32 s3, v254, 13
	s_add_u32 s16, s3, s12
	v_readlane_b32 s3, v254, 17
	s_addc_u32 s17, s3, s13
	s_and_b64 s[12:13], s[38:39], exec
	s_cselect_b32 s3, s17, s1
	s_cselect_b32 s94, s16, s0
	s_ashr_i32 s5, s4, 31
	s_lshl_b64 s[12:13], s[4:5], 19
	v_readlane_b32 s5, v254, 15
	s_add_u32 s12, s5, s12
	s_addc_u32 s13, s50, s13
	s_and_b64 s[42:43], s[38:39], exec
	s_cselect_b32 s5, s13, s41
	s_cselect_b32 s95, s12, s40
	s_add_u32 s0, s0, 0x40080
	s_addc_u32 s1, s1, 0
	s_add_u32 s96, s40, 0x100
	s_addc_u32 s97, s41, 0
	s_mov_b32 vcc_lo, -2
	ds_read_b128 v[128:131], v174
	ds_read_b128 v[132:135], v174 offset:1024
	ds_read_b128 v[136:139], v174 offset:2048
	ds_read_b128 v[140:143], v174 offset:3072
	ds_read_b128 v[162:165], v175
	ds_read_b128 v[166:169], v175 offset:1024
	ds_read_b128 v[180:183], v175 offset:2048
	ds_read_b128 v[184:187], v175 offset:3072
	s_add_u32 s8, s0, 0xfffc0080
	s_addc_u32 s9, s1, -1
	s_cmp_eq_u32 vcc_lo, 12
	s_cselect_b32 s43, s3, s9
	s_cselect_b32 s42, s94, s8
	s_cselect_b32 s41, s5, s97
	s_cselect_b32 s40, s95, s96
	s_add_i32 m0, s47, 0xc000
	ds_read_b128 v[190:193], v176
	ds_read_b128 v[194:197], v176 offset:1024
	ds_read_b128 v[198:201], v176 offset:2048
	ds_read_b128 v[202:205], v176 offset:3072
	ds_read_b128 v[206:209], v176 offset:4096
	ds_read_b128 v[210:213], v176 offset:5120
	ds_read_b128 v[214:217], v176 offset:6144
	ds_read_b128 v[218:221], v176 offset:7168
	global_load_lds_dwordx4 v158, s[0:1]
	s_add_i32 m0, s47, 0xe000
	s_nop 0
	global_load_lds_dwordx4 v160, s[0:1]
	s_waitcnt vmcnt(8)
	s_waitcnt lgkmcnt(0)
	s_barrier
	v_mfma_f32_16x16x32_bf16 v[124:127], v[128:131], v[190:193], 0
	v_mfma_f32_16x16x32_bf16 v[120:123], v[136:139], v[190:193], 0
	v_mfma_f32_16x16x32_bf16 v[108:111], v[128:131], v[198:201], 0
	v_mfma_f32_16x16x32_bf16 v[104:107], v[136:139], v[198:201], 0
	v_mfma_f32_16x16x32_bf16 v[92:95], v[128:131], v[206:209], 0
	v_mfma_f32_16x16x32_bf16 v[88:91], v[136:139], v[206:209], 0
	v_mfma_f32_16x16x32_bf16 v[76:79], v[128:131], v[214:217], 0
	v_mfma_f32_16x16x32_bf16 v[72:75], v[136:139], v[214:217], 0
	v_mfma_f32_16x16x32_bf16 v[124:127], v[132:135], v[194:197], v[124:127]
	v_mfma_f32_16x16x32_bf16 v[120:123], v[140:143], v[194:197], v[120:123]
	v_mfma_f32_16x16x32_bf16 v[108:111], v[132:135], v[202:205], v[108:111]
	v_mfma_f32_16x16x32_bf16 v[104:107], v[140:143], v[202:205], v[104:107]
	v_mfma_f32_16x16x32_bf16 v[92:95], v[132:135], v[210:213], v[92:95]
	v_mfma_f32_16x16x32_bf16 v[88:91], v[140:143], v[210:213], v[88:91]
	v_mfma_f32_16x16x32_bf16 v[76:79], v[132:135], v[218:221], v[76:79]
	v_mfma_f32_16x16x32_bf16 v[72:75], v[140:143], v[218:221], v[72:75]
	v_mfma_f32_16x16x32_bf16 v[116:119], v[162:165], v[190:193], 0
	v_mfma_f32_16x16x32_bf16 v[112:115], v[180:183], v[190:193], 0
	v_mfma_f32_16x16x32_bf16 v[100:103], v[162:165], v[198:201], 0
	v_mfma_f32_16x16x32_bf16 v[96:99], v[180:183], v[198:201], 0
	v_mfma_f32_16x16x32_bf16 v[84:87], v[162:165], v[206:209], 0
	v_mfma_f32_16x16x32_bf16 v[80:83], v[180:183], v[206:209], 0
	v_mfma_f32_16x16x32_bf16 v[68:71], v[162:165], v[214:217], 0
	v_mfma_f32_16x16x32_bf16 v[64:67], v[180:183], v[214:217], 0
	v_mfma_f32_16x16x32_bf16 v[116:119], v[166:169], v[194:197], v[116:119]
	v_mfma_f32_16x16x32_bf16 v[112:115], v[184:187], v[194:197], v[112:115]
	v_mfma_f32_16x16x32_bf16 v[100:103], v[166:169], v[202:205], v[100:103]
	v_mfma_f32_16x16x32_bf16 v[96:99], v[184:187], v[202:205], v[96:99]
	v_mfma_f32_16x16x32_bf16 v[84:87], v[166:169], v[210:213], v[84:87]
	v_mfma_f32_16x16x32_bf16 v[80:83], v[184:187], v[210:213], v[80:83]
	v_mfma_f32_16x16x32_bf16 v[68:71], v[166:169], v[218:221], v[68:71]
	v_mfma_f32_16x16x32_bf16 v[64:67], v[184:187], v[218:221], v[64:67]
	s_barrier
	s_add_u32 s98, s40, s14
	s_addc_u32 s99, s41, s15
	s_add_u32 s100, s42, s14
	s_addc_u32 s101, s43, s15
	s_add_i32 s8, s76, s46
	s_mov_b32 m0, s8
	ds_read_b128 v[190:193], v176 offset:16384
	ds_read_b128 v[194:197], v176 offset:17408
	ds_read_b128 v[198:201], v176 offset:18432
	ds_read_b128 v[202:205], v176 offset:19456
	ds_read_b128 v[206:209], v176 offset:20480
	ds_read_b128 v[210:213], v176 offset:21504
	ds_read_b128 v[214:217], v176 offset:22528
	ds_read_b128 v[218:221], v176 offset:23552
	global_load_lds_dwordx4 v146, s[40:41]
	s_add_i32 m0, s8, 0x2000
	s_add_u32 s8, s40, 0x40000
	s_addc_u32 s9, s41, 0
	s_add_i32 s54, s77, s46
	global_load_lds_dwordx4 v150, s[40:41]
	s_mov_b32 m0, s54
	s_nop 0
	global_load_lds_dwordx4 v146, s[8:9]
	s_add_i32 m0, s54, 0x2000
	s_nop 0
	global_load_lds_dwordx4 v150, s[8:9]
	s_mov_b32 m0, s47
	s_nop 0
	global_load_lds_dwordx4 v144, s[42:43]
	s_mov_b32 m0, s48
	s_nop 0
	global_load_lds_dwordx4 v148, s[42:43]
	s_waitcnt vmcnt(8)
	s_waitcnt lgkmcnt(0)
	s_barrier
	v_mfma_f32_16x16x32_bf16 v[60:63], v[128:131], v[190:193], 0
	v_mfma_f32_16x16x32_bf16 v[56:59], v[136:139], v[190:193], 0
	v_mfma_f32_16x16x32_bf16 v[44:47], v[128:131], v[198:201], 0
	v_mfma_f32_16x16x32_bf16 v[40:43], v[136:139], v[198:201], 0
	v_mfma_f32_16x16x32_bf16 v[28:31], v[128:131], v[206:209], 0
	v_mfma_f32_16x16x32_bf16 v[24:27], v[136:139], v[206:209], 0
	v_mfma_f32_16x16x32_bf16 v[12:15], v[128:131], v[214:217], 0
	v_mfma_f32_16x16x32_bf16 v[8:11], v[136:139], v[214:217], 0
	v_mfma_f32_16x16x32_bf16 v[60:63], v[132:135], v[194:197], v[60:63]
	v_mfma_f32_16x16x32_bf16 v[56:59], v[140:143], v[194:197], v[56:59]
	v_mfma_f32_16x16x32_bf16 v[44:47], v[132:135], v[202:205], v[44:47]
	v_mfma_f32_16x16x32_bf16 v[40:43], v[140:143], v[202:205], v[40:43]
	v_mfma_f32_16x16x32_bf16 v[28:31], v[132:135], v[210:213], v[28:31]
	v_mfma_f32_16x16x32_bf16 v[24:27], v[140:143], v[210:213], v[24:27]
	v_mfma_f32_16x16x32_bf16 v[12:15], v[132:135], v[218:221], v[12:15]
	v_mfma_f32_16x16x32_bf16 v[8:11], v[140:143], v[218:221], v[8:11]
	v_mfma_f32_16x16x32_bf16 v[52:55], v[162:165], v[190:193], 0
	v_mfma_f32_16x16x32_bf16 v[48:51], v[180:183], v[190:193], 0
	v_mfma_f32_16x16x32_bf16 v[36:39], v[162:165], v[198:201], 0
	v_mfma_f32_16x16x32_bf16 v[32:35], v[180:183], v[198:201], 0
	v_mfma_f32_16x16x32_bf16 v[20:23], v[162:165], v[206:209], 0
	v_mfma_f32_16x16x32_bf16 v[16:19], v[180:183], v[206:209], 0
	v_mfma_f32_16x16x32_bf16 v[4:7], v[162:165], v[214:217], 0
	v_mfma_f32_16x16x32_bf16 v[0:3], v[180:183], v[214:217], 0
	v_mfma_f32_16x16x32_bf16 v[52:55], v[166:169], v[194:197], v[52:55]
	v_mfma_f32_16x16x32_bf16 v[48:51], v[184:187], v[194:197], v[48:51]
	v_mfma_f32_16x16x32_bf16 v[36:39], v[166:169], v[202:205], v[36:39]
	v_mfma_f32_16x16x32_bf16 v[32:35], v[184:187], v[202:205], v[32:35]
	v_mfma_f32_16x16x32_bf16 v[20:23], v[166:169], v[210:213], v[20:23]
	v_mfma_f32_16x16x32_bf16 v[16:19], v[184:187], v[210:213], v[16:19]
	v_mfma_f32_16x16x32_bf16 v[4:7], v[166:169], v[218:221], v[4:7]
	v_mfma_f32_16x16x32_bf16 v[0:3], v[184:187], v[218:221], v[0:3]
	s_barrier
	s_branch .Lmy_peel_684_mid
; #define PG8_STAGE(bufoff, gbase, voff) do { _Pragma("unroll") for (int _i = 0; _i < 2; ++_i) \
;         __builtin_amdgcn_global_load_lds((const unsigned*)((const char*)(gbase) + (voff)[_i]), (PG8_LAS unsigned*)(lds + (bufoff) + ldsw + _i * 8192), 16, 0, 0); } while (0)
; #define PG8_LDA(dst, b, h) do { _Pragma("unroll") for (int m = 0; m < 4; ++m) _Pragma("unroll") for (int k = 0; k < 2; ++k) dst[m][k] = *(const PG8_LAS bf16x8*)(lds + PG8_SA(b, h) + aoff + m * 2048 + k * 1024); } while (0)
; #define PG8_LDB(dst, b, h) do { _Pragma("unroll") for (int n = 0; n < 2; ++n) _Pragma("unroll") for (int k = 0; k < 2; ++k) dst[n][k] = *(const PG8_LAS bf16x8*)(lds + PG8_SB(b, h) + boff + n * 2048 + k * 1024); } while (0)
; #define PG8_MMA(ai, bj, At, Bt) do { __builtin_amdgcn_s_setprio(1); _Pragma("unroll") for (int m = 0; m < 4; ++m) _Pragma("unroll") for (int n = 0; n < 2; ++n) _Pragma("unroll") for (int k = 0; k < 2; ++k) \
;         acc[ai][bj][m][n] = __builtin_amdgcn_mfma_f32_16x16x32_bf16(Bt[n][k], At[m][k], acc[ai][bj][m][n], 0, 0, 0); __builtin_amdgcn_s_setprio(0); } while (0)
; #define PG8_WAIT_V(n) asm volatile("s_waitcnt vmcnt(" #n ")" ::: "memory")
; #define PG8_WAIT_L(n) asm volatile("s_waitcnt lgkmcnt(" #n ")" ::: "memory")
; template <class Epi, class Sched, bool ALIGN_EPI = false, bool SP2 = false>
; __device__ __forceinline__ void gemm_phase(PG8_LAS unsigned char* lds, const Gemm g, const Sched& S, const Epi& E) {
;     ...
;             const bool last = (t == nt - 2);
;             const char* a1 = cA + (size_t)(t + 1) * kstep;
;             const char* a2 = last ? nA : cA + (size_t)(t + 2) * kstep; const char* b2 = last ? nB : cB + (size_t)(t + 2) * kstep;
;             const char* a3 = a2 + kstep; const char* b3 = b2 + kstep;
;             if (last && has_next) S.a_ready(nxt);
;             if constexpr (SP2) {
;             PG8_LDB(B0, 0, 0); PG8_LDB(B1, 0, 1); PG8_SCHED; PG8_LDA(At, 0, 0); PG8_STAGE(PG8_SA(1, 1), a1 + hstep, voffA);
;             PG8_WAIT_V(8); PG8_WAIT_L(0); PG8_BAR; PG8_MMA(0, 0, At, B0); PG8_MMA(0, 1, At, B1); PG8_BAR; PG8_SCHED;
;             PG8_LDA(At, 0, 1); PG8_STAGE(PG8_SB(0, 0), b2, voffB); PG8_STAGE(PG8_SB(0, 1), b2 + hstep, voffB); PG8_STAGE(PG8_SA(0, 0), a2, voffA);
;             PG8_WAIT_V(8); PG8_WAIT_L(0); PG8_BAR; PG8_MMA(1, 0, At, B0); PG8_MMA(1, 1, At, B1); PG8_BAR; PG8_SCHED;
.LBB0_684:
	ds_read_b128 v[128:131], v174
	ds_read_b128 v[132:135], v174 offset:1024
	ds_read_b128 v[136:139], v174 offset:2048
	ds_read_b128 v[140:143], v174 offset:3072
	ds_read_b128 v[162:165], v175
	ds_read_b128 v[166:169], v175 offset:1024
	ds_read_b128 v[180:183], v175 offset:2048
	ds_read_b128 v[184:187], v175 offset:3072
	s_add_u32 s8, s0, 0xfffc0080
	s_addc_u32 s9, s1, -1
	s_cmp_eq_u32 vcc_lo, 12
	s_cselect_b32 s43, s3, s9
	s_cselect_b32 s42, s94, s8
	s_cselect_b32 s41, s5, s97
	s_cselect_b32 s40, s95, s96
	s_add_i32 m0, s47, 0xc000
	ds_read_b128 v[190:193], v176
	ds_read_b128 v[194:197], v176 offset:1024
	ds_read_b128 v[198:201], v176 offset:2048
	ds_read_b128 v[202:205], v176 offset:3072
	ds_read_b128 v[206:209], v176 offset:4096
	ds_read_b128 v[210:213], v176 offset:5120
	ds_read_b128 v[214:217], v176 offset:6144
	ds_read_b128 v[218:221], v176 offset:7168
	global_load_lds_dwordx4 v158, s[0:1]
	s_add_i32 m0, s47, 0xe000
	s_nop 0
	global_load_lds_dwordx4 v160, s[0:1]
	s_waitcnt vmcnt(8)
	s_waitcnt lgkmcnt(0)
	s_barrier
	v_mfma_f32_16x16x32_bf16 v[124:127], v[128:131], v[190:193], v[124:127]
	v_mfma_f32_16x16x32_bf16 v[120:123], v[136:139], v[190:193], v[120:123]
	v_mfma_f32_16x16x32_bf16 v[108:111], v[128:131], v[198:201], v[108:111]
	v_mfma_f32_16x16x32_bf16 v[104:107], v[136:139], v[198:201], v[104:107]
	v_mfma_f32_16x16x32_bf16 v[92:95], v[128:131], v[206:209], v[92:95]
	v_mfma_f32_16x16x32_bf16 v[88:91], v[136:139], v[206:209], v[88:91]
	v_mfma_f32_16x16x32_bf16 v[76:79], v[128:131], v[214:217], v[76:79]
	v_mfma_f32_16x16x32_bf16 v[72:75], v[136:139], v[214:217], v[72:75]
	v_mfma_f32_16x16x32_bf16 v[124:127], v[132:135], v[194:197], v[124:127]
	v_mfma_f32_16x16x32_bf16 v[120:123], v[140:143], v[194:197], v[120:123]
	v_mfma_f32_16x16x32_bf16 v[108:111], v[132:135], v[202:205], v[108:111]
	v_mfma_f32_16x16x32_bf16 v[104:107], v[140:143], v[202:205], v[104:107]
	v_mfma_f32_16x16x32_bf16 v[92:95], v[132:135], v[210:213], v[92:95]
	v_mfma_f32_16x16x32_bf16 v[88:91], v[140:143], v[210:213], v[88:91]
	v_mfma_f32_16x16x32_bf16 v[76:79], v[132:135], v[218:221], v[76:79]
	v_mfma_f32_16x16x32_bf16 v[72:75], v[140:143], v[218:221], v[72:75]
	v_mfma_f32_16x16x32_bf16 v[116:119], v[162:165], v[190:193], v[116:119]
	v_mfma_f32_16x16x32_bf16 v[112:115], v[180:183], v[190:193], v[112:115]
	v_mfma_f32_16x16x32_bf16 v[100:103], v[162:165], v[198:201], v[100:103]
	v_mfma_f32_16x16x32_bf16 v[96:99], v[180:183], v[198:201], v[96:99]
	v_mfma_f32_16x16x32_bf16 v[84:87], v[162:165], v[206:209], v[84:87]
	v_mfma_f32_16x16x32_bf16 v[80:83], v[180:183], v[206:209], v[80:83]
	v_mfma_f32_16x16x32_bf16 v[68:71], v[162:165], v[214:217], v[68:71]
	v_mfma_f32_16x16x32_bf16 v[64:67], v[180:183], v[214:217], v[64:67]
	v_mfma_f32_16x16x32_bf16 v[116:119], v[166:169], v[194:197], v[116:119]
	v_mfma_f32_16x16x32_bf16 v[112:115], v[184:187], v[194:197], v[112:115]
	v_mfma_f32_16x16x32_bf16 v[100:103], v[166:169], v[202:205], v[100:103]
	v_mfma_f32_16x16x32_bf16 v[96:99], v[184:187], v[202:205], v[96:99]
	v_mfma_f32_16x16x32_bf16 v[84:87], v[166:169], v[210:213], v[84:87]
	v_mfma_f32_16x16x32_bf16 v[80:83], v[184:187], v[210:213], v[80:83]
	v_mfma_f32_16x16x32_bf16 v[68:71], v[166:169], v[218:221], v[68:71]
	v_mfma_f32_16x16x32_bf16 v[64:67], v[184:187], v[218:221], v[64:67]
	s_barrier
	s_add_u32 s98, s40, s14
	s_addc_u32 s99, s41, s15
	s_add_u32 s100, s42, s14
	s_addc_u32 s101, s43, s15
	s_add_i32 s8, s76, s46
	s_mov_b32 m0, s8
	ds_read_b128 v[190:193], v176 offset:16384
	ds_read_b128 v[194:197], v176 offset:17408
	ds_read_b128 v[198:201], v176 offset:18432
	ds_read_b128 v[202:205], v176 offset:19456
	ds_read_b128 v[206:209], v176 offset:20480
	ds_read_b128 v[210:213], v176 offset:21504
	ds_read_b128 v[214:217], v176 offset:22528
	ds_read_b128 v[218:221], v176 offset:23552
	global_load_lds_dwordx4 v146, s[40:41]
	s_add_i32 m0, s8, 0x2000
	s_add_u32 s8, s40, 0x40000
	s_addc_u32 s9, s41, 0
	s_add_i32 s54, s77, s46
	global_load_lds_dwordx4 v150, s[40:41]
	s_mov_b32 m0, s54
	s_nop 0
	global_load_lds_dwordx4 v146, s[8:9]
	s_add_i32 m0, s54, 0x2000
	s_nop 0
	global_load_lds_dwordx4 v150, s[8:9]
	s_mov_b32 m0, s47
	s_nop 0
	global_load_lds_dwordx4 v144, s[42:43]
	s_mov_b32 m0, s48
	s_nop 0
	global_load_lds_dwordx4 v148, s[42:43]
	s_waitcnt vmcnt(8)
	s_waitcnt lgkmcnt(0)
	s_barrier
	v_mfma_f32_16x16x32_bf16 v[60:63], v[128:131], v[190:193], v[60:63]
	v_mfma_f32_16x16x32_bf16 v[56:59], v[136:139], v[190:193], v[56:59]
	v_mfma_f32_16x16x32_bf16 v[44:47], v[128:131], v[198:201], v[44:47]
	v_mfma_f32_16x16x32_bf16 v[40:43], v[136:139], v[198:201], v[40:43]
	v_mfma_f32_16x16x32_bf16 v[28:31], v[128:131], v[206:209], v[28:31]
	v_mfma_f32_16x16x32_bf16 v[24:27], v[136:139], v[206:209], v[24:27]
	v_mfma_f32_16x16x32_bf16 v[12:15], v[128:131], v[214:217], v[12:15]
	v_mfma_f32_16x16x32_bf16 v[8:11], v[136:139], v[214:217], v[8:11]
	v_mfma_f32_16x16x32_bf16 v[60:63], v[132:135], v[194:197], v[60:63]
	v_mfma_f32_16x16x32_bf16 v[56:59], v[140:143], v[194:197], v[56:59]
	v_mfma_f32_16x16x32_bf16 v[44:47], v[132:135], v[202:205], v[44:47]
	v_mfma_f32_16x16x32_bf16 v[40:43], v[140:143], v[202:205], v[40:43]
	v_mfma_f32_16x16x32_bf16 v[28:31], v[132:135], v[210:213], v[28:31]
	v_mfma_f32_16x16x32_bf16 v[24:27], v[140:143], v[210:213], v[24:27]
	v_mfma_f32_16x16x32_bf16 v[12:15], v[132:135], v[218:221], v[12:15]
	v_mfma_f32_16x16x32_bf16 v[8:11], v[140:143], v[218:221], v[8:11]
	v_mfma_f32_16x16x32_bf16 v[52:55], v[162:165], v[190:193], v[52:55]
	v_mfma_f32_16x16x32_bf16 v[48:51], v[180:183], v[190:193], v[48:51]
	v_mfma_f32_16x16x32_bf16 v[36:39], v[162:165], v[198:201], v[36:39]
	v_mfma_f32_16x16x32_bf16 v[32:35], v[180:183], v[198:201], v[32:35]
	v_mfma_f32_16x16x32_bf16 v[20:23], v[162:165], v[206:209], v[20:23]
	v_mfma_f32_16x16x32_bf16 v[16:19], v[180:183], v[206:209], v[16:19]
	v_mfma_f32_16x16x32_bf16 v[4:7], v[162:165], v[214:217], v[4:7]
	v_mfma_f32_16x16x32_bf16 v[0:3], v[180:183], v[214:217], v[0:3]
	v_mfma_f32_16x16x32_bf16 v[52:55], v[166:169], v[194:197], v[52:55]
	v_mfma_f32_16x16x32_bf16 v[48:51], v[184:187], v[194:197], v[48:51]
	v_mfma_f32_16x16x32_bf16 v[36:39], v[166:169], v[202:205], v[36:39]
	v_mfma_f32_16x16x32_bf16 v[32:35], v[184:187], v[202:205], v[32:35]
	v_mfma_f32_16x16x32_bf16 v[20:23], v[166:169], v[210:213], v[20:23]
	v_mfma_f32_16x16x32_bf16 v[16:19], v[184:187], v[210:213], v[16:19]
	v_mfma_f32_16x16x32_bf16 v[4:7], v[166:169], v[218:221], v[4:7]
	v_mfma_f32_16x16x32_bf16 v[0:3], v[184:187], v[218:221], v[0:3]
	s_barrier
; #define PG8_STAGE(bufoff, gbase, voff) do { _Pragma("unroll") for (int _i = 0; _i < 2; ++_i) \
;         __builtin_amdgcn_global_load_lds((const unsigned*)((const char*)(gbase) + (voff)[_i]), (PG8_LAS unsigned*)(lds + (bufoff) + ldsw + _i * 8192), 16, 0, 0); } while (0)
; #define PG8_LDA(dst, b, h) do { _Pragma("unroll") for (int m = 0; m < 4; ++m) _Pragma("unroll") for (int k = 0; k < 2; ++k) dst[m][k] = *(const PG8_LAS bf16x8*)(lds + PG8_SA(b, h) + aoff + m * 2048 + k * 1024); } while (0)
; #define PG8_LDB(dst, b, h) do { _Pragma("unroll") for (int n = 0; n < 2; ++n) _Pragma("unroll") for (int k = 0; k < 2; ++k) dst[n][k] = *(const PG8_LAS bf16x8*)(lds + PG8_SB(b, h) + boff + n * 2048 + k * 1024); } while (0)
; #define PG8_MMA(ai, bj, At, Bt) do { __builtin_amdgcn_s_setprio(1); _Pragma("unroll") for (int m = 0; m < 4; ++m) _Pragma("unroll") for (int n = 0; n < 2; ++n) _Pragma("unroll") for (int k = 0; k < 2; ++k) \
;         acc[ai][bj][m][n] = __builtin_amdgcn_mfma_f32_16x16x32_bf16(Bt[n][k], At[m][k], acc[ai][bj][m][n], 0, 0, 0); __builtin_amdgcn_s_setprio(0); } while (0)
; #define PG8_WAIT_V(n) asm volatile("s_waitcnt vmcnt(" #n ")" ::: "memory")
; #define PG8_WAIT_L(n) asm volatile("s_waitcnt lgkmcnt(" #n ")" ::: "memory")
; #define PG8_BAR __builtin_amdgcn_s_barrier()
; #define PG8_SCHED __builtin_amdgcn_sched_barrier(0)
; template <class Epi, class Sched, bool ALIGN_EPI = false, bool SP2 = false>
; __device__ __forceinline__ void gemm_phase(PG8_LAS unsigned char* lds, const Gemm g, const Sched& S, const Epi& E) {
;     ...
;             PG8_LDB(B0, 1, 0); PG8_LDB(B1, 1, 1); PG8_SCHED; PG8_LDA(At, 1, 0); PG8_STAGE(PG8_SA(0, 1), a2 + hstep, voffA);
;             PG8_WAIT_V(8); PG8_WAIT_L(0); PG8_BAR; PG8_MMA(0, 0, At, B0); PG8_MMA(0, 1, At, B1); PG8_BAR; PG8_SCHED;
;             PG8_LDA(At, 1, 1); PG8_STAGE(PG8_SB(1, 0), b3, voffB); PG8_STAGE(PG8_SB(1, 1), b3 + hstep, voffB); PG8_STAGE(PG8_SA(1, 0), a3, voffA);
;             PG8_WAIT_V(8); PG8_WAIT_L(0); PG8_BAR; PG8_MMA(1, 0, At, B0); PG8_MMA(1, 1, At, B1); PG8_BAR; PG8_SCHED;
.Lmy_peel_684_mid:
	s_add_i32 s54, 0, 0x18000
	s_add_i32 s55, 0, 0x1c000
	v_add_u32_e32 v140, s54, v172
	v_add_u32_e32 v152, s55, v172
	ds_read_b128 v[128:131], v140
	ds_read_b128 v[132:135], v140 offset:1024
	ds_read_b128 v[136:139], v140 offset:2048
	ds_read_b128 v[140:143], v140 offset:3072
	ds_read_b128 v[162:165], v152
	ds_read_b128 v[166:169], v152 offset:1024
	ds_read_b128 v[180:183], v152 offset:2048
	ds_read_b128 v[184:187], v152 offset:3072
	s_add_u32 s8, s42, 0x40000
	s_addc_u32 s9, s43, 0
	s_mov_b32 m0, s49
	ds_read_b128 v[190:193], v176 offset:32768
	ds_read_b128 v[194:197], v176 offset:33792
	ds_read_b128 v[198:201], v176 offset:34816
	ds_read_b128 v[202:205], v176 offset:35840
	ds_read_b128 v[206:209], v176 offset:36864
	ds_read_b128 v[210:213], v176 offset:37888
	ds_read_b128 v[214:217], v176 offset:38912
	ds_read_b128 v[218:221], v176 offset:39936
	global_load_lds_dwordx4 v144, s[8:9]
	s_mov_b32 m0, s51
	s_nop 0
	global_load_lds_dwordx4 v148, s[8:9]
	s_waitcnt vmcnt(8)
	s_waitcnt lgkmcnt(0)
	s_barrier
	v_mfma_f32_16x16x32_bf16 v[124:127], v[128:131], v[190:193], v[124:127]
	v_mfma_f32_16x16x32_bf16 v[120:123], v[136:139], v[190:193], v[120:123]
	v_mfma_f32_16x16x32_bf16 v[108:111], v[128:131], v[198:201], v[108:111]
	v_mfma_f32_16x16x32_bf16 v[104:107], v[136:139], v[198:201], v[104:107]
	v_mfma_f32_16x16x32_bf16 v[92:95], v[128:131], v[206:209], v[92:95]
	v_mfma_f32_16x16x32_bf16 v[88:91], v[136:139], v[206:209], v[88:91]
	v_mfma_f32_16x16x32_bf16 v[76:79], v[128:131], v[214:217], v[76:79]
	v_mfma_f32_16x16x32_bf16 v[72:75], v[136:139], v[214:217], v[72:75]
	v_mfma_f32_16x16x32_bf16 v[124:127], v[132:135], v[194:197], v[124:127]
	v_mfma_f32_16x16x32_bf16 v[120:123], v[140:143], v[194:197], v[120:123]
	v_mfma_f32_16x16x32_bf16 v[108:111], v[132:135], v[202:205], v[108:111]
	v_mfma_f32_16x16x32_bf16 v[104:107], v[140:143], v[202:205], v[104:107]
	v_mfma_f32_16x16x32_bf16 v[92:95], v[132:135], v[210:213], v[92:95]
	v_mfma_f32_16x16x32_bf16 v[88:91], v[140:143], v[210:213], v[88:91]
	v_mfma_f32_16x16x32_bf16 v[76:79], v[132:135], v[218:221], v[76:79]
	v_mfma_f32_16x16x32_bf16 v[72:75], v[140:143], v[218:221], v[72:75]
	v_mfma_f32_16x16x32_bf16 v[116:119], v[162:165], v[190:193], v[116:119]
	v_mfma_f32_16x16x32_bf16 v[112:115], v[180:183], v[190:193], v[112:115]
	v_mfma_f32_16x16x32_bf16 v[100:103], v[162:165], v[198:201], v[100:103]
	v_mfma_f32_16x16x32_bf16 v[96:99], v[180:183], v[198:201], v[96:99]
	v_mfma_f32_16x16x32_bf16 v[84:87], v[162:165], v[206:209], v[84:87]
	v_mfma_f32_16x16x32_bf16 v[80:83], v[180:183], v[206:209], v[80:83]
	v_mfma_f32_16x16x32_bf16 v[68:71], v[162:165], v[214:217], v[68:71]
	v_mfma_f32_16x16x32_bf16 v[64:67], v[180:183], v[214:217], v[64:67]
	v_mfma_f32_16x16x32_bf16 v[116:119], v[166:169], v[194:197], v[116:119]
	v_mfma_f32_16x16x32_bf16 v[112:115], v[184:187], v[194:197], v[112:115]
	v_mfma_f32_16x16x32_bf16 v[100:103], v[166:169], v[202:205], v[100:103]
	v_mfma_f32_16x16x32_bf16 v[96:99], v[184:187], v[202:205], v[96:99]
	v_mfma_f32_16x16x32_bf16 v[84:87], v[166:169], v[210:213], v[84:87]
	v_mfma_f32_16x16x32_bf16 v[80:83], v[184:187], v[210:213], v[80:83]
	v_mfma_f32_16x16x32_bf16 v[68:71], v[166:169], v[218:221], v[68:71]
	v_mfma_f32_16x16x32_bf16 v[64:67], v[184:187], v[218:221], v[64:67]
	s_barrier
	s_add_i32 s8, s54, s46
	s_mov_b32 m0, s8
	ds_read_b128 v[190:193], v176 offset:49152
	ds_read_b128 v[194:197], v176 offset:50176
	ds_read_b128 v[198:201], v176 offset:51200
	ds_read_b128 v[202:205], v176 offset:52224
	ds_read_b128 v[206:209], v176 offset:53248
	ds_read_b128 v[210:213], v176 offset:54272
	ds_read_b128 v[214:217], v176 offset:55296
	ds_read_b128 v[218:221], v176 offset:56320
	global_load_lds_dwordx4 v146, s[98:99]
	s_add_i32 m0, s8, 0x2000
	s_add_u32 s8, s40, 0x40080
	s_addc_u32 s9, s41, 0
	s_add_i32 s40, s55, s46
	global_load_lds_dwordx4 v150, s[98:99]
	s_mov_b32 m0, s40
	s_nop 0
	global_load_lds_dwordx4 v146, s[8:9]
	s_add_i32 m0, s40, 0x2000
	s_nop 0
	global_load_lds_dwordx4 v150, s[8:9]
	s_mov_b32 m0, s66
	s_nop 0
	global_load_lds_dwordx4 v144, s[100:101]
	s_mov_b32 m0, s67
	s_nop 0
	global_load_lds_dwordx4 v148, s[100:101]
	s_waitcnt vmcnt(8)
	s_waitcnt lgkmcnt(0)
	s_barrier
	v_mfma_f32_16x16x32_bf16 v[60:63], v[128:131], v[190:193], v[60:63]
	v_mfma_f32_16x16x32_bf16 v[56:59], v[136:139], v[190:193], v[56:59]
	v_mfma_f32_16x16x32_bf16 v[44:47], v[128:131], v[198:201], v[44:47]
	v_mfma_f32_16x16x32_bf16 v[40:43], v[136:139], v[198:201], v[40:43]
	v_mfma_f32_16x16x32_bf16 v[28:31], v[128:131], v[206:209], v[28:31]
	v_mfma_f32_16x16x32_bf16 v[24:27], v[136:139], v[206:209], v[24:27]
	v_mfma_f32_16x16x32_bf16 v[12:15], v[128:131], v[214:217], v[12:15]
	v_mfma_f32_16x16x32_bf16 v[8:11], v[136:139], v[214:217], v[8:11]
	v_mfma_f32_16x16x32_bf16 v[60:63], v[132:135], v[194:197], v[60:63]
	v_mfma_f32_16x16x32_bf16 v[56:59], v[140:143], v[194:197], v[56:59]
	v_mfma_f32_16x16x32_bf16 v[44:47], v[132:135], v[202:205], v[44:47]
	v_mfma_f32_16x16x32_bf16 v[40:43], v[140:143], v[202:205], v[40:43]
	v_mfma_f32_16x16x32_bf16 v[28:31], v[132:135], v[210:213], v[28:31]
	v_mfma_f32_16x16x32_bf16 v[24:27], v[140:143], v[210:213], v[24:27]
	v_mfma_f32_16x16x32_bf16 v[12:15], v[132:135], v[218:221], v[12:15]
	v_mfma_f32_16x16x32_bf16 v[8:11], v[140:143], v[218:221], v[8:11]
	v_mfma_f32_16x16x32_bf16 v[52:55], v[162:165], v[190:193], v[52:55]
	v_mfma_f32_16x16x32_bf16 v[48:51], v[180:183], v[190:193], v[48:51]
	v_mfma_f32_16x16x32_bf16 v[36:39], v[162:165], v[198:201], v[36:39]
	v_mfma_f32_16x16x32_bf16 v[32:35], v[180:183], v[198:201], v[32:35]
	v_mfma_f32_16x16x32_bf16 v[20:23], v[162:165], v[206:209], v[20:23]
	v_mfma_f32_16x16x32_bf16 v[16:19], v[180:183], v[206:209], v[16:19]
	v_mfma_f32_16x16x32_bf16 v[4:7], v[162:165], v[214:217], v[4:7]
	v_mfma_f32_16x16x32_bf16 v[0:3], v[180:183], v[214:217], v[0:3]
	v_mfma_f32_16x16x32_bf16 v[52:55], v[166:169], v[194:197], v[52:55]
	v_mfma_f32_16x16x32_bf16 v[48:51], v[184:187], v[194:197], v[48:51]
	v_mfma_f32_16x16x32_bf16 v[36:39], v[166:169], v[202:205], v[36:39]
	v_mfma_f32_16x16x32_bf16 v[32:35], v[184:187], v[202:205], v[32:35]
	v_mfma_f32_16x16x32_bf16 v[20:23], v[166:169], v[210:213], v[20:23]
	v_mfma_f32_16x16x32_bf16 v[16:19], v[184:187], v[210:213], v[16:19]
	v_mfma_f32_16x16x32_bf16 v[4:7], v[166:169], v[218:221], v[4:7]
	v_mfma_f32_16x16x32_bf16 v[0:3], v[184:187], v[218:221], v[0:3]
	s_barrier
	s_add_i32 vcc_lo, vcc_lo, 2
	s_add_u32 s0, s0, 0x100
	s_addc_u32 s1, s1, 0
	s_add_u32 s96, s96, 0x100
	s_addc_u32 s97, s97, 0
	s_cmp_gt_u32 vcc_lo, 13
	s_cbranch_scc0 .LBB0_684
	s_and_b64 vcc, exec, s[18:19]
	s_cbranch_vccz .LBB0_687
	s_barrier

; #define PG8_STAGE(bufoff, gbase, voff) do { _Pragma("unroll") for (int _i = 0; _i < 2; ++_i) \
;         __builtin_amdgcn_global_load_lds((const unsigned*)((const char*)(gbase) + (voff)[_i]), (PG8_LAS unsigned*)(lds + (bufoff) + ldsw + _i * 8192), 16, 0, 0); } while (0)
; #define PG8_LDA(dst, b, h) do { _Pragma("unroll") for (int m = 0; m < 4; ++m) _Pragma("unroll") for (int k = 0; k < 2; ++k) dst[m][k] = *(const PG8_LAS bf16x8*)(lds + PG8_SA(b, h) + aoff + m * 2048 + k * 1024); } while (0)
; #define PG8_LDB(dst, b, h) do { _Pragma("unroll") for (int n = 0; n < 2; ++n) _Pragma("unroll") for (int k = 0; k < 2; ++k) dst[n][k] = *(const PG8_LAS bf16x8*)(lds + PG8_SB(b, h) + boff + n * 2048 + k * 1024); } while (0)
; #define PG8_MMA(ai, bj, At, Bt) do { __builtin_amdgcn_s_setprio(1); _Pragma("unroll") for (int m = 0; m < 4; ++m) _Pragma("unroll") for (int n = 0; n < 2; ++n) _Pragma("unroll") for (int k = 0; k < 2; ++k) \
;         acc[ai][bj][m][n] = __builtin_amdgcn_mfma_f32_16x16x32_bf16(Bt[n][k], At[m][k], acc[ai][bj][m][n], 0, 0, 0); __builtin_amdgcn_s_setprio(0); } while (0)
; #define PG8_WAIT_V(n) asm volatile("s_waitcnt vmcnt(" #n ")" ::: "memory")
; #define PG8_WAIT_L(n) asm volatile("s_waitcnt lgkmcnt(" #n ")" ::: "memory")
; template <class Epi, class Sched, bool ALIGN_EPI = false, bool SP2 = false>
; __device__ __forceinline__ void gemm_phase(PG8_LAS unsigned char* lds, const Gemm g, const Sched& S, const Epi& E) {
;     ...
;             const bool last = (t == nt - 2);
;             const char* a1 = cA + (size_t)(t + 1) * kstep;
;             const char* a2 = last ? nA : cA + (size_t)(t + 2) * kstep; const char* b2 = last ? nB : cB + (size_t)(t + 2) * kstep;
;             const char* a3 = a2 + kstep; const char* b3 = b2 + kstep;
;             if (last && has_next) S.a_ready(nxt);
;             if constexpr (SP2) {
;             PG8_LDB(B0, 0, 0); PG8_LDB(B1, 0, 1); PG8_SCHED; PG8_LDA(At, 0, 0); PG8_STAGE(PG8_SA(1, 1), a1 + hstep, voffA);
;             PG8_WAIT_V(8); PG8_WAIT_L(0); PG8_BAR; PG8_MMA(0, 0, At, B0); PG8_MMA(0, 1, At, B1); PG8_BAR; PG8_SCHED;
;             PG8_LDA(At, 0, 1); PG8_STAGE(PG8_SB(0, 0), b2, voffB); PG8_STAGE(PG8_SB(0, 1), b2 + hstep, voffB); PG8_STAGE(PG8_SA(0, 0), a2, voffA);
;             PG8_WAIT_V(8); PG8_WAIT_L(0); PG8_BAR; PG8_MMA(1, 0, At, B0); PG8_MMA(1, 1, At, B1); PG8_BAR; PG8_SCHED;
.LBB0_795:
	v_add_u32_e32 v162, s67, v186
	v_add_u32_e32 v178, s68, v186
	ds_read_b128 v[150:153], v162
	ds_read_b128 v[154:157], v162 offset:1024
	ds_read_b128 v[158:161], v162 offset:2048
	ds_read_b128 v[162:165], v162 offset:3072
	ds_read_b128 v[166:169], v178
	ds_read_b128 v[170:173], v178 offset:1024
	ds_read_b128 v[174:177], v178 offset:2048
	ds_read_b128 v[178:181], v178 offset:3072
	s_add_u32 s54, s46, 0xfff80080
	s_addc_u32 s55, s47, -1
	s_cmp_eq_u32 s82, 12
	s_cselect_b32 s57, s41, s55
	s_cselect_b32 s56, s78, s54
	s_cselect_b32 s55, s39, s81
	s_cselect_b32 s54, s79, s80
	s_add_i32 m0, s61, 0xc000
	ds_read_b128 v[182:185], v187
	ds_read_b128 v[190:193], v187 offset:1024
	ds_read_b128 v[194:197], v187 offset:2048
	ds_read_b128 v[198:201], v187 offset:3072
	ds_read_b128 v[202:205], v187 offset:4096
	ds_read_b128 v[206:209], v187 offset:5120
	ds_read_b128 v[210:213], v187 offset:6144
	ds_read_b128 v[214:217], v187 offset:7168
	global_load_lds_dwordx4 v142, s[46:47]
	s_add_i32 m0, s61, 0xe000
	s_nop 0
	global_load_lds_dwordx4 v144, s[46:47]
	s_waitcnt vmcnt(8)
	s_waitcnt lgkmcnt(0)
	s_barrier
	v_mfma_f32_16x16x32_bf16 v[124:127], v[150:153], v[182:185], v[124:127]
	v_mfma_f32_16x16x32_bf16 v[120:123], v[158:161], v[182:185], v[120:123]
	v_mfma_f32_16x16x32_bf16 v[116:119], v[150:153], v[194:197], v[116:119]
	v_mfma_f32_16x16x32_bf16 v[112:115], v[158:161], v[194:197], v[112:115]
	v_mfma_f32_16x16x32_bf16 v[108:111], v[150:153], v[202:205], v[108:111]
	v_mfma_f32_16x16x32_bf16 v[104:107], v[158:161], v[202:205], v[104:107]
	v_mfma_f32_16x16x32_bf16 v[100:103], v[150:153], v[210:213], v[100:103]
	v_mfma_f32_16x16x32_bf16 v[96:99], v[158:161], v[210:213], v[96:99]
	v_mfma_f32_16x16x32_bf16 v[124:127], v[154:157], v[190:193], v[124:127]
	v_mfma_f32_16x16x32_bf16 v[120:123], v[162:165], v[190:193], v[120:123]
	v_mfma_f32_16x16x32_bf16 v[116:119], v[154:157], v[198:201], v[116:119]
	v_mfma_f32_16x16x32_bf16 v[112:115], v[162:165], v[198:201], v[112:115]
	v_mfma_f32_16x16x32_bf16 v[108:111], v[154:157], v[206:209], v[108:111]
	v_mfma_f32_16x16x32_bf16 v[104:107], v[162:165], v[206:209], v[104:107]
	v_mfma_f32_16x16x32_bf16 v[100:103], v[154:157], v[214:217], v[100:103]
	v_mfma_f32_16x16x32_bf16 v[96:99], v[162:165], v[214:217], v[96:99]
	v_mfma_f32_16x16x32_bf16 v[92:95], v[166:169], v[182:185], v[92:95]
	v_mfma_f32_16x16x32_bf16 v[88:91], v[174:177], v[182:185], v[88:91]
	v_mfma_f32_16x16x32_bf16 v[84:87], v[166:169], v[194:197], v[84:87]
	v_mfma_f32_16x16x32_bf16 v[80:83], v[174:177], v[194:197], v[80:83]
	v_mfma_f32_16x16x32_bf16 v[76:79], v[166:169], v[202:205], v[76:79]
	v_mfma_f32_16x16x32_bf16 v[72:75], v[174:177], v[202:205], v[72:75]
	v_mfma_f32_16x16x32_bf16 v[68:71], v[166:169], v[210:213], v[68:71]
	v_mfma_f32_16x16x32_bf16 v[64:67], v[174:177], v[210:213], v[64:67]
	v_mfma_f32_16x16x32_bf16 v[92:95], v[170:173], v[190:193], v[92:95]
	v_mfma_f32_16x16x32_bf16 v[88:91], v[178:181], v[190:193], v[88:91]
	v_mfma_f32_16x16x32_bf16 v[84:87], v[170:173], v[198:201], v[84:87]
	v_mfma_f32_16x16x32_bf16 v[80:83], v[178:181], v[198:201], v[80:83]
	v_mfma_f32_16x16x32_bf16 v[76:79], v[170:173], v[206:209], v[76:79]
	v_mfma_f32_16x16x32_bf16 v[72:75], v[178:181], v[206:209], v[72:75]
	v_mfma_f32_16x16x32_bf16 v[68:71], v[170:173], v[214:217], v[68:71]
	v_mfma_f32_16x16x32_bf16 v[64:67], v[178:181], v[214:217], v[64:67]
	s_barrier
	s_add_u32 s92, s54, s14
	s_addc_u32 s93, s55, s15
	s_add_u32 s94, s56, s14
	s_addc_u32 s95, s57, s15
	s_add_i32 s83, s67, s60
	s_mov_b32 m0, s83
	ds_read_b128 v[182:185], v187 offset:16384
	ds_read_b128 v[190:193], v187 offset:17408
	ds_read_b128 v[194:197], v187 offset:18432
	ds_read_b128 v[198:201], v187 offset:19456
	ds_read_b128 v[202:205], v187 offset:20480
	ds_read_b128 v[206:209], v187 offset:21504
	ds_read_b128 v[210:213], v187 offset:22528
	ds_read_b128 v[214:217], v187 offset:23552
	global_load_lds_dwordx4 v130, s[54:55]
	s_add_i32 m0, s83, 0x2000
	s_add_u32 s86, s54, 0x80000
	s_addc_u32 s87, s55, 0
	s_add_i32 s83, s68, s60
	global_load_lds_dwordx4 v134, s[54:55]
	s_mov_b32 m0, s83
	s_nop 0
	global_load_lds_dwordx4 v130, s[86:87]
	s_add_i32 m0, s83, 0x2000
	s_nop 0
	global_load_lds_dwordx4 v134, s[86:87]
	s_mov_b32 m0, s61
	s_nop 0
	global_load_lds_dwordx4 v128, s[56:57]
	s_mov_b32 m0, s62
	s_nop 0
	global_load_lds_dwordx4 v132, s[56:57]
	s_waitcnt vmcnt(8)
	s_waitcnt lgkmcnt(0)
	s_barrier
	v_mfma_f32_16x16x32_bf16 v[60:63], v[150:153], v[182:185], v[60:63]
	v_mfma_f32_16x16x32_bf16 v[56:59], v[158:161], v[182:185], v[56:59]
	v_mfma_f32_16x16x32_bf16 v[52:55], v[150:153], v[194:197], v[52:55]
	v_mfma_f32_16x16x32_bf16 v[48:51], v[158:161], v[194:197], v[48:51]
	v_mfma_f32_16x16x32_bf16 v[44:47], v[150:153], v[202:205], v[44:47]
	v_mfma_f32_16x16x32_bf16 v[40:43], v[158:161], v[202:205], v[40:43]
	v_mfma_f32_16x16x32_bf16 v[36:39], v[150:153], v[210:213], v[36:39]
	v_mfma_f32_16x16x32_bf16 v[32:35], v[158:161], v[210:213], v[32:35]
	v_mfma_f32_16x16x32_bf16 v[60:63], v[154:157], v[190:193], v[60:63]
	v_mfma_f32_16x16x32_bf16 v[56:59], v[162:165], v[190:193], v[56:59]
	v_mfma_f32_16x16x32_bf16 v[52:55], v[154:157], v[198:201], v[52:55]
	v_mfma_f32_16x16x32_bf16 v[48:51], v[162:165], v[198:201], v[48:51]
	v_mfma_f32_16x16x32_bf16 v[44:47], v[154:157], v[206:209], v[44:47]
	v_mfma_f32_16x16x32_bf16 v[40:43], v[162:165], v[206:209], v[40:43]
	v_mfma_f32_16x16x32_bf16 v[36:39], v[154:157], v[214:217], v[36:39]
	v_mfma_f32_16x16x32_bf16 v[32:35], v[162:165], v[214:217], v[32:35]
	v_mfma_f32_16x16x32_bf16 v[28:31], v[166:169], v[182:185], v[28:31]
	v_mfma_f32_16x16x32_bf16 v[24:27], v[174:177], v[182:185], v[24:27]
	v_mfma_f32_16x16x32_bf16 v[20:23], v[166:169], v[194:197], v[20:23]
	v_mfma_f32_16x16x32_bf16 v[16:19], v[174:177], v[194:197], v[16:19]
	v_mfma_f32_16x16x32_bf16 v[12:15], v[166:169], v[202:205], v[12:15]
	v_mfma_f32_16x16x32_bf16 v[8:11], v[174:177], v[202:205], v[8:11]
	v_mfma_f32_16x16x32_bf16 v[4:7], v[166:169], v[210:213], v[4:7]
	v_mfma_f32_16x16x32_bf16 v[0:3], v[174:177], v[210:213], v[0:3]
	v_mfma_f32_16x16x32_bf16 v[28:31], v[170:173], v[190:193], v[28:31]
	v_mfma_f32_16x16x32_bf16 v[24:27], v[178:181], v[190:193], v[24:27]
	v_mfma_f32_16x16x32_bf16 v[20:23], v[170:173], v[198:201], v[20:23]
	v_mfma_f32_16x16x32_bf16 v[16:19], v[178:181], v[198:201], v[16:19]
	v_mfma_f32_16x16x32_bf16 v[12:15], v[170:173], v[206:209], v[12:15]
	v_mfma_f32_16x16x32_bf16 v[8:11], v[178:181], v[206:209], v[8:11]
	v_mfma_f32_16x16x32_bf16 v[4:7], v[170:173], v[214:217], v[4:7]
	v_mfma_f32_16x16x32_bf16 v[0:3], v[178:181], v[214:217], v[0:3]
	s_barrier
; #define PG8_STAGE(bufoff, gbase, voff) do { _Pragma("unroll") for (int _i = 0; _i < 2; ++_i) \
;         __builtin_amdgcn_global_load_lds((const unsigned*)((const char*)(gbase) + (voff)[_i]), (PG8_LAS unsigned*)(lds + (bufoff) + ldsw + _i * 8192), 16, 0, 0); } while (0)
; #define PG8_LDA(dst, b, h) do { _Pragma("unroll") for (int m = 0; m < 4; ++m) _Pragma("unroll") for (int k = 0; k < 2; ++k) dst[m][k] = *(const PG8_LAS bf16x8*)(lds + PG8_SA(b, h) + aoff + m * 2048 + k * 1024); } while (0)
; #define PG8_LDB(dst, b, h) do { _Pragma("unroll") for (int n = 0; n < 2; ++n) _Pragma("unroll") for (int k = 0; k < 2; ++k) dst[n][k] = *(const PG8_LAS bf16x8*)(lds + PG8_SB(b, h) + boff + n * 2048 + k * 1024); } while (0)
; #define PG8_MMA(ai, bj, At, Bt) do { __builtin_amdgcn_s_setprio(1); _Pragma("unroll") for (int m = 0; m < 4; ++m) _Pragma("unroll") for (int n = 0; n < 2; ++n) _Pragma("unroll") for (int k = 0; k < 2; ++k) \
;         acc[ai][bj][m][n] = __builtin_amdgcn_mfma_f32_16x16x32_bf16(Bt[n][k], At[m][k], acc[ai][bj][m][n], 0, 0, 0); __builtin_amdgcn_s_setprio(0); } while (0)
; #define PG8_WAIT_V(n) asm volatile("s_waitcnt vmcnt(" #n ")" ::: "memory")
; #define PG8_WAIT_L(n) asm volatile("s_waitcnt lgkmcnt(" #n ")" ::: "memory")
; #define PG8_BAR __builtin_amdgcn_s_barrier()
; #define PG8_SCHED __builtin_amdgcn_sched_barrier(0)
; template <class Epi, class Sched, bool ALIGN_EPI = false, bool SP2 = false>
; __device__ __forceinline__ void gemm_phase(PG8_LAS unsigned char* lds, const Gemm g, const Sched& S, const Epi& E) {
;     ...
;             PG8_LDB(B0, 1, 0); PG8_LDB(B1, 1, 1); PG8_SCHED; PG8_LDA(At, 1, 0); PG8_STAGE(PG8_SA(0, 1), a2 + hstep, voffA);
;             PG8_WAIT_V(8); PG8_WAIT_L(0); PG8_BAR; PG8_MMA(0, 0, At, B0); PG8_MMA(0, 1, At, B1); PG8_BAR; PG8_SCHED;
;             PG8_LDA(At, 1, 1); PG8_STAGE(PG8_SB(1, 0), b3, voffB); PG8_STAGE(PG8_SB(1, 1), b3 + hstep, voffB); PG8_STAGE(PG8_SA(1, 0), a3, voffA);
;             PG8_WAIT_V(8); PG8_WAIT_L(0); PG8_BAR; PG8_MMA(1, 0, At, B0); PG8_MMA(1, 1, At, B1); PG8_BAR; PG8_SCHED;
	s_add_i32 s83, 0, 0x18000
	s_add_i32 s86, 0, 0x1c000
	v_add_u32_e32 v162, s83, v186
	v_add_u32_e32 v178, s86, v186
	ds_read_b128 v[150:153], v162
	ds_read_b128 v[154:157], v162 offset:1024
	ds_read_b128 v[158:161], v162 offset:2048
	ds_read_b128 v[162:165], v162 offset:3072
	ds_read_b128 v[166:169], v178
	ds_read_b128 v[170:173], v178 offset:1024
	ds_read_b128 v[174:177], v178 offset:2048
	ds_read_b128 v[178:181], v178 offset:3072
	s_add_u32 s56, s56, 0x80000
	s_addc_u32 s57, s57, 0
	s_mov_b32 m0, s63
	ds_read_b128 v[182:185], v187 offset:32768
	ds_read_b128 v[190:193], v187 offset:33792
	ds_read_b128 v[194:197], v187 offset:34816
	ds_read_b128 v[198:201], v187 offset:35840
	ds_read_b128 v[202:205], v187 offset:36864
	ds_read_b128 v[206:209], v187 offset:37888
	ds_read_b128 v[210:213], v187 offset:38912
	ds_read_b128 v[214:217], v187 offset:39936
	global_load_lds_dwordx4 v128, s[56:57]
	s_mov_b32 m0, s64
	s_nop 0
	global_load_lds_dwordx4 v132, s[56:57]
	s_waitcnt vmcnt(8)
	s_waitcnt lgkmcnt(0)
	s_barrier
	v_mfma_f32_16x16x32_bf16 v[124:127], v[150:153], v[182:185], v[124:127]
	v_mfma_f32_16x16x32_bf16 v[120:123], v[158:161], v[182:185], v[120:123]
	v_mfma_f32_16x16x32_bf16 v[116:119], v[150:153], v[194:197], v[116:119]
	v_mfma_f32_16x16x32_bf16 v[112:115], v[158:161], v[194:197], v[112:115]
	v_mfma_f32_16x16x32_bf16 v[108:111], v[150:153], v[202:205], v[108:111]
	v_mfma_f32_16x16x32_bf16 v[104:107], v[158:161], v[202:205], v[104:107]
	v_mfma_f32_16x16x32_bf16 v[100:103], v[150:153], v[210:213], v[100:103]
	v_mfma_f32_16x16x32_bf16 v[96:99], v[158:161], v[210:213], v[96:99]
	v_mfma_f32_16x16x32_bf16 v[124:127], v[154:157], v[190:193], v[124:127]
	v_mfma_f32_16x16x32_bf16 v[120:123], v[162:165], v[190:193], v[120:123]
	v_mfma_f32_16x16x32_bf16 v[116:119], v[154:157], v[198:201], v[116:119]
	v_mfma_f32_16x16x32_bf16 v[112:115], v[162:165], v[198:201], v[112:115]
	v_mfma_f32_16x16x32_bf16 v[108:111], v[154:157], v[206:209], v[108:111]
	v_mfma_f32_16x16x32_bf16 v[104:107], v[162:165], v[206:209], v[104:107]
	v_mfma_f32_16x16x32_bf16 v[100:103], v[154:157], v[214:217], v[100:103]
	v_mfma_f32_16x16x32_bf16 v[96:99], v[162:165], v[214:217], v[96:99]
	v_mfma_f32_16x16x32_bf16 v[92:95], v[166:169], v[182:185], v[92:95]
	v_mfma_f32_16x16x32_bf16 v[88:91], v[174:177], v[182:185], v[88:91]
	v_mfma_f32_16x16x32_bf16 v[84:87], v[166:169], v[194:197], v[84:87]
	v_mfma_f32_16x16x32_bf16 v[80:83], v[174:177], v[194:197], v[80:83]
	v_mfma_f32_16x16x32_bf16 v[76:79], v[166:169], v[202:205], v[76:79]
	v_mfma_f32_16x16x32_bf16 v[72:75], v[174:177], v[202:205], v[72:75]
	v_mfma_f32_16x16x32_bf16 v[68:71], v[166:169], v[210:213], v[68:71]
	v_mfma_f32_16x16x32_bf16 v[64:67], v[174:177], v[210:213], v[64:67]
	v_mfma_f32_16x16x32_bf16 v[92:95], v[170:173], v[190:193], v[92:95]
	v_mfma_f32_16x16x32_bf16 v[88:91], v[178:181], v[190:193], v[88:91]
	v_mfma_f32_16x16x32_bf16 v[84:87], v[170:173], v[198:201], v[84:87]
	v_mfma_f32_16x16x32_bf16 v[80:83], v[178:181], v[198:201], v[80:83]
	v_mfma_f32_16x16x32_bf16 v[76:79], v[170:173], v[206:209], v[76:79]
	v_mfma_f32_16x16x32_bf16 v[72:75], v[178:181], v[206:209], v[72:75]
	v_mfma_f32_16x16x32_bf16 v[68:71], v[170:173], v[214:217], v[68:71]
	v_mfma_f32_16x16x32_bf16 v[64:67], v[178:181], v[214:217], v[64:67]
	s_barrier
	s_add_i32 s56, s83, s60
	s_mov_b32 m0, s56
	ds_read_b128 v[182:185], v187 offset:49152
	ds_read_b128 v[190:193], v187 offset:50176
	ds_read_b128 v[194:197], v187 offset:51200
	ds_read_b128 v[198:201], v187 offset:52224
	ds_read_b128 v[202:205], v187 offset:53248
	ds_read_b128 v[206:209], v187 offset:54272
	ds_read_b128 v[210:213], v187 offset:55296
	ds_read_b128 v[214:217], v187 offset:56320
	global_load_lds_dwordx4 v130, s[92:93]
	s_add_i32 m0, s56, 0x2000
	s_add_u32 s54, s54, 0x80080
	s_addc_u32 s55, s55, 0
	s_add_i32 s56, s86, s60
	global_load_lds_dwordx4 v134, s[92:93]
	s_mov_b32 m0, s56
	s_nop 0
	global_load_lds_dwordx4 v130, s[54:55]
	s_add_i32 m0, s56, 0x2000
	s_nop 0
	global_load_lds_dwordx4 v134, s[54:55]
	s_mov_b32 m0, s65
	s_nop 0
	global_load_lds_dwordx4 v128, s[94:95]
	s_mov_b32 m0, s66
	s_nop 0
	global_load_lds_dwordx4 v132, s[94:95]
	s_waitcnt vmcnt(8)
	s_waitcnt lgkmcnt(0)
	s_barrier
	v_mfma_f32_16x16x32_bf16 v[60:63], v[150:153], v[182:185], v[60:63]
	v_mfma_f32_16x16x32_bf16 v[56:59], v[158:161], v[182:185], v[56:59]
	v_mfma_f32_16x16x32_bf16 v[52:55], v[150:153], v[194:197], v[52:55]
	v_mfma_f32_16x16x32_bf16 v[48:51], v[158:161], v[194:197], v[48:51]
	v_mfma_f32_16x16x32_bf16 v[44:47], v[150:153], v[202:205], v[44:47]
	v_mfma_f32_16x16x32_bf16 v[40:43], v[158:161], v[202:205], v[40:43]
	v_mfma_f32_16x16x32_bf16 v[36:39], v[150:153], v[210:213], v[36:39]
	v_mfma_f32_16x16x32_bf16 v[32:35], v[158:161], v[210:213], v[32:35]
	v_mfma_f32_16x16x32_bf16 v[60:63], v[154:157], v[190:193], v[60:63]
	v_mfma_f32_16x16x32_bf16 v[56:59], v[162:165], v[190:193], v[56:59]
	v_mfma_f32_16x16x32_bf16 v[52:55], v[154:157], v[198:201], v[52:55]
	v_mfma_f32_16x16x32_bf16 v[48:51], v[162:165], v[198:201], v[48:51]
	v_mfma_f32_16x16x32_bf16 v[44:47], v[154:157], v[206:209], v[44:47]
	v_mfma_f32_16x16x32_bf16 v[40:43], v[162:165], v[206:209], v[40:43]
	v_mfma_f32_16x16x32_bf16 v[36:39], v[154:157], v[214:217], v[36:39]
	v_mfma_f32_16x16x32_bf16 v[32:35], v[162:165], v[214:217], v[32:35]
	v_mfma_f32_16x16x32_bf16 v[28:31], v[166:169], v[182:185], v[28:31]
	v_mfma_f32_16x16x32_bf16 v[24:27], v[174:177], v[182:185], v[24:27]
	v_mfma_f32_16x16x32_bf16 v[20:23], v[166:169], v[194:197], v[20:23]
	v_mfma_f32_16x16x32_bf16 v[16:19], v[174:177], v[194:197], v[16:19]
	v_mfma_f32_16x16x32_bf16 v[12:15], v[166:169], v[202:205], v[12:15]
	v_mfma_f32_16x16x32_bf16 v[8:11], v[174:177], v[202:205], v[8:11]
	v_mfma_f32_16x16x32_bf16 v[4:7], v[166:169], v[210:213], v[4:7]
	v_mfma_f32_16x16x32_bf16 v[0:3], v[174:177], v[210:213], v[0:3]
	v_mfma_f32_16x16x32_bf16 v[28:31], v[170:173], v[190:193], v[28:31]
	v_mfma_f32_16x16x32_bf16 v[24:27], v[178:181], v[190:193], v[24:27]
	v_mfma_f32_16x16x32_bf16 v[20:23], v[170:173], v[198:201], v[20:23]
	v_mfma_f32_16x16x32_bf16 v[16:19], v[178:181], v[198:201], v[16:19]
	v_mfma_f32_16x16x32_bf16 v[12:15], v[170:173], v[206:209], v[12:15]
	v_mfma_f32_16x16x32_bf16 v[8:11], v[178:181], v[206:209], v[8:11]
	v_mfma_f32_16x16x32_bf16 v[4:7], v[170:173], v[214:217], v[4:7]
	v_mfma_f32_16x16x32_bf16 v[0:3], v[178:181], v[214:217], v[0:3]
	s_barrier
	s_add_i32 s82, s82, 2
	s_add_u32 s46, s46, 0x100
	s_addc_u32 s47, s47, 0
	s_add_u32 s80, s80, 0x100
	s_addc_u32 s81, s81, 0
	s_cmp_gt_u32 s82, 13
	s_cbranch_scc0 .LBB0_795
	s_and_b64 vcc, exec, s[16:17]
	s_cbranch_vccz .LBB0_798
	s_barrier

;     __host__ __device__ bool next(int i, Unit& u) const { const long L = (long)i * G + c; if (L >= nwg) return false; return unit_of((int)L, u); }
;     __host__ __device__ bool next(int i, Unit& u) const { const int L = i == 0 ? l0 : (i == 1 ? l1 : (i == 2 ? l2 : -1)); if (L < 0 || L >= s.nwg) return false; return s.unit_of(L, u); }
;     __host__ __device__ bool next(int i, Unit& u) const { const bool ok = s.next(i >> 1, u); u.kh = i & 1; return ok; }
; #define PG8_STAGE(bufoff, gbase, voff) do { _Pragma("unroll") for (int _i = 0; _i < 2; ++_i) \
;         __builtin_amdgcn_global_load_lds((const unsigned*)((const char*)(gbase) + (voff)[_i]), (PG8_LAS unsigned*)(lds + (bufoff) + ldsw + _i * 8192), 16, 0, 0); } while (0)
; #define PG8_LDA(dst, b, h) do { _Pragma("unroll") for (int m = 0; m < 4; ++m) _Pragma("unroll") for (int k = 0; k < 2; ++k) dst[m][k] = *(const PG8_LAS bf16x8*)(lds + PG8_SA(b, h) + aoff + m * 2048 + k * 1024); } while (0)
; template <class Epi, class Sched, bool ALIGN_EPI = false, bool SP2 = false>
; __device__ __forceinline__ void gemm_phase(PG8_LAS unsigned char* lds, const Gemm g, const Sched& S, const Epi& E) {
;     ...
;         const bool has_next = S.next(ui + 1, nxt);
;         const char* nA = has_next ? (const char*)g.A + (size_t)nxt.pm * tstep + nxt.kh * khb : cA; const char* nB = has_next ? (const char*)g.Bt + (size_t)nxt.pn * tstep + nxt.kh * khb : cB;
;         for (int t = 0; t < nt; t += 2) {
;             const bool last = (t == nt - 2);
;             const char* a1 = cA + (size_t)(t + 1) * kstep;
;             const char* a2 = last ? nA : cA + (size_t)(t + 2) * kstep; const char* b2 = last ? nB : cB + (size_t)(t + 2) * kstep;
;             const char* a3 = a2 + kstep; const char* b3 = b2 + kstep;
;             if (last && has_next) S.a_ready(nxt);
;             if constexpr (SP2) {
;             PG8_LDB(B0, 0, 0); PG8_LDB(B1, 0, 1); PG8_SCHED; PG8_LDA(At, 0, 0); PG8_STAGE(PG8_SA(1, 1), a1 + hstep, voffA);
;             PG8_WAIT_V(8); PG8_WAIT_L(0); PG8_BAR; PG8_MMA(0, 0, At, B0); PG8_MMA(0, 1, At, B1); PG8_BAR; PG8_SCHED;
;             PG8_LDA(At, 0, 1); PG8_STAGE(PG8_SB(0, 0), b2, voffB); PG8_STAGE(PG8_SB(0, 1), b2 + hstep, voffB); PG8_STAGE(PG8_SA(0, 0), a2, voffA);
;             PG8_WAIT_V(8); PG8_WAIT_L(0); PG8_BAR; PG8_MMA(1, 0, At, B0); PG8_MMA(1, 1, At, B1); PG8_BAR; PG8_SCHED;
.LBB0_881:
	s_ashr_i32 s23, s22, 31
	s_lshl_b64 s[24:25], s[22:23], 19
	s_add_u32 s24, s38, s24
	s_addc_u32 s25, s39, s25
	s_and_b64 s[26:27], s[4:5], exec
	s_cselect_b32 s23, s25, s31
	s_cselect_b32 s29, s24, s30
	s_ashr_i32 s21, s20, 31
	s_lshl_b64 s[26:27], s[20:21], 19
	s_add_u32 s26, s40, s26
	s_addc_u32 s27, s41, s27
	s_and_b64 s[36:37], s[4:5], exec
	s_cselect_b32 s21, s27, s35
	s_cselect_b32 s58, s26, s34
	s_add_u32 s30, s30, 0x40080
	s_addc_u32 s31, s31, 0
	s_add_u32 s59, s34, 0x100
	s_addc_u32 s60, s35, 0
	s_mov_b32 s61, -2
	s_waitcnt lgkmcnt(0)
	ds_read_b128 v[128:131], v173
	ds_read_b128 v[132:135], v173 offset:1024
	ds_read_b128 v[136:139], v173 offset:2048
	ds_read_b128 v[140:143], v173 offset:3072
	ds_read_b128 v[164:167], v174
	ds_read_b128 v[168:171], v174 offset:1024
	ds_read_b128 v[178:181], v174 offset:2048
	ds_read_b128 v[182:185], v174 offset:3072
	s_add_u32 s34, s30, 0xfffc0080
	s_addc_u32 s35, s31, -1
	s_cmp_eq_u32 s61, 12
	s_cselect_b32 s37, s23, s35
	s_cselect_b32 s36, s29, s34
	s_cselect_b32 s35, s21, s60
	s_cselect_b32 s34, s58, s59
	s_add_i32 m0, s43, 0xc000
	ds_read_b128 v[190:193], v175
	ds_read_b128 v[194:197], v175 offset:1024
	ds_read_b128 v[198:201], v175 offset:2048
	ds_read_b128 v[202:205], v175 offset:3072
	ds_read_b128 v[206:209], v175 offset:4096
	ds_read_b128 v[210:213], v175 offset:5120
	ds_read_b128 v[214:217], v175 offset:6144
	ds_read_b128 v[218:221], v175 offset:7168
	global_load_lds_dwordx4 v156, s[30:31]
	s_add_i32 m0, s43, 0xe000
	s_nop 0
	global_load_lds_dwordx4 v158, s[30:31]
	s_waitcnt vmcnt(8)
	s_waitcnt lgkmcnt(0)
	s_barrier
	v_mfma_f32_16x16x32_bf16 v[124:127], v[128:131], v[190:193], 0
	v_mfma_f32_16x16x32_bf16 v[120:123], v[136:139], v[190:193], 0
	v_mfma_f32_16x16x32_bf16 v[108:111], v[128:131], v[198:201], 0
	v_mfma_f32_16x16x32_bf16 v[104:107], v[136:139], v[198:201], 0
	v_mfma_f32_16x16x32_bf16 v[92:95], v[128:131], v[206:209], 0
	v_mfma_f32_16x16x32_bf16 v[88:91], v[136:139], v[206:209], 0
	v_mfma_f32_16x16x32_bf16 v[76:79], v[128:131], v[214:217], 0
	v_mfma_f32_16x16x32_bf16 v[72:75], v[136:139], v[214:217], 0
	v_mfma_f32_16x16x32_bf16 v[124:127], v[132:135], v[194:197], v[124:127]
	v_mfma_f32_16x16x32_bf16 v[120:123], v[140:143], v[194:197], v[120:123]
	v_mfma_f32_16x16x32_bf16 v[108:111], v[132:135], v[202:205], v[108:111]
	v_mfma_f32_16x16x32_bf16 v[104:107], v[140:143], v[202:205], v[104:107]
	v_mfma_f32_16x16x32_bf16 v[92:95], v[132:135], v[210:213], v[92:95]
	v_mfma_f32_16x16x32_bf16 v[88:91], v[140:143], v[210:213], v[88:91]
	v_mfma_f32_16x16x32_bf16 v[76:79], v[132:135], v[218:221], v[76:79]
	v_mfma_f32_16x16x32_bf16 v[72:75], v[140:143], v[218:221], v[72:75]
	v_mfma_f32_16x16x32_bf16 v[116:119], v[164:167], v[190:193], 0
	v_mfma_f32_16x16x32_bf16 v[112:115], v[178:181], v[190:193], 0
	v_mfma_f32_16x16x32_bf16 v[100:103], v[164:167], v[198:201], 0
	v_mfma_f32_16x16x32_bf16 v[96:99], v[178:181], v[198:201], 0
	v_mfma_f32_16x16x32_bf16 v[84:87], v[164:167], v[206:209], 0
	v_mfma_f32_16x16x32_bf16 v[80:83], v[178:181], v[206:209], 0
	v_mfma_f32_16x16x32_bf16 v[68:71], v[164:167], v[214:217], 0
	v_mfma_f32_16x16x32_bf16 v[64:67], v[178:181], v[214:217], 0
	v_mfma_f32_16x16x32_bf16 v[116:119], v[168:171], v[194:197], v[116:119]
	v_mfma_f32_16x16x32_bf16 v[112:115], v[182:185], v[194:197], v[112:115]
	v_mfma_f32_16x16x32_bf16 v[100:103], v[168:171], v[202:205], v[100:103]
	v_mfma_f32_16x16x32_bf16 v[96:99], v[182:185], v[202:205], v[96:99]
	v_mfma_f32_16x16x32_bf16 v[84:87], v[168:171], v[210:213], v[84:87]
	v_mfma_f32_16x16x32_bf16 v[80:83], v[182:185], v[210:213], v[80:83]
	v_mfma_f32_16x16x32_bf16 v[68:71], v[168:171], v[218:221], v[68:71]
	v_mfma_f32_16x16x32_bf16 v[64:67], v[182:185], v[218:221], v[64:67]
	s_barrier
	s_add_u32 s92, s34, s16
	s_addc_u32 s93, s35, s17
	s_add_u32 s94, s36, s16
	s_addc_u32 s95, s37, s17
	s_add_i32 s62, s55, s42
	s_mov_b32 m0, s62
	ds_read_b128 v[190:193], v175 offset:16384
	ds_read_b128 v[194:197], v175 offset:17408
	ds_read_b128 v[198:201], v175 offset:18432
	ds_read_b128 v[202:205], v175 offset:19456
	ds_read_b128 v[206:209], v175 offset:20480
	ds_read_b128 v[210:213], v175 offset:21504
	ds_read_b128 v[214:217], v175 offset:22528
	ds_read_b128 v[218:221], v175 offset:23552
	global_load_lds_dwordx4 v146, s[34:35]
	s_add_i32 m0, s62, 0x2000
	s_add_u32 s62, s34, 0x40000
	s_addc_u32 s63, s35, 0
	s_add_i32 s64, s56, s42
	global_load_lds_dwordx4 v150, s[34:35]
	s_mov_b32 m0, s64
	s_nop 0
	global_load_lds_dwordx4 v146, s[62:63]
	s_add_i32 m0, s64, 0x2000
	s_nop 0
	global_load_lds_dwordx4 v150, s[62:63]
	s_mov_b32 m0, s43
	s_nop 0
	global_load_lds_dwordx4 v144, s[36:37]
	s_mov_b32 m0, s44
	s_nop 0
	global_load_lds_dwordx4 v148, s[36:37]
	s_waitcnt vmcnt(8)
	s_waitcnt lgkmcnt(0)
	s_barrier
	v_mfma_f32_16x16x32_bf16 v[60:63], v[128:131], v[190:193], 0
	v_mfma_f32_16x16x32_bf16 v[56:59], v[136:139], v[190:193], 0
	v_mfma_f32_16x16x32_bf16 v[44:47], v[128:131], v[198:201], 0
	v_mfma_f32_16x16x32_bf16 v[40:43], v[136:139], v[198:201], 0
	v_mfma_f32_16x16x32_bf16 v[28:31], v[128:131], v[206:209], 0
	v_mfma_f32_16x16x32_bf16 v[24:27], v[136:139], v[206:209], 0
	v_mfma_f32_16x16x32_bf16 v[12:15], v[128:131], v[214:217], 0
	v_mfma_f32_16x16x32_bf16 v[8:11], v[136:139], v[214:217], 0
	v_mfma_f32_16x16x32_bf16 v[60:63], v[132:135], v[194:197], v[60:63]
	v_mfma_f32_16x16x32_bf16 v[56:59], v[140:143], v[194:197], v[56:59]
	v_mfma_f32_16x16x32_bf16 v[44:47], v[132:135], v[202:205], v[44:47]
	v_mfma_f32_16x16x32_bf16 v[40:43], v[140:143], v[202:205], v[40:43]
	v_mfma_f32_16x16x32_bf16 v[28:31], v[132:135], v[210:213], v[28:31]
	v_mfma_f32_16x16x32_bf16 v[24:27], v[140:143], v[210:213], v[24:27]
	v_mfma_f32_16x16x32_bf16 v[12:15], v[132:135], v[218:221], v[12:15]
	v_mfma_f32_16x16x32_bf16 v[8:11], v[140:143], v[218:221], v[8:11]
	v_mfma_f32_16x16x32_bf16 v[52:55], v[164:167], v[190:193], 0
	v_mfma_f32_16x16x32_bf16 v[48:51], v[178:181], v[190:193], 0
	v_mfma_f32_16x16x32_bf16 v[36:39], v[164:167], v[198:201], 0
	v_mfma_f32_16x16x32_bf16 v[32:35], v[178:181], v[198:201], 0
	v_mfma_f32_16x16x32_bf16 v[20:23], v[164:167], v[206:209], 0
	v_mfma_f32_16x16x32_bf16 v[16:19], v[178:181], v[206:209], 0
	v_mfma_f32_16x16x32_bf16 v[4:7], v[164:167], v[214:217], 0
	v_mfma_f32_16x16x32_bf16 v[0:3], v[178:181], v[214:217], 0
	v_mfma_f32_16x16x32_bf16 v[52:55], v[168:171], v[194:197], v[52:55]
	v_mfma_f32_16x16x32_bf16 v[48:51], v[182:185], v[194:197], v[48:51]
	v_mfma_f32_16x16x32_bf16 v[36:39], v[168:171], v[202:205], v[36:39]
	v_mfma_f32_16x16x32_bf16 v[32:35], v[182:185], v[202:205], v[32:35]
	v_mfma_f32_16x16x32_bf16 v[20:23], v[168:171], v[210:213], v[20:23]
	v_mfma_f32_16x16x32_bf16 v[16:19], v[182:185], v[210:213], v[16:19]
	v_mfma_f32_16x16x32_bf16 v[4:7], v[168:171], v[218:221], v[4:7]
	v_mfma_f32_16x16x32_bf16 v[0:3], v[182:185], v[218:221], v[0:3]
	s_barrier
	s_branch .Lmy_peel_882_mid
; #define PG8_STAGE(bufoff, gbase, voff) do { _Pragma("unroll") for (int _i = 0; _i < 2; ++_i) \
;         __builtin_amdgcn_global_load_lds((const unsigned*)((const char*)(gbase) + (voff)[_i]), (PG8_LAS unsigned*)(lds + (bufoff) + ldsw + _i * 8192), 16, 0, 0); } while (0)
; #define PG8_LDA(dst, b, h) do { _Pragma("unroll") for (int m = 0; m < 4; ++m) _Pragma("unroll") for (int k = 0; k < 2; ++k) dst[m][k] = *(const PG8_LAS bf16x8*)(lds + PG8_SA(b, h) + aoff + m * 2048 + k * 1024); } while (0)
; #define PG8_LDB(dst, b, h) do { _Pragma("unroll") for (int n = 0; n < 2; ++n) _Pragma("unroll") for (int k = 0; k < 2; ++k) dst[n][k] = *(const PG8_LAS bf16x8*)(lds + PG8_SB(b, h) + boff + n * 2048 + k * 1024); } while (0)
; #define PG8_MMA(ai, bj, At, Bt) do { __builtin_amdgcn_s_setprio(1); _Pragma("unroll") for (int m = 0; m < 4; ++m) _Pragma("unroll") for (int n = 0; n < 2; ++n) _Pragma("unroll") for (int k = 0; k < 2; ++k) \
;         acc[ai][bj][m][n] = __builtin_amdgcn_mfma_f32_16x16x32_bf16(Bt[n][k], At[m][k], acc[ai][bj][m][n], 0, 0, 0); __builtin_amdgcn_s_setprio(0); } while (0)
; #define PG8_WAIT_V(n) asm volatile("s_waitcnt vmcnt(" #n ")" ::: "memory")
; #define PG8_WAIT_L(n) asm volatile("s_waitcnt lgkmcnt(" #n ")" ::: "memory")
; template <class Epi, class Sched, bool ALIGN_EPI = false, bool SP2 = false>
; __device__ __forceinline__ void gemm_phase(PG8_LAS unsigned char* lds, const Gemm g, const Sched& S, const Epi& E) {
;     ...
;             const bool last = (t == nt - 2);
;             const char* a1 = cA + (size_t)(t + 1) * kstep;
;             const char* a2 = last ? nA : cA + (size_t)(t + 2) * kstep; const char* b2 = last ? nB : cB + (size_t)(t + 2) * kstep;
;             const char* a3 = a2 + kstep; const char* b3 = b2 + kstep;
;             if (last && has_next) S.a_ready(nxt);
;             if constexpr (SP2) {
;             PG8_LDB(B0, 0, 0); PG8_LDB(B1, 0, 1); PG8_SCHED; PG8_LDA(At, 0, 0); PG8_STAGE(PG8_SA(1, 1), a1 + hstep, voffA);
;             PG8_WAIT_V(8); PG8_WAIT_L(0); PG8_BAR; PG8_MMA(0, 0, At, B0); PG8_MMA(0, 1, At, B1); PG8_BAR; PG8_SCHED;
;             PG8_LDA(At, 0, 1); PG8_STAGE(PG8_SB(0, 0), b2, voffB); PG8_STAGE(PG8_SB(0, 1), b2 + hstep, voffB); PG8_STAGE(PG8_SA(0, 0), a2, voffA);
;             PG8_WAIT_V(8); PG8_WAIT_L(0); PG8_BAR; PG8_MMA(1, 0, At, B0); PG8_MMA(1, 1, At, B1); PG8_BAR; PG8_SCHED;
.LBB0_882:
	ds_read_b128 v[128:131], v173
	ds_read_b128 v[132:135], v173 offset:1024
	ds_read_b128 v[136:139], v173 offset:2048
	ds_read_b128 v[140:143], v173 offset:3072
	ds_read_b128 v[164:167], v174
	ds_read_b128 v[168:171], v174 offset:1024
	ds_read_b128 v[178:181], v174 offset:2048
	ds_read_b128 v[182:185], v174 offset:3072
	s_add_u32 s34, s30, 0xfffc0080
	s_addc_u32 s35, s31, -1
	s_cmp_eq_u32 s61, 12
	s_cselect_b32 s37, s23, s35
	s_cselect_b32 s36, s29, s34
	s_cselect_b32 s35, s21, s60
	s_cselect_b32 s34, s58, s59
	s_add_i32 m0, s43, 0xc000
	ds_read_b128 v[190:193], v175
	ds_read_b128 v[194:197], v175 offset:1024
	ds_read_b128 v[198:201], v175 offset:2048
	ds_read_b128 v[202:205], v175 offset:3072
	ds_read_b128 v[206:209], v175 offset:4096
	ds_read_b128 v[210:213], v175 offset:5120
	ds_read_b128 v[214:217], v175 offset:6144
	ds_read_b128 v[218:221], v175 offset:7168
	global_load_lds_dwordx4 v156, s[30:31]
	s_add_i32 m0, s43, 0xe000
	s_nop 0
	global_load_lds_dwordx4 v158, s[30:31]
	s_waitcnt vmcnt(8)
	s_waitcnt lgkmcnt(0)
	s_barrier
	v_mfma_f32_16x16x32_bf16 v[124:127], v[128:131], v[190:193], v[124:127]
	v_mfma_f32_16x16x32_bf16 v[120:123], v[136:139], v[190:193], v[120:123]
	v_mfma_f32_16x16x32_bf16 v[108:111], v[128:131], v[198:201], v[108:111]
	v_mfma_f32_16x16x32_bf16 v[104:107], v[136:139], v[198:201], v[104:107]
	v_mfma_f32_16x16x32_bf16 v[92:95], v[128:131], v[206:209], v[92:95]
	v_mfma_f32_16x16x32_bf16 v[88:91], v[136:139], v[206:209], v[88:91]
	v_mfma_f32_16x16x32_bf16 v[76:79], v[128:131], v[214:217], v[76:79]
	v_mfma_f32_16x16x32_bf16 v[72:75], v[136:139], v[214:217], v[72:75]
	v_mfma_f32_16x16x32_bf16 v[124:127], v[132:135], v[194:197], v[124:127]
	v_mfma_f32_16x16x32_bf16 v[120:123], v[140:143], v[194:197], v[120:123]
	v_mfma_f32_16x16x32_bf16 v[108:111], v[132:135], v[202:205], v[108:111]
	v_mfma_f32_16x16x32_bf16 v[104:107], v[140:143], v[202:205], v[104:107]
	v_mfma_f32_16x16x32_bf16 v[92:95], v[132:135], v[210:213], v[92:95]
	v_mfma_f32_16x16x32_bf16 v[88:91], v[140:143], v[210:213], v[88:91]
	v_mfma_f32_16x16x32_bf16 v[76:79], v[132:135], v[218:221], v[76:79]
	v_mfma_f32_16x16x32_bf16 v[72:75], v[140:143], v[218:221], v[72:75]
	v_mfma_f32_16x16x32_bf16 v[116:119], v[164:167], v[190:193], v[116:119]
	v_mfma_f32_16x16x32_bf16 v[112:115], v[178:181], v[190:193], v[112:115]
	v_mfma_f32_16x16x32_bf16 v[100:103], v[164:167], v[198:201], v[100:103]
	v_mfma_f32_16x16x32_bf16 v[96:99], v[178:181], v[198:201], v[96:99]
	v_mfma_f32_16x16x32_bf16 v[84:87], v[164:167], v[206:209], v[84:87]
	v_mfma_f32_16x16x32_bf16 v[80:83], v[178:181], v[206:209], v[80:83]
	v_mfma_f32_16x16x32_bf16 v[68:71], v[164:167], v[214:217], v[68:71]
	v_mfma_f32_16x16x32_bf16 v[64:67], v[178:181], v[214:217], v[64:67]
	v_mfma_f32_16x16x32_bf16 v[116:119], v[168:171], v[194:197], v[116:119]
	v_mfma_f32_16x16x32_bf16 v[112:115], v[182:185], v[194:197], v[112:115]
	v_mfma_f32_16x16x32_bf16 v[100:103], v[168:171], v[202:205], v[100:103]
	v_mfma_f32_16x16x32_bf16 v[96:99], v[182:185], v[202:205], v[96:99]
	v_mfma_f32_16x16x32_bf16 v[84:87], v[168:171], v[210:213], v[84:87]
	v_mfma_f32_16x16x32_bf16 v[80:83], v[182:185], v[210:213], v[80:83]
	v_mfma_f32_16x16x32_bf16 v[68:71], v[168:171], v[218:221], v[68:71]
	v_mfma_f32_16x16x32_bf16 v[64:67], v[182:185], v[218:221], v[64:67]
	s_barrier
	s_add_u32 s92, s34, s16
	s_addc_u32 s93, s35, s17
	s_add_u32 s94, s36, s16
	s_addc_u32 s95, s37, s17
	s_add_i32 s62, s55, s42
	s_mov_b32 m0, s62
	ds_read_b128 v[190:193], v175 offset:16384
	ds_read_b128 v[194:197], v175 offset:17408
	ds_read_b128 v[198:201], v175 offset:18432
	ds_read_b128 v[202:205], v175 offset:19456
	ds_read_b128 v[206:209], v175 offset:20480
	ds_read_b128 v[210:213], v175 offset:21504
	ds_read_b128 v[214:217], v175 offset:22528
	ds_read_b128 v[218:221], v175 offset:23552
	global_load_lds_dwordx4 v146, s[34:35]
	s_add_i32 m0, s62, 0x2000
	s_add_u32 s62, s34, 0x40000
	s_addc_u32 s63, s35, 0
	s_add_i32 s64, s56, s42
	global_load_lds_dwordx4 v150, s[34:35]
	s_mov_b32 m0, s64
	s_nop 0
	global_load_lds_dwordx4 v146, s[62:63]
	s_add_i32 m0, s64, 0x2000
	s_nop 0
	global_load_lds_dwordx4 v150, s[62:63]
	s_mov_b32 m0, s43
	s_nop 0
	global_load_lds_dwordx4 v144, s[36:37]
	s_mov_b32 m0, s44
	s_nop 0
	global_load_lds_dwordx4 v148, s[36:37]
	s_waitcnt vmcnt(8)
	s_waitcnt lgkmcnt(0)
	s_barrier
	v_mfma_f32_16x16x32_bf16 v[60:63], v[128:131], v[190:193], v[60:63]
	v_mfma_f32_16x16x32_bf16 v[56:59], v[136:139], v[190:193], v[56:59]
	v_mfma_f32_16x16x32_bf16 v[44:47], v[128:131], v[198:201], v[44:47]
	v_mfma_f32_16x16x32_bf16 v[40:43], v[136:139], v[198:201], v[40:43]
	v_mfma_f32_16x16x32_bf16 v[28:31], v[128:131], v[206:209], v[28:31]
	v_mfma_f32_16x16x32_bf16 v[24:27], v[136:139], v[206:209], v[24:27]
	v_mfma_f32_16x16x32_bf16 v[12:15], v[128:131], v[214:217], v[12:15]
	v_mfma_f32_16x16x32_bf16 v[8:11], v[136:139], v[214:217], v[8:11]
	v_mfma_f32_16x16x32_bf16 v[60:63], v[132:135], v[194:197], v[60:63]
	v_mfma_f32_16x16x32_bf16 v[56:59], v[140:143], v[194:197], v[56:59]
	v_mfma_f32_16x16x32_bf16 v[44:47], v[132:135], v[202:205], v[44:47]
	v_mfma_f32_16x16x32_bf16 v[40:43], v[140:143], v[202:205], v[40:43]
	v_mfma_f32_16x16x32_bf16 v[28:31], v[132:135], v[210:213], v[28:31]
	v_mfma_f32_16x16x32_bf16 v[24:27], v[140:143], v[210:213], v[24:27]
	v_mfma_f32_16x16x32_bf16 v[12:15], v[132:135], v[218:221], v[12:15]
	v_mfma_f32_16x16x32_bf16 v[8:11], v[140:143], v[218:221], v[8:11]
	v_mfma_f32_16x16x32_bf16 v[52:55], v[164:167], v[190:193], v[52:55]
	v_mfma_f32_16x16x32_bf16 v[48:51], v[178:181], v[190:193], v[48:51]
	v_mfma_f32_16x16x32_bf16 v[36:39], v[164:167], v[198:201], v[36:39]
	v_mfma_f32_16x16x32_bf16 v[32:35], v[178:181], v[198:201], v[32:35]
	v_mfma_f32_16x16x32_bf16 v[20:23], v[164:167], v[206:209], v[20:23]
	v_mfma_f32_16x16x32_bf16 v[16:19], v[178:181], v[206:209], v[16:19]
	v_mfma_f32_16x16x32_bf16 v[4:7], v[164:167], v[214:217], v[4:7]
	v_mfma_f32_16x16x32_bf16 v[0:3], v[178:181], v[214:217], v[0:3]
	v_mfma_f32_16x16x32_bf16 v[52:55], v[168:171], v[194:197], v[52:55]
	v_mfma_f32_16x16x32_bf16 v[48:51], v[182:185], v[194:197], v[48:51]
	v_mfma_f32_16x16x32_bf16 v[36:39], v[168:171], v[202:205], v[36:39]
	v_mfma_f32_16x16x32_bf16 v[32:35], v[182:185], v[202:205], v[32:35]
	v_mfma_f32_16x16x32_bf16 v[20:23], v[168:171], v[210:213], v[20:23]
	v_mfma_f32_16x16x32_bf16 v[16:19], v[182:185], v[210:213], v[16:19]
	v_mfma_f32_16x16x32_bf16 v[4:7], v[168:171], v[218:221], v[4:7]
	v_mfma_f32_16x16x32_bf16 v[0:3], v[182:185], v[218:221], v[0:3]
	s_barrier
; #define PG8_STAGE(bufoff, gbase, voff) do { _Pragma("unroll") for (int _i = 0; _i < 2; ++_i) \
;         __builtin_amdgcn_global_load_lds((const unsigned*)((const char*)(gbase) + (voff)[_i]), (PG8_LAS unsigned*)(lds + (bufoff) + ldsw + _i * 8192), 16, 0, 0); } while (0)
; #define PG8_LDA(dst, b, h) do { _Pragma("unroll") for (int m = 0; m < 4; ++m) _Pragma("unroll") for (int k = 0; k < 2; ++k) dst[m][k] = *(const PG8_LAS bf16x8*)(lds + PG8_SA(b, h) + aoff + m * 2048 + k * 1024); } while (0)
; #define PG8_LDB(dst, b, h) do { _Pragma("unroll") for (int n = 0; n < 2; ++n) _Pragma("unroll") for (int k = 0; k < 2; ++k) dst[n][k] = *(const PG8_LAS bf16x8*)(lds + PG8_SB(b, h) + boff + n * 2048 + k * 1024); } while (0)
; #define PG8_MMA(ai, bj, At, Bt) do { __builtin_amdgcn_s_setprio(1); _Pragma("unroll") for (int m = 0; m < 4; ++m) _Pragma("unroll") for (int n = 0; n < 2; ++n) _Pragma("unroll") for (int k = 0; k < 2; ++k) \
;         acc[ai][bj][m][n] = __builtin_amdgcn_mfma_f32_16x16x32_bf16(Bt[n][k], At[m][k], acc[ai][bj][m][n], 0, 0, 0); __builtin_amdgcn_s_setprio(0); } while (0)
; #define PG8_WAIT_V(n) asm volatile("s_waitcnt vmcnt(" #n ")" ::: "memory")
; #define PG8_WAIT_L(n) asm volatile("s_waitcnt lgkmcnt(" #n ")" ::: "memory")
; #define PG8_BAR __builtin_amdgcn_s_barrier()
; #define PG8_SCHED __builtin_amdgcn_sched_barrier(0)
; template <class Epi, class Sched, bool ALIGN_EPI = false, bool SP2 = false>
; __device__ __forceinline__ void gemm_phase(PG8_LAS unsigned char* lds, const Gemm g, const Sched& S, const Epi& E) {
;     ...
;             PG8_LDB(B0, 1, 0); PG8_LDB(B1, 1, 1); PG8_SCHED; PG8_LDA(At, 1, 0); PG8_STAGE(PG8_SA(0, 1), a2 + hstep, voffA);
;             PG8_WAIT_V(8); PG8_WAIT_L(0); PG8_BAR; PG8_MMA(0, 0, At, B0); PG8_MMA(0, 1, At, B1); PG8_BAR; PG8_SCHED;
;             PG8_LDA(At, 1, 1); PG8_STAGE(PG8_SB(1, 0), b3, voffB); PG8_STAGE(PG8_SB(1, 1), b3 + hstep, voffB); PG8_STAGE(PG8_SA(1, 0), a3, voffA);
;             PG8_WAIT_V(8); PG8_WAIT_L(0); PG8_BAR; PG8_MMA(1, 0, At, B0); PG8_MMA(1, 1, At, B1); PG8_BAR; PG8_SCHED;
.Lmy_peel_882_mid:
	s_add_i32 s62, 0, 0x18000
	s_add_i32 s63, 0, 0x1c000
	v_add_u32_e32 v140, s62, v172
	v_add_u32_e32 v177, s63, v172
	ds_read_b128 v[128:131], v140
	ds_read_b128 v[132:135], v140 offset:1024
	ds_read_b128 v[136:139], v140 offset:2048
	ds_read_b128 v[140:143], v140 offset:3072
	ds_read_b128 v[164:167], v177
	ds_read_b128 v[168:171], v177 offset:1024
	ds_read_b128 v[178:181], v177 offset:2048
	ds_read_b128 v[182:185], v177 offset:3072
	s_add_u32 s36, s36, 0x40000
	s_addc_u32 s37, s37, 0
	s_mov_b32 m0, s45
	ds_read_b128 v[190:193], v175 offset:32768
	ds_read_b128 v[194:197], v175 offset:33792
	ds_read_b128 v[198:201], v175 offset:34816
	ds_read_b128 v[202:205], v175 offset:35840
	ds_read_b128 v[206:209], v175 offset:36864
	ds_read_b128 v[210:213], v175 offset:37888
	ds_read_b128 v[214:217], v175 offset:38912
	ds_read_b128 v[218:221], v175 offset:39936
	global_load_lds_dwordx4 v144, s[36:37]
	s_mov_b32 m0, s46
	s_nop 0
	global_load_lds_dwordx4 v148, s[36:37]
	s_waitcnt vmcnt(8)
	s_waitcnt lgkmcnt(0)
	s_barrier
	v_mfma_f32_16x16x32_bf16 v[124:127], v[128:131], v[190:193], v[124:127]
	v_mfma_f32_16x16x32_bf16 v[120:123], v[136:139], v[190:193], v[120:123]
	v_mfma_f32_16x16x32_bf16 v[108:111], v[128:131], v[198:201], v[108:111]
	v_mfma_f32_16x16x32_bf16 v[104:107], v[136:139], v[198:201], v[104:107]
	v_mfma_f32_16x16x32_bf16 v[92:95], v[128:131], v[206:209], v[92:95]
	v_mfma_f32_16x16x32_bf16 v[88:91], v[136:139], v[206:209], v[88:91]
	v_mfma_f32_16x16x32_bf16 v[76:79], v[128:131], v[214:217], v[76:79]
	v_mfma_f32_16x16x32_bf16 v[72:75], v[136:139], v[214:217], v[72:75]
	v_mfma_f32_16x16x32_bf16 v[124:127], v[132:135], v[194:197], v[124:127]
	v_mfma_f32_16x16x32_bf16 v[120:123], v[140:143], v[194:197], v[120:123]
	v_mfma_f32_16x16x32_bf16 v[108:111], v[132:135], v[202:205], v[108:111]
	v_mfma_f32_16x16x32_bf16 v[104:107], v[140:143], v[202:205], v[104:107]
	v_mfma_f32_16x16x32_bf16 v[92:95], v[132:135], v[210:213], v[92:95]
	v_mfma_f32_16x16x32_bf16 v[88:91], v[140:143], v[210:213], v[88:91]
	v_mfma_f32_16x16x32_bf16 v[76:79], v[132:135], v[218:221], v[76:79]
	v_mfma_f32_16x16x32_bf16 v[72:75], v[140:143], v[218:221], v[72:75]
	v_mfma_f32_16x16x32_bf16 v[116:119], v[164:167], v[190:193], v[116:119]
	v_mfma_f32_16x16x32_bf16 v[112:115], v[178:181], v[190:193], v[112:115]
	v_mfma_f32_16x16x32_bf16 v[100:103], v[164:167], v[198:201], v[100:103]
	v_mfma_f32_16x16x32_bf16 v[96:99], v[178:181], v[198:201], v[96:99]
	v_mfma_f32_16x16x32_bf16 v[84:87], v[164:167], v[206:209], v[84:87]
	v_mfma_f32_16x16x32_bf16 v[80:83], v[178:181], v[206:209], v[80:83]
	v_mfma_f32_16x16x32_bf16 v[68:71], v[164:167], v[214:217], v[68:71]
	v_mfma_f32_16x16x32_bf16 v[64:67], v[178:181], v[214:217], v[64:67]
	v_mfma_f32_16x16x32_bf16 v[116:119], v[168:171], v[194:197], v[116:119]
	v_mfma_f32_16x16x32_bf16 v[112:115], v[182:185], v[194:197], v[112:115]
	v_mfma_f32_16x16x32_bf16 v[100:103], v[168:171], v[202:205], v[100:103]
	v_mfma_f32_16x16x32_bf16 v[96:99], v[182:185], v[202:205], v[96:99]
	v_mfma_f32_16x16x32_bf16 v[84:87], v[168:171], v[210:213], v[84:87]
	v_mfma_f32_16x16x32_bf16 v[80:83], v[182:185], v[210:213], v[80:83]
	v_mfma_f32_16x16x32_bf16 v[68:71], v[168:171], v[218:221], v[68:71]
	v_mfma_f32_16x16x32_bf16 v[64:67], v[182:185], v[218:221], v[64:67]
	s_barrier
	s_add_i32 s36, s62, s42
	s_mov_b32 m0, s36
	ds_read_b128 v[190:193], v175 offset:49152
	ds_read_b128 v[194:197], v175 offset:50176
	ds_read_b128 v[198:201], v175 offset:51200
	ds_read_b128 v[202:205], v175 offset:52224
	ds_read_b128 v[206:209], v175 offset:53248
	ds_read_b128 v[210:213], v175 offset:54272
	ds_read_b128 v[214:217], v175 offset:55296
	ds_read_b128 v[218:221], v175 offset:56320
	global_load_lds_dwordx4 v146, s[92:93]
	s_add_i32 m0, s36, 0x2000
	s_add_u32 s34, s34, 0x40080
	s_addc_u32 s35, s35, 0
	s_add_i32 s36, s63, s42
	global_load_lds_dwordx4 v150, s[92:93]
	s_mov_b32 m0, s36
	s_nop 0
	global_load_lds_dwordx4 v146, s[34:35]
	s_add_i32 m0, s36, 0x2000
	s_nop 0
	global_load_lds_dwordx4 v150, s[34:35]
	s_mov_b32 m0, s48
	s_nop 0
	global_load_lds_dwordx4 v144, s[94:95]
	s_mov_b32 m0, s49
	s_nop 0
	global_load_lds_dwordx4 v148, s[94:95]
	s_waitcnt vmcnt(8)
	s_waitcnt lgkmcnt(0)
	s_barrier
	v_mfma_f32_16x16x32_bf16 v[60:63], v[128:131], v[190:193], v[60:63]
	v_mfma_f32_16x16x32_bf16 v[56:59], v[136:139], v[190:193], v[56:59]
	v_mfma_f32_16x16x32_bf16 v[44:47], v[128:131], v[198:201], v[44:47]
	v_mfma_f32_16x16x32_bf16 v[40:43], v[136:139], v[198:201], v[40:43]
	v_mfma_f32_16x16x32_bf16 v[28:31], v[128:131], v[206:209], v[28:31]
	v_mfma_f32_16x16x32_bf16 v[24:27], v[136:139], v[206:209], v[24:27]
	v_mfma_f32_16x16x32_bf16 v[12:15], v[128:131], v[214:217], v[12:15]
	v_mfma_f32_16x16x32_bf16 v[8:11], v[136:139], v[214:217], v[8:11]
	v_mfma_f32_16x16x32_bf16 v[60:63], v[132:135], v[194:197], v[60:63]
	v_mfma_f32_16x16x32_bf16 v[56:59], v[140:143], v[194:197], v[56:59]
	v_mfma_f32_16x16x32_bf16 v[44:47], v[132:135], v[202:205], v[44:47]
	v_mfma_f32_16x16x32_bf16 v[40:43], v[140:143], v[202:205], v[40:43]
	v_mfma_f32_16x16x32_bf16 v[28:31], v[132:135], v[210:213], v[28:31]
	v_mfma_f32_16x16x32_bf16 v[24:27], v[140:143], v[210:213], v[24:27]
	v_mfma_f32_16x16x32_bf16 v[12:15], v[132:135], v[218:221], v[12:15]
	v_mfma_f32_16x16x32_bf16 v[8:11], v[140:143], v[218:221], v[8:11]
	v_mfma_f32_16x16x32_bf16 v[52:55], v[164:167], v[190:193], v[52:55]
	v_mfma_f32_16x16x32_bf16 v[48:51], v[178:181], v[190:193], v[48:51]
	v_mfma_f32_16x16x32_bf16 v[36:39], v[164:167], v[198:201], v[36:39]
	v_mfma_f32_16x16x32_bf16 v[32:35], v[178:181], v[198:201], v[32:35]
	v_mfma_f32_16x16x32_bf16 v[20:23], v[164:167], v[206:209], v[20:23]
	v_mfma_f32_16x16x32_bf16 v[16:19], v[178:181], v[206:209], v[16:19]
	v_mfma_f32_16x16x32_bf16 v[4:7], v[164:167], v[214:217], v[4:7]
	v_mfma_f32_16x16x32_bf16 v[0:3], v[178:181], v[214:217], v[0:3]
	v_mfma_f32_16x16x32_bf16 v[52:55], v[168:171], v[194:197], v[52:55]
	v_mfma_f32_16x16x32_bf16 v[48:51], v[182:185], v[194:197], v[48:51]
	v_mfma_f32_16x16x32_bf16 v[36:39], v[168:171], v[202:205], v[36:39]
	v_mfma_f32_16x16x32_bf16 v[32:35], v[182:185], v[202:205], v[32:35]
	v_mfma_f32_16x16x32_bf16 v[20:23], v[168:171], v[210:213], v[20:23]
	v_mfma_f32_16x16x32_bf16 v[16:19], v[182:185], v[210:213], v[16:19]
	v_mfma_f32_16x16x32_bf16 v[4:7], v[168:171], v[218:221], v[4:7]
	v_mfma_f32_16x16x32_bf16 v[0:3], v[182:185], v[218:221], v[0:3]
	s_barrier
	s_add_i32 s61, s61, 2
	s_add_u32 s30, s30, 0x100
	s_addc_u32 s31, s31, 0
	s_add_u32 s59, s59, 0x100
	s_addc_u32 s60, s60, 0
	s_cmp_gt_u32 s61, 13
	s_cbranch_scc0 .LBB0_882
	s_and_b64 vcc, exec, s[18:19]
	s_cbranch_vccz .LBB0_885
	s_barrier

;     __host__ __device__ bool next(int i, Unit& u) const { const long L = (long)i * G + c; if (L >= nwg) return false; return unit_of((int)L, u); }
;     __host__ __device__ bool next(int i, Unit& u) const { const int L = i == 0 ? l0 : (i == 1 ? l1 : (i == 2 ? l2 : -1)); if (L < 0 || L >= s.nwg) return false; return s.unit_of(L, u); }
;     __host__ __device__ bool next(int i, Unit& u) const { const bool ok = s.next(i >> 1, u); u.kh = i & 1; return ok; }
; #define PG8_STAGE(bufoff, gbase, voff) do { _Pragma("unroll") for (int _i = 0; _i < 2; ++_i) \
;         __builtin_amdgcn_global_load_lds((const unsigned*)((const char*)(gbase) + (voff)[_i]), (PG8_LAS unsigned*)(lds + (bufoff) + ldsw + _i * 8192), 16, 0, 0); } while (0)
; #define PG8_LDA(dst, b, h) do { _Pragma("unroll") for (int m = 0; m < 4; ++m) _Pragma("unroll") for (int k = 0; k < 2; ++k) dst[m][k] = *(const PG8_LAS bf16x8*)(lds + PG8_SA(b, h) + aoff + m * 2048 + k * 1024); } while (0)
; template <class Epi, class Sched, bool ALIGN_EPI = false, bool SP2 = false>
; __device__ __forceinline__ void gemm_phase(PG8_LAS unsigned char* lds, const Gemm g, const Sched& S, const Epi& E) {
;     ...
;         const bool has_next = S.next(ui + 1, nxt);
;         const char* nA = has_next ? (const char*)g.A + (size_t)nxt.pm * tstep + nxt.kh * khb : cA; const char* nB = has_next ? (const char*)g.Bt + (size_t)nxt.pn * tstep + nxt.kh * khb : cB;
;         for (int t = 0; t < nt; t += 2) {
;             const bool last = (t == nt - 2);
;             const char* a1 = cA + (size_t)(t + 1) * kstep;
;             const char* a2 = last ? nA : cA + (size_t)(t + 2) * kstep; const char* b2 = last ? nB : cB + (size_t)(t + 2) * kstep;
;             const char* a3 = a2 + kstep; const char* b3 = b2 + kstep;
;             if (last && has_next) S.a_ready(nxt);
;             if constexpr (SP2) {
;             PG8_LDB(B0, 0, 0); PG8_LDB(B1, 0, 1); PG8_SCHED; PG8_LDA(At, 0, 0); PG8_STAGE(PG8_SA(1, 1), a1 + hstep, voffA);
;             PG8_WAIT_V(8); PG8_WAIT_L(0); PG8_BAR; PG8_MMA(0, 0, At, B0); PG8_MMA(0, 1, At, B1); PG8_BAR; PG8_SCHED;
;             PG8_LDA(At, 0, 1); PG8_STAGE(PG8_SB(0, 0), b2, voffB); PG8_STAGE(PG8_SB(0, 1), b2 + hstep, voffB); PG8_STAGE(PG8_SA(0, 0), a2, voffA);
;             PG8_WAIT_V(8); PG8_WAIT_L(0); PG8_BAR; PG8_MMA(1, 0, At, B0); PG8_MMA(1, 1, At, B1); PG8_BAR; PG8_SCHED;
.LBB0_968:
	s_ashr_i32 s17, s16, 31
	s_lshl_b64 s[18:19], s[16:17], 19
	s_add_u32 s18, s30, s18
	s_addc_u32 s19, s31, s19
	s_and_b64 s[20:21], s[2:3], exec
	s_cselect_b32 s17, s19, s25
	s_cselect_b32 s51, s18, s24
	s_ashr_i32 s15, s14, 31
	s_lshl_b64 s[20:21], s[14:15], 19
	s_add_u32 s20, s34, s20
	s_addc_u32 s21, s35, s21
	s_and_b64 s[28:29], s[2:3], exec
	s_cselect_b32 s15, s21, s27
	s_cselect_b32 s54, s20, s26
	s_add_u32 s24, s24, 0x40080
	s_addc_u32 s25, s25, 0
	s_add_u32 s55, s26, 0x100
	s_addc_u32 s56, s27, 0
	s_mov_b32 s57, -2
	ds_read_b128 v[128:131], v191
	ds_read_b128 v[132:135], v191 offset:1024
	ds_read_b128 v[136:139], v191 offset:2048
	ds_read_b128 v[140:143], v191 offset:3072
	ds_read_b128 v[144:147], v192
	ds_read_b128 v[148:151], v192 offset:1024
	ds_read_b128 v[172:175], v192 offset:2048
	ds_read_b128 v[176:179], v192 offset:3072
	s_add_u32 s26, s24, 0xfffc0080
	s_addc_u32 s27, s25, -1
	s_cmp_eq_u32 s57, 12
	s_cselect_b32 s29, s17, s27
	s_cselect_b32 s28, s51, s26
	s_cselect_b32 s27, s15, s56
	s_cselect_b32 s26, s54, s55
	s_add_i32 m0, s39, 0xc000
	ds_read_b128 v[180:183], v193
	ds_read_b128 v[184:187], v193 offset:1024
	ds_read_b128 v[196:199], v193 offset:2048
	ds_read_b128 v[200:203], v193 offset:3072
	ds_read_b128 v[204:207], v193 offset:4096
	ds_read_b128 v[208:211], v193 offset:5120
	ds_read_b128 v[212:215], v193 offset:6144
	ds_read_b128 v[216:219], v193 offset:7168
	global_load_lds_dwordx4 v164, s[24:25]
	s_add_i32 m0, s39, 0xe000
	s_nop 0
	global_load_lds_dwordx4 v166, s[24:25]
	s_waitcnt vmcnt(8)
	s_waitcnt lgkmcnt(0)
	s_barrier
	v_mfma_f32_16x16x32_bf16 v[124:127], v[128:131], v[180:183], 0
	v_mfma_f32_16x16x32_bf16 v[120:123], v[136:139], v[180:183], 0
	v_mfma_f32_16x16x32_bf16 v[108:111], v[128:131], v[196:199], 0
	v_mfma_f32_16x16x32_bf16 v[104:107], v[136:139], v[196:199], 0
	v_mfma_f32_16x16x32_bf16 v[92:95], v[128:131], v[204:207], 0
	v_mfma_f32_16x16x32_bf16 v[84:87], v[136:139], v[204:207], 0
	v_mfma_f32_16x16x32_bf16 v[76:79], v[128:131], v[212:215], 0
	v_mfma_f32_16x16x32_bf16 v[72:75], v[136:139], v[212:215], 0
	v_mfma_f32_16x16x32_bf16 v[124:127], v[132:135], v[184:187], v[124:127]
	v_mfma_f32_16x16x32_bf16 v[120:123], v[140:143], v[184:187], v[120:123]
	v_mfma_f32_16x16x32_bf16 v[108:111], v[132:135], v[200:203], v[108:111]
	v_mfma_f32_16x16x32_bf16 v[104:107], v[140:143], v[200:203], v[104:107]
	v_mfma_f32_16x16x32_bf16 v[92:95], v[132:135], v[208:211], v[92:95]
	v_mfma_f32_16x16x32_bf16 v[84:87], v[140:143], v[208:211], v[84:87]
	v_mfma_f32_16x16x32_bf16 v[76:79], v[132:135], v[216:219], v[76:79]
	v_mfma_f32_16x16x32_bf16 v[72:75], v[140:143], v[216:219], v[72:75]
	v_mfma_f32_16x16x32_bf16 v[116:119], v[144:147], v[180:183], 0
	v_mfma_f32_16x16x32_bf16 v[112:115], v[172:175], v[180:183], 0
	v_mfma_f32_16x16x32_bf16 v[100:103], v[144:147], v[196:199], 0
	v_mfma_f32_16x16x32_bf16 v[96:99], v[172:175], v[196:199], 0
	v_mfma_f32_16x16x32_bf16 v[88:91], v[144:147], v[204:207], 0
	v_mfma_f32_16x16x32_bf16 v[80:83], v[172:175], v[204:207], 0
	v_mfma_f32_16x16x32_bf16 v[68:71], v[144:147], v[212:215], 0
	v_mfma_f32_16x16x32_bf16 v[64:67], v[172:175], v[212:215], 0
	v_mfma_f32_16x16x32_bf16 v[116:119], v[148:151], v[184:187], v[116:119]
	v_mfma_f32_16x16x32_bf16 v[112:115], v[176:179], v[184:187], v[112:115]
	v_mfma_f32_16x16x32_bf16 v[100:103], v[148:151], v[200:203], v[100:103]
	v_mfma_f32_16x16x32_bf16 v[96:99], v[176:179], v[200:203], v[96:99]
	v_mfma_f32_16x16x32_bf16 v[88:91], v[148:151], v[208:211], v[88:91]
	v_mfma_f32_16x16x32_bf16 v[80:83], v[176:179], v[208:211], v[80:83]
	v_mfma_f32_16x16x32_bf16 v[68:71], v[148:151], v[216:219], v[68:71]
	v_mfma_f32_16x16x32_bf16 v[64:67], v[176:179], v[216:219], v[64:67]
	s_barrier
	s_add_u32 s92, s26, s10
	s_addc_u32 s93, s27, s11
	s_add_u32 s94, s28, s10
	s_addc_u32 s95, s29, s11
	s_add_i32 s58, s47, s36
	s_mov_b32 m0, s58
	ds_read_b128 v[180:183], v193 offset:16384
	ds_read_b128 v[184:187], v193 offset:17408
	ds_read_b128 v[196:199], v193 offset:18432
	ds_read_b128 v[200:203], v193 offset:19456
	ds_read_b128 v[204:207], v193 offset:20480
	ds_read_b128 v[208:211], v193 offset:21504
	ds_read_b128 v[212:215], v193 offset:22528
	ds_read_b128 v[216:219], v193 offset:23552
	global_load_lds_dwordx4 v156, s[26:27]
	s_add_i32 m0, s58, 0x2000
	s_add_u32 s58, s26, 0x40000
	s_addc_u32 s59, s27, 0
	s_add_i32 s60, s48, s36
	global_load_lds_dwordx4 v152, s[26:27]
	s_mov_b32 m0, s60
	s_nop 0
	global_load_lds_dwordx4 v156, s[58:59]
	s_add_i32 m0, s60, 0x2000
	s_nop 0
	global_load_lds_dwordx4 v152, s[58:59]
	s_mov_b32 m0, s39
	s_nop 0
	global_load_lds_dwordx4 v158, s[28:29]
	s_mov_b32 m0, s40
	s_nop 0
	global_load_lds_dwordx4 v154, s[28:29]
	s_waitcnt vmcnt(8)
	s_waitcnt lgkmcnt(0)
	s_barrier
	v_mfma_f32_16x16x32_bf16 v[60:63], v[128:131], v[180:183], 0
	v_mfma_f32_16x16x32_bf16 v[52:55], v[136:139], v[180:183], 0
	v_mfma_f32_16x16x32_bf16 v[44:47], v[128:131], v[196:199], 0
	v_mfma_f32_16x16x32_bf16 v[40:43], v[136:139], v[196:199], 0
	v_mfma_f32_16x16x32_bf16 v[28:31], v[128:131], v[204:207], 0
	v_mfma_f32_16x16x32_bf16 v[20:23], v[136:139], v[204:207], 0
	v_mfma_f32_16x16x32_bf16 v[12:15], v[128:131], v[212:215], 0
	v_mfma_f32_16x16x32_bf16 v[8:11], v[136:139], v[212:215], 0
	v_mfma_f32_16x16x32_bf16 v[60:63], v[132:135], v[184:187], v[60:63]
	v_mfma_f32_16x16x32_bf16 v[52:55], v[140:143], v[184:187], v[52:55]
	v_mfma_f32_16x16x32_bf16 v[44:47], v[132:135], v[200:203], v[44:47]
	v_mfma_f32_16x16x32_bf16 v[40:43], v[140:143], v[200:203], v[40:43]
	v_mfma_f32_16x16x32_bf16 v[28:31], v[132:135], v[208:211], v[28:31]
	v_mfma_f32_16x16x32_bf16 v[20:23], v[140:143], v[208:211], v[20:23]
	v_mfma_f32_16x16x32_bf16 v[12:15], v[132:135], v[216:219], v[12:15]
	v_mfma_f32_16x16x32_bf16 v[8:11], v[140:143], v[216:219], v[8:11]
	v_mfma_f32_16x16x32_bf16 v[56:59], v[144:147], v[180:183], 0
	v_mfma_f32_16x16x32_bf16 v[48:51], v[172:175], v[180:183], 0
	v_mfma_f32_16x16x32_bf16 v[36:39], v[144:147], v[196:199], 0
	v_mfma_f32_16x16x32_bf16 v[32:35], v[172:175], v[196:199], 0
	v_mfma_f32_16x16x32_bf16 v[24:27], v[144:147], v[204:207], 0
	v_mfma_f32_16x16x32_bf16 v[16:19], v[172:175], v[204:207], 0
	v_mfma_f32_16x16x32_bf16 v[4:7], v[144:147], v[212:215], 0
	v_mfma_f32_16x16x32_bf16 v[0:3], v[172:175], v[212:215], 0
	v_mfma_f32_16x16x32_bf16 v[56:59], v[148:151], v[184:187], v[56:59]
	v_mfma_f32_16x16x32_bf16 v[48:51], v[176:179], v[184:187], v[48:51]
	v_mfma_f32_16x16x32_bf16 v[36:39], v[148:151], v[200:203], v[36:39]
	v_mfma_f32_16x16x32_bf16 v[32:35], v[176:179], v[200:203], v[32:35]
	v_mfma_f32_16x16x32_bf16 v[24:27], v[148:151], v[208:211], v[24:27]
	v_mfma_f32_16x16x32_bf16 v[16:19], v[176:179], v[208:211], v[16:19]
	v_mfma_f32_16x16x32_bf16 v[4:7], v[148:151], v[216:219], v[4:7]
	v_mfma_f32_16x16x32_bf16 v[0:3], v[176:179], v[216:219], v[0:3]
	s_barrier
	s_branch .Lmy_peel_969_mid
; #define PG8_STAGE(bufoff, gbase, voff) do { _Pragma("unroll") for (int _i = 0; _i < 2; ++_i) \
;         __builtin_amdgcn_global_load_lds((const unsigned*)((const char*)(gbase) + (voff)[_i]), (PG8_LAS unsigned*)(lds + (bufoff) + ldsw + _i * 8192), 16, 0, 0); } while (0)
; #define PG8_LDA(dst, b, h) do { _Pragma("unroll") for (int m = 0; m < 4; ++m) _Pragma("unroll") for (int k = 0; k < 2; ++k) dst[m][k] = *(const PG8_LAS bf16x8*)(lds + PG8_SA(b, h) + aoff + m * 2048 + k * 1024); } while (0)
; #define PG8_LDB(dst, b, h) do { _Pragma("unroll") for (int n = 0; n < 2; ++n) _Pragma("unroll") for (int k = 0; k < 2; ++k) dst[n][k] = *(const PG8_LAS bf16x8*)(lds + PG8_SB(b, h) + boff + n * 2048 + k * 1024); } while (0)
; #define PG8_MMA(ai, bj, At, Bt) do { __builtin_amdgcn_s_setprio(1); _Pragma("unroll") for (int m = 0; m < 4; ++m) _Pragma("unroll") for (int n = 0; n < 2; ++n) _Pragma("unroll") for (int k = 0; k < 2; ++k) \
;         acc[ai][bj][m][n] = __builtin_amdgcn_mfma_f32_16x16x32_bf16(Bt[n][k], At[m][k], acc[ai][bj][m][n], 0, 0, 0); __builtin_amdgcn_s_setprio(0); } while (0)
; #define PG8_WAIT_V(n) asm volatile("s_waitcnt vmcnt(" #n ")" ::: "memory")
; #define PG8_WAIT_L(n) asm volatile("s_waitcnt lgkmcnt(" #n ")" ::: "memory")
; template <class Epi, class Sched, bool ALIGN_EPI = false, bool SP2 = false>
; __device__ __forceinline__ void gemm_phase(PG8_LAS unsigned char* lds, const Gemm g, const Sched& S, const Epi& E) {
;     ...
;             const bool last = (t == nt - 2);
;             const char* a1 = cA + (size_t)(t + 1) * kstep;
;             const char* a2 = last ? nA : cA + (size_t)(t + 2) * kstep; const char* b2 = last ? nB : cB + (size_t)(t + 2) * kstep;
;             const char* a3 = a2 + kstep; const char* b3 = b2 + kstep;
;             if (last && has_next) S.a_ready(nxt);
;             if constexpr (SP2) {
;             PG8_LDB(B0, 0, 0); PG8_LDB(B1, 0, 1); PG8_SCHED; PG8_LDA(At, 0, 0); PG8_STAGE(PG8_SA(1, 1), a1 + hstep, voffA);
;             PG8_WAIT_V(8); PG8_WAIT_L(0); PG8_BAR; PG8_MMA(0, 0, At, B0); PG8_MMA(0, 1, At, B1); PG8_BAR; PG8_SCHED;
;             PG8_LDA(At, 0, 1); PG8_STAGE(PG8_SB(0, 0), b2, voffB); PG8_STAGE(PG8_SB(0, 1), b2 + hstep, voffB); PG8_STAGE(PG8_SA(0, 0), a2, voffA);
;             PG8_WAIT_V(8); PG8_WAIT_L(0); PG8_BAR; PG8_MMA(1, 0, At, B0); PG8_MMA(1, 1, At, B1); PG8_BAR; PG8_SCHED;
.LBB0_969:
	ds_read_b128 v[128:131], v191
	ds_read_b128 v[132:135], v191 offset:1024
	ds_read_b128 v[136:139], v191 offset:2048
	ds_read_b128 v[140:143], v191 offset:3072
	ds_read_b128 v[144:147], v192
	ds_read_b128 v[148:151], v192 offset:1024
	ds_read_b128 v[172:175], v192 offset:2048
	ds_read_b128 v[176:179], v192 offset:3072
	s_add_u32 s26, s24, 0xfffc0080
	s_addc_u32 s27, s25, -1
	s_cmp_eq_u32 s57, 12
	s_cselect_b32 s29, s17, s27
	s_cselect_b32 s28, s51, s26
	s_cselect_b32 s27, s15, s56
	s_cselect_b32 s26, s54, s55
	s_add_i32 m0, s39, 0xc000
	ds_read_b128 v[180:183], v193
	ds_read_b128 v[184:187], v193 offset:1024
	ds_read_b128 v[196:199], v193 offset:2048
	ds_read_b128 v[200:203], v193 offset:3072
	ds_read_b128 v[204:207], v193 offset:4096
	ds_read_b128 v[208:211], v193 offset:5120
	ds_read_b128 v[212:215], v193 offset:6144
	ds_read_b128 v[216:219], v193 offset:7168
	global_load_lds_dwordx4 v164, s[24:25]
	s_add_i32 m0, s39, 0xe000
	s_nop 0
	global_load_lds_dwordx4 v166, s[24:25]
	s_waitcnt vmcnt(8)
	s_waitcnt lgkmcnt(0)
	s_barrier
	v_mfma_f32_16x16x32_bf16 v[124:127], v[128:131], v[180:183], v[124:127]
	v_mfma_f32_16x16x32_bf16 v[120:123], v[136:139], v[180:183], v[120:123]
	v_mfma_f32_16x16x32_bf16 v[108:111], v[128:131], v[196:199], v[108:111]
	v_mfma_f32_16x16x32_bf16 v[104:107], v[136:139], v[196:199], v[104:107]
	v_mfma_f32_16x16x32_bf16 v[92:95], v[128:131], v[204:207], v[92:95]
	v_mfma_f32_16x16x32_bf16 v[84:87], v[136:139], v[204:207], v[84:87]
	v_mfma_f32_16x16x32_bf16 v[76:79], v[128:131], v[212:215], v[76:79]
	v_mfma_f32_16x16x32_bf16 v[72:75], v[136:139], v[212:215], v[72:75]
	v_mfma_f32_16x16x32_bf16 v[124:127], v[132:135], v[184:187], v[124:127]
	v_mfma_f32_16x16x32_bf16 v[120:123], v[140:143], v[184:187], v[120:123]
	v_mfma_f32_16x16x32_bf16 v[108:111], v[132:135], v[200:203], v[108:111]
	v_mfma_f32_16x16x32_bf16 v[104:107], v[140:143], v[200:203], v[104:107]
	v_mfma_f32_16x16x32_bf16 v[92:95], v[132:135], v[208:211], v[92:95]
	v_mfma_f32_16x16x32_bf16 v[84:87], v[140:143], v[208:211], v[84:87]
	v_mfma_f32_16x16x32_bf16 v[76:79], v[132:135], v[216:219], v[76:79]
	v_mfma_f32_16x16x32_bf16 v[72:75], v[140:143], v[216:219], v[72:75]
	v_mfma_f32_16x16x32_bf16 v[116:119], v[144:147], v[180:183], v[116:119]
	v_mfma_f32_16x16x32_bf16 v[112:115], v[172:175], v[180:183], v[112:115]
	v_mfma_f32_16x16x32_bf16 v[100:103], v[144:147], v[196:199], v[100:103]
	v_mfma_f32_16x16x32_bf16 v[96:99], v[172:175], v[196:199], v[96:99]
	v_mfma_f32_16x16x32_bf16 v[88:91], v[144:147], v[204:207], v[88:91]
	v_mfma_f32_16x16x32_bf16 v[80:83], v[172:175], v[204:207], v[80:83]
	v_mfma_f32_16x16x32_bf16 v[68:71], v[144:147], v[212:215], v[68:71]
	v_mfma_f32_16x16x32_bf16 v[64:67], v[172:175], v[212:215], v[64:67]
	v_mfma_f32_16x16x32_bf16 v[116:119], v[148:151], v[184:187], v[116:119]
	v_mfma_f32_16x16x32_bf16 v[112:115], v[176:179], v[184:187], v[112:115]
	v_mfma_f32_16x16x32_bf16 v[100:103], v[148:151], v[200:203], v[100:103]
	v_mfma_f32_16x16x32_bf16 v[96:99], v[176:179], v[200:203], v[96:99]
	v_mfma_f32_16x16x32_bf16 v[88:91], v[148:151], v[208:211], v[88:91]
	v_mfma_f32_16x16x32_bf16 v[80:83], v[176:179], v[208:211], v[80:83]
	v_mfma_f32_16x16x32_bf16 v[68:71], v[148:151], v[216:219], v[68:71]
	v_mfma_f32_16x16x32_bf16 v[64:67], v[176:179], v[216:219], v[64:67]
	s_barrier
	s_add_u32 s92, s26, s10
	s_addc_u32 s93, s27, s11
	s_add_u32 s94, s28, s10
	s_addc_u32 s95, s29, s11
	s_add_i32 s58, s47, s36
	s_mov_b32 m0, s58
	ds_read_b128 v[180:183], v193 offset:16384
	ds_read_b128 v[184:187], v193 offset:17408
	ds_read_b128 v[196:199], v193 offset:18432
	ds_read_b128 v[200:203], v193 offset:19456
	ds_read_b128 v[204:207], v193 offset:20480
	ds_read_b128 v[208:211], v193 offset:21504
	ds_read_b128 v[212:215], v193 offset:22528
	ds_read_b128 v[216:219], v193 offset:23552
	global_load_lds_dwordx4 v156, s[26:27]
	s_add_i32 m0, s58, 0x2000
	s_add_u32 s58, s26, 0x40000
	s_addc_u32 s59, s27, 0
	s_add_i32 s60, s48, s36
	global_load_lds_dwordx4 v152, s[26:27]
	s_mov_b32 m0, s60
	s_nop 0
	global_load_lds_dwordx4 v156, s[58:59]
	s_add_i32 m0, s60, 0x2000
	s_nop 0
	global_load_lds_dwordx4 v152, s[58:59]
	s_mov_b32 m0, s39
	s_nop 0
	global_load_lds_dwordx4 v158, s[28:29]
	s_mov_b32 m0, s40
	s_nop 0
	global_load_lds_dwordx4 v154, s[28:29]
	s_waitcnt vmcnt(8)
	s_waitcnt lgkmcnt(0)
	s_barrier
	v_mfma_f32_16x16x32_bf16 v[60:63], v[128:131], v[180:183], v[60:63]
	v_mfma_f32_16x16x32_bf16 v[52:55], v[136:139], v[180:183], v[52:55]
	v_mfma_f32_16x16x32_bf16 v[44:47], v[128:131], v[196:199], v[44:47]
	v_mfma_f32_16x16x32_bf16 v[40:43], v[136:139], v[196:199], v[40:43]
	v_mfma_f32_16x16x32_bf16 v[28:31], v[128:131], v[204:207], v[28:31]
	v_mfma_f32_16x16x32_bf16 v[20:23], v[136:139], v[204:207], v[20:23]
	v_mfma_f32_16x16x32_bf16 v[12:15], v[128:131], v[212:215], v[12:15]
	v_mfma_f32_16x16x32_bf16 v[8:11], v[136:139], v[212:215], v[8:11]
	v_mfma_f32_16x16x32_bf16 v[60:63], v[132:135], v[184:187], v[60:63]
	v_mfma_f32_16x16x32_bf16 v[52:55], v[140:143], v[184:187], v[52:55]
	v_mfma_f32_16x16x32_bf16 v[44:47], v[132:135], v[200:203], v[44:47]
	v_mfma_f32_16x16x32_bf16 v[40:43], v[140:143], v[200:203], v[40:43]
	v_mfma_f32_16x16x32_bf16 v[28:31], v[132:135], v[208:211], v[28:31]
	v_mfma_f32_16x16x32_bf16 v[20:23], v[140:143], v[208:211], v[20:23]
	v_mfma_f32_16x16x32_bf16 v[12:15], v[132:135], v[216:219], v[12:15]
	v_mfma_f32_16x16x32_bf16 v[8:11], v[140:143], v[216:219], v[8:11]
	v_mfma_f32_16x16x32_bf16 v[56:59], v[144:147], v[180:183], v[56:59]
	v_mfma_f32_16x16x32_bf16 v[48:51], v[172:175], v[180:183], v[48:51]
	v_mfma_f32_16x16x32_bf16 v[36:39], v[144:147], v[196:199], v[36:39]
	v_mfma_f32_16x16x32_bf16 v[32:35], v[172:175], v[196:199], v[32:35]
	v_mfma_f32_16x16x32_bf16 v[24:27], v[144:147], v[204:207], v[24:27]
	v_mfma_f32_16x16x32_bf16 v[16:19], v[172:175], v[204:207], v[16:19]
	v_mfma_f32_16x16x32_bf16 v[4:7], v[144:147], v[212:215], v[4:7]
	v_mfma_f32_16x16x32_bf16 v[0:3], v[172:175], v[212:215], v[0:3]
	v_mfma_f32_16x16x32_bf16 v[56:59], v[148:151], v[184:187], v[56:59]
	v_mfma_f32_16x16x32_bf16 v[48:51], v[176:179], v[184:187], v[48:51]
	v_mfma_f32_16x16x32_bf16 v[36:39], v[148:151], v[200:203], v[36:39]
	v_mfma_f32_16x16x32_bf16 v[32:35], v[176:179], v[200:203], v[32:35]
	v_mfma_f32_16x16x32_bf16 v[24:27], v[148:151], v[208:211], v[24:27]
	v_mfma_f32_16x16x32_bf16 v[16:19], v[176:179], v[208:211], v[16:19]
	v_mfma_f32_16x16x32_bf16 v[4:7], v[148:151], v[216:219], v[4:7]
	v_mfma_f32_16x16x32_bf16 v[0:3], v[176:179], v[216:219], v[0:3]
	s_barrier
; #define PG8_STAGE(bufoff, gbase, voff) do { _Pragma("unroll") for (int _i = 0; _i < 2; ++_i) \
;         __builtin_amdgcn_global_load_lds((const unsigned*)((const char*)(gbase) + (voff)[_i]), (PG8_LAS unsigned*)(lds + (bufoff) + ldsw + _i * 8192), 16, 0, 0); } while (0)
; #define PG8_LDA(dst, b, h) do { _Pragma("unroll") for (int m = 0; m < 4; ++m) _Pragma("unroll") for (int k = 0; k < 2; ++k) dst[m][k] = *(const PG8_LAS bf16x8*)(lds + PG8_SA(b, h) + aoff + m * 2048 + k * 1024); } while (0)
; #define PG8_LDB(dst, b, h) do { _Pragma("unroll") for (int n = 0; n < 2; ++n) _Pragma("unroll") for (int k = 0; k < 2; ++k) dst[n][k] = *(const PG8_LAS bf16x8*)(lds + PG8_SB(b, h) + boff + n * 2048 + k * 1024); } while (0)
; #define PG8_MMA(ai, bj, At, Bt) do { __builtin_amdgcn_s_setprio(1); _Pragma("unroll") for (int m = 0; m < 4; ++m) _Pragma("unroll") for (int n = 0; n < 2; ++n) _Pragma("unroll") for (int k = 0; k < 2; ++k) \
;         acc[ai][bj][m][n] = __builtin_amdgcn_mfma_f32_16x16x32_bf16(Bt[n][k], At[m][k], acc[ai][bj][m][n], 0, 0, 0); __builtin_amdgcn_s_setprio(0); } while (0)
; #define PG8_WAIT_V(n) asm volatile("s_waitcnt vmcnt(" #n ")" ::: "memory")
; #define PG8_WAIT_L(n) asm volatile("s_waitcnt lgkmcnt(" #n ")" ::: "memory")
; #define PG8_BAR __builtin_amdgcn_s_barrier()
; #define PG8_SCHED __builtin_amdgcn_sched_barrier(0)
; template <class Epi, class Sched, bool ALIGN_EPI = false, bool SP2 = false>
; __device__ __forceinline__ void gemm_phase(PG8_LAS unsigned char* lds, const Gemm g, const Sched& S, const Epi& E) {
;     ...
;             PG8_LDB(B0, 1, 0); PG8_LDB(B1, 1, 1); PG8_SCHED; PG8_LDA(At, 1, 0); PG8_STAGE(PG8_SA(0, 1), a2 + hstep, voffA);
;             PG8_WAIT_V(8); PG8_WAIT_L(0); PG8_BAR; PG8_MMA(0, 0, At, B0); PG8_MMA(0, 1, At, B1); PG8_BAR; PG8_SCHED;
;             PG8_LDA(At, 1, 1); PG8_STAGE(PG8_SB(1, 0), b3, voffB); PG8_STAGE(PG8_SB(1, 1), b3 + hstep, voffB); PG8_STAGE(PG8_SA(1, 0), a3, voffA);
;             PG8_WAIT_V(8); PG8_WAIT_L(0); PG8_BAR; PG8_MMA(1, 0, At, B0); PG8_MMA(1, 1, At, B1); PG8_BAR; PG8_SCHED;
.Lmy_peel_969_mid:
	s_add_i32 s58, 0, 0x18000
	s_add_i32 s59, 0, 0x1c000
	v_add_u32_e32 v140, s58, v190
	v_add_u32_e32 v176, s59, v190
	ds_read_b128 v[128:131], v140
	ds_read_b128 v[132:135], v140 offset:1024
	ds_read_b128 v[136:139], v140 offset:2048
	ds_read_b128 v[140:143], v140 offset:3072
	ds_read_b128 v[144:147], v176
	ds_read_b128 v[148:151], v176 offset:1024
	ds_read_b128 v[172:175], v176 offset:2048
	ds_read_b128 v[176:179], v176 offset:3072
	s_add_u32 s28, s28, 0x40000
	s_addc_u32 s29, s29, 0
	s_mov_b32 m0, s41
	ds_read_b128 v[180:183], v193 offset:32768
	ds_read_b128 v[184:187], v193 offset:33792
	ds_read_b128 v[196:199], v193 offset:34816
	ds_read_b128 v[200:203], v193 offset:35840
	ds_read_b128 v[204:207], v193 offset:36864
	ds_read_b128 v[208:211], v193 offset:37888
	ds_read_b128 v[212:215], v193 offset:38912
	ds_read_b128 v[216:219], v193 offset:39936
	global_load_lds_dwordx4 v158, s[28:29]
	s_mov_b32 m0, s42
	s_nop 0
	global_load_lds_dwordx4 v154, s[28:29]
	s_waitcnt vmcnt(8)
	s_waitcnt lgkmcnt(0)
	s_barrier
	v_mfma_f32_16x16x32_bf16 v[124:127], v[128:131], v[180:183], v[124:127]
	v_mfma_f32_16x16x32_bf16 v[120:123], v[136:139], v[180:183], v[120:123]
	v_mfma_f32_16x16x32_bf16 v[108:111], v[128:131], v[196:199], v[108:111]
	v_mfma_f32_16x16x32_bf16 v[104:107], v[136:139], v[196:199], v[104:107]
	v_mfma_f32_16x16x32_bf16 v[92:95], v[128:131], v[204:207], v[92:95]
	v_mfma_f32_16x16x32_bf16 v[84:87], v[136:139], v[204:207], v[84:87]
	v_mfma_f32_16x16x32_bf16 v[76:79], v[128:131], v[212:215], v[76:79]
	v_mfma_f32_16x16x32_bf16 v[72:75], v[136:139], v[212:215], v[72:75]
	v_mfma_f32_16x16x32_bf16 v[124:127], v[132:135], v[184:187], v[124:127]
	v_mfma_f32_16x16x32_bf16 v[120:123], v[140:143], v[184:187], v[120:123]
	v_mfma_f32_16x16x32_bf16 v[108:111], v[132:135], v[200:203], v[108:111]
	v_mfma_f32_16x16x32_bf16 v[104:107], v[140:143], v[200:203], v[104:107]
	v_mfma_f32_16x16x32_bf16 v[92:95], v[132:135], v[208:211], v[92:95]
	v_mfma_f32_16x16x32_bf16 v[84:87], v[140:143], v[208:211], v[84:87]
	v_mfma_f32_16x16x32_bf16 v[76:79], v[132:135], v[216:219], v[76:79]
	v_mfma_f32_16x16x32_bf16 v[72:75], v[140:143], v[216:219], v[72:75]
	v_mfma_f32_16x16x32_bf16 v[116:119], v[144:147], v[180:183], v[116:119]
	v_mfma_f32_16x16x32_bf16 v[112:115], v[172:175], v[180:183], v[112:115]
	v_mfma_f32_16x16x32_bf16 v[100:103], v[144:147], v[196:199], v[100:103]
	v_mfma_f32_16x16x32_bf16 v[96:99], v[172:175], v[196:199], v[96:99]
	v_mfma_f32_16x16x32_bf16 v[88:91], v[144:147], v[204:207], v[88:91]
	v_mfma_f32_16x16x32_bf16 v[80:83], v[172:175], v[204:207], v[80:83]
	v_mfma_f32_16x16x32_bf16 v[68:71], v[144:147], v[212:215], v[68:71]
	v_mfma_f32_16x16x32_bf16 v[64:67], v[172:175], v[212:215], v[64:67]
	v_mfma_f32_16x16x32_bf16 v[116:119], v[148:151], v[184:187], v[116:119]
	v_mfma_f32_16x16x32_bf16 v[112:115], v[176:179], v[184:187], v[112:115]
	v_mfma_f32_16x16x32_bf16 v[100:103], v[148:151], v[200:203], v[100:103]
	v_mfma_f32_16x16x32_bf16 v[96:99], v[176:179], v[200:203], v[96:99]
	v_mfma_f32_16x16x32_bf16 v[88:91], v[148:151], v[208:211], v[88:91]
	v_mfma_f32_16x16x32_bf16 v[80:83], v[176:179], v[208:211], v[80:83]
	v_mfma_f32_16x16x32_bf16 v[68:71], v[148:151], v[216:219], v[68:71]
	v_mfma_f32_16x16x32_bf16 v[64:67], v[176:179], v[216:219], v[64:67]
	s_barrier
	s_add_i32 s28, s58, s36
	s_mov_b32 m0, s28
	ds_read_b128 v[180:183], v193 offset:49152
	ds_read_b128 v[184:187], v193 offset:50176
	ds_read_b128 v[196:199], v193 offset:51200
	ds_read_b128 v[200:203], v193 offset:52224
	ds_read_b128 v[204:207], v193 offset:53248
	ds_read_b128 v[208:211], v193 offset:54272
	ds_read_b128 v[212:215], v193 offset:55296
	ds_read_b128 v[216:219], v193 offset:56320
	global_load_lds_dwordx4 v156, s[92:93]
	s_add_i32 m0, s28, 0x2000
	s_add_u32 s26, s26, 0x40080
	s_addc_u32 s27, s27, 0
	s_add_i32 s28, s59, s36
	global_load_lds_dwordx4 v152, s[92:93]
	s_mov_b32 m0, s28
	s_nop 0
	global_load_lds_dwordx4 v156, s[26:27]
	s_add_i32 m0, s28, 0x2000
	s_nop 0
	global_load_lds_dwordx4 v152, s[26:27]
	s_mov_b32 m0, s43
	s_nop 0
	global_load_lds_dwordx4 v158, s[94:95]
	s_mov_b32 m0, s44
	s_nop 0
	global_load_lds_dwordx4 v154, s[94:95]
	s_waitcnt vmcnt(8)
	s_waitcnt lgkmcnt(0)
	s_barrier
	v_mfma_f32_16x16x32_bf16 v[60:63], v[128:131], v[180:183], v[60:63]
	v_mfma_f32_16x16x32_bf16 v[52:55], v[136:139], v[180:183], v[52:55]
	v_mfma_f32_16x16x32_bf16 v[44:47], v[128:131], v[196:199], v[44:47]
	v_mfma_f32_16x16x32_bf16 v[40:43], v[136:139], v[196:199], v[40:43]
	v_mfma_f32_16x16x32_bf16 v[28:31], v[128:131], v[204:207], v[28:31]
	v_mfma_f32_16x16x32_bf16 v[20:23], v[136:139], v[204:207], v[20:23]
	v_mfma_f32_16x16x32_bf16 v[12:15], v[128:131], v[212:215], v[12:15]
	v_mfma_f32_16x16x32_bf16 v[8:11], v[136:139], v[212:215], v[8:11]
	v_mfma_f32_16x16x32_bf16 v[60:63], v[132:135], v[184:187], v[60:63]
	v_mfma_f32_16x16x32_bf16 v[52:55], v[140:143], v[184:187], v[52:55]
	v_mfma_f32_16x16x32_bf16 v[44:47], v[132:135], v[200:203], v[44:47]
	v_mfma_f32_16x16x32_bf16 v[40:43], v[140:143], v[200:203], v[40:43]
	v_mfma_f32_16x16x32_bf16 v[28:31], v[132:135], v[208:211], v[28:31]
	v_mfma_f32_16x16x32_bf16 v[20:23], v[140:143], v[208:211], v[20:23]
	v_mfma_f32_16x16x32_bf16 v[12:15], v[132:135], v[216:219], v[12:15]
	v_mfma_f32_16x16x32_bf16 v[8:11], v[140:143], v[216:219], v[8:11]
	v_mfma_f32_16x16x32_bf16 v[56:59], v[144:147], v[180:183], v[56:59]
	v_mfma_f32_16x16x32_bf16 v[48:51], v[172:175], v[180:183], v[48:51]
	v_mfma_f32_16x16x32_bf16 v[36:39], v[144:147], v[196:199], v[36:39]
	v_mfma_f32_16x16x32_bf16 v[32:35], v[172:175], v[196:199], v[32:35]
	v_mfma_f32_16x16x32_bf16 v[24:27], v[144:147], v[204:207], v[24:27]
	v_mfma_f32_16x16x32_bf16 v[16:19], v[172:175], v[204:207], v[16:19]
	v_mfma_f32_16x16x32_bf16 v[4:7], v[144:147], v[212:215], v[4:7]
	v_mfma_f32_16x16x32_bf16 v[0:3], v[172:175], v[212:215], v[0:3]
	v_mfma_f32_16x16x32_bf16 v[56:59], v[148:151], v[184:187], v[56:59]
	v_mfma_f32_16x16x32_bf16 v[48:51], v[176:179], v[184:187], v[48:51]
	v_mfma_f32_16x16x32_bf16 v[36:39], v[148:151], v[200:203], v[36:39]
	v_mfma_f32_16x16x32_bf16 v[32:35], v[176:179], v[200:203], v[32:35]
	v_mfma_f32_16x16x32_bf16 v[24:27], v[148:151], v[208:211], v[24:27]
	v_mfma_f32_16x16x32_bf16 v[16:19], v[176:179], v[208:211], v[16:19]
	v_mfma_f32_16x16x32_bf16 v[4:7], v[148:151], v[216:219], v[4:7]
	v_mfma_f32_16x16x32_bf16 v[0:3], v[176:179], v[216:219], v[0:3]
	s_barrier
	s_add_i32 s57, s57, 2
	s_add_u32 s24, s24, 0x100
	s_addc_u32 s25, s25, 0
	s_add_u32 s55, s55, 0x100
	s_addc_u32 s56, s56, 0
	s_cmp_gt_u32 s57, 13
	s_cbranch_scc0 .LBB0_969
	s_and_b64 vcc, exec, s[12:13]
	s_cbranch_vccz .LBB0_972
	s_barrier

;     __host__ __device__ bool next(int i, Unit& u) const { const long L = (long)i * G + c; if (L >= nwg) return false; return unit_of((int)L, u); }
;     __host__ __device__ bool next(int i, Unit& u) const { const int L = i == 0 ? l0 : (i == 1 ? l1 : (i == 2 ? l2 : -1)); if (L < 0 || L >= s.nwg) return false; return s.unit_of(L, u); }
;     __host__ __device__ bool next(int i, Unit& u) const { const bool ok = s.next(i >> 1, u); u.kh = i & 1; return ok; }
; #define PG8_STAGE(bufoff, gbase, voff) do { _Pragma("unroll") for (int _i = 0; _i < 2; ++_i) \
;         __builtin_amdgcn_global_load_lds((const unsigned*)((const char*)(gbase) + (voff)[_i]), (PG8_LAS unsigned*)(lds + (bufoff) + ldsw + _i * 8192), 16, 0, 0); } while (0)
; #define PG8_LDA(dst, b, h) do { _Pragma("unroll") for (int m = 0; m < 4; ++m) _Pragma("unroll") for (int k = 0; k < 2; ++k) dst[m][k] = *(const PG8_LAS bf16x8*)(lds + PG8_SA(b, h) + aoff + m * 2048 + k * 1024); } while (0)
; template <class Epi, class Sched, bool ALIGN_EPI = false, bool SP2 = false>
; __device__ __forceinline__ void gemm_phase(PG8_LAS unsigned char* lds, const Gemm g, const Sched& S, const Epi& E) {
;     ...
;         const bool has_next = S.next(ui + 1, nxt);
;         const char* nA = has_next ? (const char*)g.A + (size_t)nxt.pm * tstep + nxt.kh * khb : cA; const char* nB = has_next ? (const char*)g.Bt + (size_t)nxt.pn * tstep + nxt.kh * khb : cB;
;         for (int t = 0; t < nt; t += 2) {
;             const bool last = (t == nt - 2);
;             const char* a1 = cA + (size_t)(t + 1) * kstep;
;             const char* a2 = last ? nA : cA + (size_t)(t + 2) * kstep; const char* b2 = last ? nB : cB + (size_t)(t + 2) * kstep;
;             const char* a3 = a2 + kstep; const char* b3 = b2 + kstep;
;             if (last && has_next) S.a_ready(nxt);
;             if constexpr (SP2) {
;             PG8_LDB(B0, 0, 0); PG8_LDB(B1, 0, 1); PG8_SCHED; PG8_LDA(At, 0, 0); PG8_STAGE(PG8_SA(1, 1), a1 + hstep, voffA);
;             PG8_WAIT_V(8); PG8_WAIT_L(0); PG8_BAR; PG8_MMA(0, 0, At, B0); PG8_MMA(0, 1, At, B1); PG8_BAR; PG8_SCHED;
;             PG8_LDA(At, 0, 1); PG8_STAGE(PG8_SB(0, 0), b2, voffB); PG8_STAGE(PG8_SB(0, 1), b2 + hstep, voffB); PG8_STAGE(PG8_SA(0, 0), a2, voffA);
;             PG8_WAIT_V(8); PG8_WAIT_L(0); PG8_BAR; PG8_MMA(1, 0, At, B0); PG8_MMA(1, 1, At, B1); PG8_BAR; PG8_SCHED;
.LBB0_1051:
	s_add_u32 s54, s24, 0x100
	s_addc_u32 s55, s25, 0
	s_mov_b32 s56, -2
	ds_read_b128 v[146:149], v153
	ds_read_b128 v[156:159], v153 offset:1024
	ds_read_b128 v[160:163], v153 offset:2048
	ds_read_b128 v[164:167], v153 offset:3072
	ds_read_b128 v[168:171], v154
	ds_read_b128 v[172:175], v154 offset:1024
	ds_read_b128 v[176:179], v154 offset:2048
	ds_read_b128 v[180:183], v154 offset:3072
	s_add_u32 s24, s22, 0x100
	s_addc_u32 s25, s23, 0
	s_cmp_eq_u32 s56, 40
	s_cselect_b32 s29, s3, s25
	s_cselect_b32 s28, s2, s24
	s_cselect_b32 s27, s21, s55
	s_cselect_b32 s26, s20, s54
	s_add_i32 m0, s38, 0xc000
	ds_read_b128 v[184:187], v155
	ds_read_b128 v[188:191], v155 offset:1024
	ds_read_b128 v[192:195], v155 offset:2048
	ds_read_b128 v[196:199], v155 offset:3072
	ds_read_b128 v[200:203], v155 offset:4096
	ds_read_b128 v[204:207], v155 offset:5120
	ds_read_b128 v[208:211], v155 offset:6144
	ds_read_b128 v[212:215], v155 offset:7168
	global_load_lds_dwordx4 v138, s[22:23]
	s_add_i32 m0, s38, 0xe000
	s_nop 0
	global_load_lds_dwordx4 v140, s[22:23]
	s_waitcnt vmcnt(8)
	s_waitcnt lgkmcnt(0)
	s_barrier
	v_mfma_f32_16x16x32_bf16 v[124:127], v[146:149], v[184:187], 0
	v_mfma_f32_16x16x32_bf16 v[120:123], v[160:163], v[184:187], 0
	v_mfma_f32_16x16x32_bf16 v[116:119], v[146:149], v[192:195], 0
	v_mfma_f32_16x16x32_bf16 v[112:115], v[160:163], v[192:195], 0
	v_mfma_f32_16x16x32_bf16 v[92:95], v[146:149], v[200:203], 0
	v_mfma_f32_16x16x32_bf16 v[88:91], v[160:163], v[200:203], 0
	v_mfma_f32_16x16x32_bf16 v[76:79], v[146:149], v[208:211], 0
	v_mfma_f32_16x16x32_bf16 v[72:75], v[160:163], v[208:211], 0
	v_mfma_f32_16x16x32_bf16 v[124:127], v[156:159], v[188:191], v[124:127]
	v_mfma_f32_16x16x32_bf16 v[120:123], v[164:167], v[188:191], v[120:123]
	v_mfma_f32_16x16x32_bf16 v[116:119], v[156:159], v[196:199], v[116:119]
	v_mfma_f32_16x16x32_bf16 v[112:115], v[164:167], v[196:199], v[112:115]
	v_mfma_f32_16x16x32_bf16 v[92:95], v[156:159], v[204:207], v[92:95]
	v_mfma_f32_16x16x32_bf16 v[88:91], v[164:167], v[204:207], v[88:91]
	v_mfma_f32_16x16x32_bf16 v[76:79], v[156:159], v[212:215], v[76:79]
	v_mfma_f32_16x16x32_bf16 v[72:75], v[164:167], v[212:215], v[72:75]
	v_mfma_f32_16x16x32_bf16 v[108:111], v[168:171], v[184:187], 0
	v_mfma_f32_16x16x32_bf16 v[104:107], v[176:179], v[184:187], 0
	v_mfma_f32_16x16x32_bf16 v[100:103], v[168:171], v[192:195], 0
	v_mfma_f32_16x16x32_bf16 v[96:99], v[176:179], v[192:195], 0
	v_mfma_f32_16x16x32_bf16 v[84:87], v[168:171], v[200:203], 0
	v_mfma_f32_16x16x32_bf16 v[80:83], v[176:179], v[200:203], 0
	v_mfma_f32_16x16x32_bf16 v[68:71], v[168:171], v[208:211], 0
	v_mfma_f32_16x16x32_bf16 v[64:67], v[176:179], v[208:211], 0
	v_mfma_f32_16x16x32_bf16 v[108:111], v[172:175], v[188:191], v[108:111]
	v_mfma_f32_16x16x32_bf16 v[104:107], v[180:183], v[188:191], v[104:107]
	v_mfma_f32_16x16x32_bf16 v[100:103], v[172:175], v[196:199], v[100:103]
	v_mfma_f32_16x16x32_bf16 v[96:99], v[180:183], v[196:199], v[96:99]
	v_mfma_f32_16x16x32_bf16 v[84:87], v[172:175], v[204:207], v[84:87]
	v_mfma_f32_16x16x32_bf16 v[80:83], v[180:183], v[204:207], v[80:83]
	v_mfma_f32_16x16x32_bf16 v[68:71], v[172:175], v[212:215], v[68:71]
	v_mfma_f32_16x16x32_bf16 v[64:67], v[180:183], v[212:215], v[64:67]
	s_barrier
	s_add_u32 s92, s26, s8
	s_addc_u32 s93, s27, s9
	s_add_u32 s94, s28, s8
	s_addc_u32 s95, s29, s9
	s_add_i32 s22, s46, s37
	s_mov_b32 m0, s22
	ds_read_b128 v[184:187], v155 offset:16384
	ds_read_b128 v[188:191], v155 offset:17408
	ds_read_b128 v[192:195], v155 offset:18432
	ds_read_b128 v[196:199], v155 offset:19456
	ds_read_b128 v[200:203], v155 offset:20480
	ds_read_b128 v[204:207], v155 offset:21504
	ds_read_b128 v[208:211], v155 offset:22528
	ds_read_b128 v[212:215], v155 offset:23552
	global_load_lds_dwordx4 v130, s[26:27]
	s_add_i32 m0, s22, 0x2000
	s_add_u32 s22, s26, 0xb0000
	s_addc_u32 s23, s27, 0
	s_add_i32 s57, s47, s37
	global_load_lds_dwordx4 v134, s[26:27]
	s_mov_b32 m0, s57
	s_nop 0
	global_load_lds_dwordx4 v130, s[22:23]
	s_add_i32 m0, s57, 0x2000
	s_nop 0
	global_load_lds_dwordx4 v134, s[22:23]
	s_mov_b32 m0, s38
	s_nop 0
	global_load_lds_dwordx4 v128, s[28:29]
	s_mov_b32 m0, s39
	s_nop 0
	global_load_lds_dwordx4 v132, s[28:29]
	s_waitcnt vmcnt(8)
	s_waitcnt lgkmcnt(0)
	s_barrier
	v_mfma_f32_16x16x32_bf16 v[60:63], v[146:149], v[184:187], 0
	v_mfma_f32_16x16x32_bf16 v[56:59], v[160:163], v[184:187], 0
	v_mfma_f32_16x16x32_bf16 v[44:47], v[146:149], v[192:195], 0
	v_mfma_f32_16x16x32_bf16 v[40:43], v[160:163], v[192:195], 0
	v_mfma_f32_16x16x32_bf16 v[28:31], v[146:149], v[200:203], 0
	v_mfma_f32_16x16x32_bf16 v[24:27], v[160:163], v[200:203], 0
	v_mfma_f32_16x16x32_bf16 v[12:15], v[146:149], v[208:211], 0
	v_mfma_f32_16x16x32_bf16 v[8:11], v[160:163], v[208:211], 0
	v_mfma_f32_16x16x32_bf16 v[60:63], v[156:159], v[188:191], v[60:63]
	v_mfma_f32_16x16x32_bf16 v[56:59], v[164:167], v[188:191], v[56:59]
	v_mfma_f32_16x16x32_bf16 v[44:47], v[156:159], v[196:199], v[44:47]
	v_mfma_f32_16x16x32_bf16 v[40:43], v[164:167], v[196:199], v[40:43]
	v_mfma_f32_16x16x32_bf16 v[28:31], v[156:159], v[204:207], v[28:31]
	v_mfma_f32_16x16x32_bf16 v[24:27], v[164:167], v[204:207], v[24:27]
	v_mfma_f32_16x16x32_bf16 v[12:15], v[156:159], v[212:215], v[12:15]
	v_mfma_f32_16x16x32_bf16 v[8:11], v[164:167], v[212:215], v[8:11]
	v_mfma_f32_16x16x32_bf16 v[52:55], v[168:171], v[184:187], 0
	v_mfma_f32_16x16x32_bf16 v[48:51], v[176:179], v[184:187], 0
	v_mfma_f32_16x16x32_bf16 v[36:39], v[168:171], v[192:195], 0
	v_mfma_f32_16x16x32_bf16 v[32:35], v[176:179], v[192:195], 0
	v_mfma_f32_16x16x32_bf16 v[20:23], v[168:171], v[200:203], 0
	v_mfma_f32_16x16x32_bf16 v[16:19], v[176:179], v[200:203], 0
	v_mfma_f32_16x16x32_bf16 v[4:7], v[168:171], v[208:211], 0
	v_mfma_f32_16x16x32_bf16 v[0:3], v[176:179], v[208:211], 0
	v_mfma_f32_16x16x32_bf16 v[52:55], v[172:175], v[188:191], v[52:55]
	v_mfma_f32_16x16x32_bf16 v[48:51], v[180:183], v[188:191], v[48:51]
	v_mfma_f32_16x16x32_bf16 v[36:39], v[172:175], v[196:199], v[36:39]
	v_mfma_f32_16x16x32_bf16 v[32:35], v[180:183], v[196:199], v[32:35]
	v_mfma_f32_16x16x32_bf16 v[20:23], v[172:175], v[204:207], v[20:23]
	v_mfma_f32_16x16x32_bf16 v[16:19], v[180:183], v[204:207], v[16:19]
	v_mfma_f32_16x16x32_bf16 v[4:7], v[172:175], v[212:215], v[4:7]
	v_mfma_f32_16x16x32_bf16 v[0:3], v[180:183], v[212:215], v[0:3]
	s_barrier
	s_branch .Lmy_peel_1052_mid
; #define PG8_STAGE(bufoff, gbase, voff) do { _Pragma("unroll") for (int _i = 0; _i < 2; ++_i) \
;         __builtin_amdgcn_global_load_lds((const unsigned*)((const char*)(gbase) + (voff)[_i]), (PG8_LAS unsigned*)(lds + (bufoff) + ldsw + _i * 8192), 16, 0, 0); } while (0)
; #define PG8_LDA(dst, b, h) do { _Pragma("unroll") for (int m = 0; m < 4; ++m) _Pragma("unroll") for (int k = 0; k < 2; ++k) dst[m][k] = *(const PG8_LAS bf16x8*)(lds + PG8_SA(b, h) + aoff + m * 2048 + k * 1024); } while (0)
; #define PG8_LDB(dst, b, h) do { _Pragma("unroll") for (int n = 0; n < 2; ++n) _Pragma("unroll") for (int k = 0; k < 2; ++k) dst[n][k] = *(const PG8_LAS bf16x8*)(lds + PG8_SB(b, h) + boff + n * 2048 + k * 1024); } while (0)
; #define PG8_MMA(ai, bj, At, Bt) do { __builtin_amdgcn_s_setprio(1); _Pragma("unroll") for (int m = 0; m < 4; ++m) _Pragma("unroll") for (int n = 0; n < 2; ++n) _Pragma("unroll") for (int k = 0; k < 2; ++k) \
;         acc[ai][bj][m][n] = __builtin_amdgcn_mfma_f32_16x16x32_bf16(Bt[n][k], At[m][k], acc[ai][bj][m][n], 0, 0, 0); __builtin_amdgcn_s_setprio(0); } while (0)
; #define PG8_WAIT_V(n) asm volatile("s_waitcnt vmcnt(" #n ")" ::: "memory")
; #define PG8_WAIT_L(n) asm volatile("s_waitcnt lgkmcnt(" #n ")" ::: "memory")
; template <class Epi, class Sched, bool ALIGN_EPI = false, bool SP2 = false>
; __device__ __forceinline__ void gemm_phase(PG8_LAS unsigned char* lds, const Gemm g, const Sched& S, const Epi& E) {
;     ...
;             const bool last = (t == nt - 2);
;             const char* a1 = cA + (size_t)(t + 1) * kstep;
;             const char* a2 = last ? nA : cA + (size_t)(t + 2) * kstep; const char* b2 = last ? nB : cB + (size_t)(t + 2) * kstep;
;             const char* a3 = a2 + kstep; const char* b3 = b2 + kstep;
;             if (last && has_next) S.a_ready(nxt);
;             if constexpr (SP2) {
;             PG8_LDB(B0, 0, 0); PG8_LDB(B1, 0, 1); PG8_SCHED; PG8_LDA(At, 0, 0); PG8_STAGE(PG8_SA(1, 1), a1 + hstep, voffA);
;             PG8_WAIT_V(8); PG8_WAIT_L(0); PG8_BAR; PG8_MMA(0, 0, At, B0); PG8_MMA(0, 1, At, B1); PG8_BAR; PG8_SCHED;
;             PG8_LDA(At, 0, 1); PG8_STAGE(PG8_SB(0, 0), b2, voffB); PG8_STAGE(PG8_SB(0, 1), b2 + hstep, voffB); PG8_STAGE(PG8_SA(0, 0), a2, voffA);
;             PG8_WAIT_V(8); PG8_WAIT_L(0); PG8_BAR; PG8_MMA(1, 0, At, B0); PG8_MMA(1, 1, At, B1); PG8_BAR; PG8_SCHED;
.LBB0_1052:
	ds_read_b128 v[146:149], v153
	ds_read_b128 v[156:159], v153 offset:1024
	ds_read_b128 v[160:163], v153 offset:2048
	ds_read_b128 v[164:167], v153 offset:3072
	ds_read_b128 v[168:171], v154
	ds_read_b128 v[172:175], v154 offset:1024
	ds_read_b128 v[176:179], v154 offset:2048
	ds_read_b128 v[180:183], v154 offset:3072
	s_add_u32 s24, s22, 0x100
	s_addc_u32 s25, s23, 0
	s_cmp_eq_u32 s56, 40
	s_cselect_b32 s29, s3, s25
	s_cselect_b32 s28, s2, s24
	s_cselect_b32 s27, s21, s55
	s_cselect_b32 s26, s20, s54
	s_add_i32 m0, s38, 0xc000
	ds_read_b128 v[184:187], v155
	ds_read_b128 v[188:191], v155 offset:1024
	ds_read_b128 v[192:195], v155 offset:2048
	ds_read_b128 v[196:199], v155 offset:3072
	ds_read_b128 v[200:203], v155 offset:4096
	ds_read_b128 v[204:207], v155 offset:5120
	ds_read_b128 v[208:211], v155 offset:6144
	ds_read_b128 v[212:215], v155 offset:7168
	global_load_lds_dwordx4 v138, s[22:23]
	s_add_i32 m0, s38, 0xe000
	s_nop 0
	global_load_lds_dwordx4 v140, s[22:23]
	s_waitcnt vmcnt(8)
	s_waitcnt lgkmcnt(0)
	s_barrier
	v_mfma_f32_16x16x32_bf16 v[124:127], v[146:149], v[184:187], v[124:127]
	v_mfma_f32_16x16x32_bf16 v[120:123], v[160:163], v[184:187], v[120:123]
	v_mfma_f32_16x16x32_bf16 v[116:119], v[146:149], v[192:195], v[116:119]
	v_mfma_f32_16x16x32_bf16 v[112:115], v[160:163], v[192:195], v[112:115]
	v_mfma_f32_16x16x32_bf16 v[92:95], v[146:149], v[200:203], v[92:95]
	v_mfma_f32_16x16x32_bf16 v[88:91], v[160:163], v[200:203], v[88:91]
	v_mfma_f32_16x16x32_bf16 v[76:79], v[146:149], v[208:211], v[76:79]
	v_mfma_f32_16x16x32_bf16 v[72:75], v[160:163], v[208:211], v[72:75]
	v_mfma_f32_16x16x32_bf16 v[124:127], v[156:159], v[188:191], v[124:127]
	v_mfma_f32_16x16x32_bf16 v[120:123], v[164:167], v[188:191], v[120:123]
	v_mfma_f32_16x16x32_bf16 v[116:119], v[156:159], v[196:199], v[116:119]
	v_mfma_f32_16x16x32_bf16 v[112:115], v[164:167], v[196:199], v[112:115]
	v_mfma_f32_16x16x32_bf16 v[92:95], v[156:159], v[204:207], v[92:95]
	v_mfma_f32_16x16x32_bf16 v[88:91], v[164:167], v[204:207], v[88:91]
	v_mfma_f32_16x16x32_bf16 v[76:79], v[156:159], v[212:215], v[76:79]
	v_mfma_f32_16x16x32_bf16 v[72:75], v[164:167], v[212:215], v[72:75]
	v_mfma_f32_16x16x32_bf16 v[108:111], v[168:171], v[184:187], v[108:111]
	v_mfma_f32_16x16x32_bf16 v[104:107], v[176:179], v[184:187], v[104:107]
	v_mfma_f32_16x16x32_bf16 v[100:103], v[168:171], v[192:195], v[100:103]
	v_mfma_f32_16x16x32_bf16 v[96:99], v[176:179], v[192:195], v[96:99]
	v_mfma_f32_16x16x32_bf16 v[84:87], v[168:171], v[200:203], v[84:87]
	v_mfma_f32_16x16x32_bf16 v[80:83], v[176:179], v[200:203], v[80:83]
	v_mfma_f32_16x16x32_bf16 v[68:71], v[168:171], v[208:211], v[68:71]
	v_mfma_f32_16x16x32_bf16 v[64:67], v[176:179], v[208:211], v[64:67]
	v_mfma_f32_16x16x32_bf16 v[108:111], v[172:175], v[188:191], v[108:111]
	v_mfma_f32_16x16x32_bf16 v[104:107], v[180:183], v[188:191], v[104:107]
	v_mfma_f32_16x16x32_bf16 v[100:103], v[172:175], v[196:199], v[100:103]
	v_mfma_f32_16x16x32_bf16 v[96:99], v[180:183], v[196:199], v[96:99]
	v_mfma_f32_16x16x32_bf16 v[84:87], v[172:175], v[204:207], v[84:87]
	v_mfma_f32_16x16x32_bf16 v[80:83], v[180:183], v[204:207], v[80:83]
	v_mfma_f32_16x16x32_bf16 v[68:71], v[172:175], v[212:215], v[68:71]
	v_mfma_f32_16x16x32_bf16 v[64:67], v[180:183], v[212:215], v[64:67]
	s_barrier
	s_add_u32 s92, s26, s8
	s_addc_u32 s93, s27, s9
	s_add_u32 s94, s28, s8
	s_addc_u32 s95, s29, s9
	s_add_i32 s22, s46, s37
	s_mov_b32 m0, s22
	ds_read_b128 v[184:187], v155 offset:16384
	ds_read_b128 v[188:191], v155 offset:17408
	ds_read_b128 v[192:195], v155 offset:18432
	ds_read_b128 v[196:199], v155 offset:19456
	ds_read_b128 v[200:203], v155 offset:20480
	ds_read_b128 v[204:207], v155 offset:21504
	ds_read_b128 v[208:211], v155 offset:22528
	ds_read_b128 v[212:215], v155 offset:23552
	global_load_lds_dwordx4 v130, s[26:27]
	s_add_i32 m0, s22, 0x2000
	s_add_u32 s22, s26, 0xb0000
	s_addc_u32 s23, s27, 0
	s_add_i32 s57, s47, s37
	global_load_lds_dwordx4 v134, s[26:27]
	s_mov_b32 m0, s57
	s_nop 0
	global_load_lds_dwordx4 v130, s[22:23]
	s_add_i32 m0, s57, 0x2000
	s_nop 0
	global_load_lds_dwordx4 v134, s[22:23]
	s_mov_b32 m0, s38
	s_nop 0
	global_load_lds_dwordx4 v128, s[28:29]
	s_mov_b32 m0, s39
	s_nop 0
	global_load_lds_dwordx4 v132, s[28:29]
	s_waitcnt vmcnt(8)
	s_waitcnt lgkmcnt(0)
	s_barrier
	v_mfma_f32_16x16x32_bf16 v[60:63], v[146:149], v[184:187], v[60:63]
	v_mfma_f32_16x16x32_bf16 v[56:59], v[160:163], v[184:187], v[56:59]
	v_mfma_f32_16x16x32_bf16 v[44:47], v[146:149], v[192:195], v[44:47]
	v_mfma_f32_16x16x32_bf16 v[40:43], v[160:163], v[192:195], v[40:43]
	v_mfma_f32_16x16x32_bf16 v[28:31], v[146:149], v[200:203], v[28:31]
	v_mfma_f32_16x16x32_bf16 v[24:27], v[160:163], v[200:203], v[24:27]
	v_mfma_f32_16x16x32_bf16 v[12:15], v[146:149], v[208:211], v[12:15]
	v_mfma_f32_16x16x32_bf16 v[8:11], v[160:163], v[208:211], v[8:11]
	v_mfma_f32_16x16x32_bf16 v[60:63], v[156:159], v[188:191], v[60:63]
	v_mfma_f32_16x16x32_bf16 v[56:59], v[164:167], v[188:191], v[56:59]
	v_mfma_f32_16x16x32_bf16 v[44:47], v[156:159], v[196:199], v[44:47]
	v_mfma_f32_16x16x32_bf16 v[40:43], v[164:167], v[196:199], v[40:43]
	v_mfma_f32_16x16x32_bf16 v[28:31], v[156:159], v[204:207], v[28:31]
	v_mfma_f32_16x16x32_bf16 v[24:27], v[164:167], v[204:207], v[24:27]
	v_mfma_f32_16x16x32_bf16 v[12:15], v[156:159], v[212:215], v[12:15]
	v_mfma_f32_16x16x32_bf16 v[8:11], v[164:167], v[212:215], v[8:11]
	v_mfma_f32_16x16x32_bf16 v[52:55], v[168:171], v[184:187], v[52:55]
	v_mfma_f32_16x16x32_bf16 v[48:51], v[176:179], v[184:187], v[48:51]
	v_mfma_f32_16x16x32_bf16 v[36:39], v[168:171], v[192:195], v[36:39]
	v_mfma_f32_16x16x32_bf16 v[32:35], v[176:179], v[192:195], v[32:35]
	v_mfma_f32_16x16x32_bf16 v[20:23], v[168:171], v[200:203], v[20:23]
	v_mfma_f32_16x16x32_bf16 v[16:19], v[176:179], v[200:203], v[16:19]
	v_mfma_f32_16x16x32_bf16 v[4:7], v[168:171], v[208:211], v[4:7]
	v_mfma_f32_16x16x32_bf16 v[0:3], v[176:179], v[208:211], v[0:3]
	v_mfma_f32_16x16x32_bf16 v[52:55], v[172:175], v[188:191], v[52:55]
	v_mfma_f32_16x16x32_bf16 v[48:51], v[180:183], v[188:191], v[48:51]
	v_mfma_f32_16x16x32_bf16 v[36:39], v[172:175], v[196:199], v[36:39]
	v_mfma_f32_16x16x32_bf16 v[32:35], v[180:183], v[196:199], v[32:35]
	v_mfma_f32_16x16x32_bf16 v[20:23], v[172:175], v[204:207], v[20:23]
	v_mfma_f32_16x16x32_bf16 v[16:19], v[180:183], v[204:207], v[16:19]
	v_mfma_f32_16x16x32_bf16 v[4:7], v[172:175], v[212:215], v[4:7]
	v_mfma_f32_16x16x32_bf16 v[0:3], v[180:183], v[212:215], v[0:3]
	s_barrier
; #define PG8_STAGE(bufoff, gbase, voff) do { _Pragma("unroll") for (int _i = 0; _i < 2; ++_i) \
;         __builtin_amdgcn_global_load_lds((const unsigned*)((const char*)(gbase) + (voff)[_i]), (PG8_LAS unsigned*)(lds + (bufoff) + ldsw + _i * 8192), 16, 0, 0); } while (0)
; #define PG8_LDA(dst, b, h) do { _Pragma("unroll") for (int m = 0; m < 4; ++m) _Pragma("unroll") for (int k = 0; k < 2; ++k) dst[m][k] = *(const PG8_LAS bf16x8*)(lds + PG8_SA(b, h) + aoff + m * 2048 + k * 1024); } while (0)
; #define PG8_LDB(dst, b, h) do { _Pragma("unroll") for (int n = 0; n < 2; ++n) _Pragma("unroll") for (int k = 0; k < 2; ++k) dst[n][k] = *(const PG8_LAS bf16x8*)(lds + PG8_SB(b, h) + boff + n * 2048 + k * 1024); } while (0)
; #define PG8_MMA(ai, bj, At, Bt) do { __builtin_amdgcn_s_setprio(1); _Pragma("unroll") for (int m = 0; m < 4; ++m) _Pragma("unroll") for (int n = 0; n < 2; ++n) _Pragma("unroll") for (int k = 0; k < 2; ++k) \
;         acc[ai][bj][m][n] = __builtin_amdgcn_mfma_f32_16x16x32_bf16(Bt[n][k], At[m][k], acc[ai][bj][m][n], 0, 0, 0); __builtin_amdgcn_s_setprio(0); } while (0)
; #define PG8_WAIT_V(n) asm volatile("s_waitcnt vmcnt(" #n ")" ::: "memory")
; #define PG8_WAIT_L(n) asm volatile("s_waitcnt lgkmcnt(" #n ")" ::: "memory")
; #define PG8_BAR __builtin_amdgcn_s_barrier()
; #define PG8_SCHED __builtin_amdgcn_sched_barrier(0)
; template <class Epi, class Sched, bool ALIGN_EPI = false, bool SP2 = false>
; __device__ __forceinline__ void gemm_phase(PG8_LAS unsigned char* lds, const Gemm g, const Sched& S, const Epi& E) {
;     ...
;             PG8_LDB(B0, 1, 0); PG8_LDB(B1, 1, 1); PG8_SCHED; PG8_LDA(At, 1, 0); PG8_STAGE(PG8_SA(0, 1), a2 + hstep, voffA);
;             PG8_WAIT_V(8); PG8_WAIT_L(0); PG8_BAR; PG8_MMA(0, 0, At, B0); PG8_MMA(0, 1, At, B1); PG8_BAR; PG8_SCHED;
;             PG8_LDA(At, 1, 1); PG8_STAGE(PG8_SB(1, 0), b3, voffB); PG8_STAGE(PG8_SB(1, 1), b3 + hstep, voffB); PG8_STAGE(PG8_SA(1, 0), a3, voffA);
;             PG8_WAIT_V(8); PG8_WAIT_L(0); PG8_BAR; PG8_MMA(1, 0, At, B0); PG8_MMA(1, 1, At, B1); PG8_BAR; PG8_SCHED;
.Lmy_peel_1052_mid:
	s_add_i32 s57, 0, 0x18000
	s_add_i32 s58, 0, 0x1c000
	v_add_u32_e32 v164, s57, v152
	v_add_u32_e32 v180, s58, v152
	ds_read_b128 v[146:149], v164
	ds_read_b128 v[156:159], v164 offset:1024
	ds_read_b128 v[160:163], v164 offset:2048
	ds_read_b128 v[164:167], v164 offset:3072
	ds_read_b128 v[168:171], v180
	ds_read_b128 v[172:175], v180 offset:1024
	ds_read_b128 v[176:179], v180 offset:2048
	ds_read_b128 v[180:183], v180 offset:3072
	s_add_u32 s22, s28, 0xb0000
	s_addc_u32 s23, s29, 0
	s_mov_b32 m0, s40
	ds_read_b128 v[184:187], v155 offset:32768
	ds_read_b128 v[188:191], v155 offset:33792
	ds_read_b128 v[192:195], v155 offset:34816
	ds_read_b128 v[196:199], v155 offset:35840
	ds_read_b128 v[200:203], v155 offset:36864
	ds_read_b128 v[204:207], v155 offset:37888
	ds_read_b128 v[208:211], v155 offset:38912
	ds_read_b128 v[212:215], v155 offset:39936
	global_load_lds_dwordx4 v128, s[22:23]
	s_mov_b32 m0, s41
	s_nop 0
	global_load_lds_dwordx4 v132, s[22:23]
	s_waitcnt vmcnt(8)
	s_waitcnt lgkmcnt(0)
	s_barrier
	v_mfma_f32_16x16x32_bf16 v[124:127], v[146:149], v[184:187], v[124:127]
	v_mfma_f32_16x16x32_bf16 v[120:123], v[160:163], v[184:187], v[120:123]
	v_mfma_f32_16x16x32_bf16 v[116:119], v[146:149], v[192:195], v[116:119]
	v_mfma_f32_16x16x32_bf16 v[112:115], v[160:163], v[192:195], v[112:115]
	v_mfma_f32_16x16x32_bf16 v[92:95], v[146:149], v[200:203], v[92:95]
	v_mfma_f32_16x16x32_bf16 v[88:91], v[160:163], v[200:203], v[88:91]
	v_mfma_f32_16x16x32_bf16 v[76:79], v[146:149], v[208:211], v[76:79]
	v_mfma_f32_16x16x32_bf16 v[72:75], v[160:163], v[208:211], v[72:75]
	v_mfma_f32_16x16x32_bf16 v[124:127], v[156:159], v[188:191], v[124:127]
	v_mfma_f32_16x16x32_bf16 v[120:123], v[164:167], v[188:191], v[120:123]
	v_mfma_f32_16x16x32_bf16 v[116:119], v[156:159], v[196:199], v[116:119]
	v_mfma_f32_16x16x32_bf16 v[112:115], v[164:167], v[196:199], v[112:115]
	v_mfma_f32_16x16x32_bf16 v[92:95], v[156:159], v[204:207], v[92:95]
	v_mfma_f32_16x16x32_bf16 v[88:91], v[164:167], v[204:207], v[88:91]
	v_mfma_f32_16x16x32_bf16 v[76:79], v[156:159], v[212:215], v[76:79]
	v_mfma_f32_16x16x32_bf16 v[72:75], v[164:167], v[212:215], v[72:75]
	v_mfma_f32_16x16x32_bf16 v[108:111], v[168:171], v[184:187], v[108:111]
	v_mfma_f32_16x16x32_bf16 v[104:107], v[176:179], v[184:187], v[104:107]
	v_mfma_f32_16x16x32_bf16 v[100:103], v[168:171], v[192:195], v[100:103]
	v_mfma_f32_16x16x32_bf16 v[96:99], v[176:179], v[192:195], v[96:99]
	v_mfma_f32_16x16x32_bf16 v[84:87], v[168:171], v[200:203], v[84:87]
	v_mfma_f32_16x16x32_bf16 v[80:83], v[176:179], v[200:203], v[80:83]
	v_mfma_f32_16x16x32_bf16 v[68:71], v[168:171], v[208:211], v[68:71]
	v_mfma_f32_16x16x32_bf16 v[64:67], v[176:179], v[208:211], v[64:67]
	v_mfma_f32_16x16x32_bf16 v[108:111], v[172:175], v[188:191], v[108:111]
	v_mfma_f32_16x16x32_bf16 v[104:107], v[180:183], v[188:191], v[104:107]
	v_mfma_f32_16x16x32_bf16 v[100:103], v[172:175], v[196:199], v[100:103]
	v_mfma_f32_16x16x32_bf16 v[96:99], v[180:183], v[196:199], v[96:99]
	v_mfma_f32_16x16x32_bf16 v[84:87], v[172:175], v[204:207], v[84:87]
	v_mfma_f32_16x16x32_bf16 v[80:83], v[180:183], v[204:207], v[80:83]
	v_mfma_f32_16x16x32_bf16 v[68:71], v[172:175], v[212:215], v[68:71]
	v_mfma_f32_16x16x32_bf16 v[64:67], v[180:183], v[212:215], v[64:67]
	s_barrier
	s_add_i32 s22, s57, s37
	s_mov_b32 m0, s22
	ds_read_b128 v[184:187], v155 offset:49152
	ds_read_b128 v[188:191], v155 offset:50176
	ds_read_b128 v[192:195], v155 offset:51200
	ds_read_b128 v[196:199], v155 offset:52224
	ds_read_b128 v[200:203], v155 offset:53248
	ds_read_b128 v[204:207], v155 offset:54272
	ds_read_b128 v[208:211], v155 offset:55296
	ds_read_b128 v[212:215], v155 offset:56320
	global_load_lds_dwordx4 v130, s[92:93]
	s_add_i32 m0, s22, 0x2000
	s_add_u32 s22, s26, 0xb0080
	s_addc_u32 s23, s27, 0
	s_add_i32 s26, s58, s37
	global_load_lds_dwordx4 v134, s[92:93]
	s_mov_b32 m0, s26
	s_nop 0
	global_load_lds_dwordx4 v130, s[22:23]
	s_add_i32 m0, s26, 0x2000
	s_nop 0
	global_load_lds_dwordx4 v134, s[22:23]
	s_mov_b32 m0, s43
	s_nop 0
	global_load_lds_dwordx4 v128, s[94:95]
	s_mov_b32 m0, s44
	s_nop 0
	global_load_lds_dwordx4 v132, s[94:95]
	s_waitcnt vmcnt(8)
	s_waitcnt lgkmcnt(0)
	s_barrier
	v_mfma_f32_16x16x32_bf16 v[60:63], v[146:149], v[184:187], v[60:63]
	v_mfma_f32_16x16x32_bf16 v[56:59], v[160:163], v[184:187], v[56:59]
	v_mfma_f32_16x16x32_bf16 v[44:47], v[146:149], v[192:195], v[44:47]
	v_mfma_f32_16x16x32_bf16 v[40:43], v[160:163], v[192:195], v[40:43]
	v_mfma_f32_16x16x32_bf16 v[28:31], v[146:149], v[200:203], v[28:31]
	v_mfma_f32_16x16x32_bf16 v[24:27], v[160:163], v[200:203], v[24:27]
	v_mfma_f32_16x16x32_bf16 v[12:15], v[146:149], v[208:211], v[12:15]
	v_mfma_f32_16x16x32_bf16 v[8:11], v[160:163], v[208:211], v[8:11]
	v_mfma_f32_16x16x32_bf16 v[60:63], v[156:159], v[188:191], v[60:63]
	v_mfma_f32_16x16x32_bf16 v[56:59], v[164:167], v[188:191], v[56:59]
	v_mfma_f32_16x16x32_bf16 v[44:47], v[156:159], v[196:199], v[44:47]
	v_mfma_f32_16x16x32_bf16 v[40:43], v[164:167], v[196:199], v[40:43]
	v_mfma_f32_16x16x32_bf16 v[28:31], v[156:159], v[204:207], v[28:31]
	v_mfma_f32_16x16x32_bf16 v[24:27], v[164:167], v[204:207], v[24:27]
	v_mfma_f32_16x16x32_bf16 v[12:15], v[156:159], v[212:215], v[12:15]
	v_mfma_f32_16x16x32_bf16 v[8:11], v[164:167], v[212:215], v[8:11]
	v_mfma_f32_16x16x32_bf16 v[52:55], v[168:171], v[184:187], v[52:55]
	v_mfma_f32_16x16x32_bf16 v[48:51], v[176:179], v[184:187], v[48:51]
	v_mfma_f32_16x16x32_bf16 v[36:39], v[168:171], v[192:195], v[36:39]
	v_mfma_f32_16x16x32_bf16 v[32:35], v[176:179], v[192:195], v[32:35]
	v_mfma_f32_16x16x32_bf16 v[20:23], v[168:171], v[200:203], v[20:23]
	v_mfma_f32_16x16x32_bf16 v[16:19], v[176:179], v[200:203], v[16:19]
	v_mfma_f32_16x16x32_bf16 v[4:7], v[168:171], v[208:211], v[4:7]
	v_mfma_f32_16x16x32_bf16 v[0:3], v[176:179], v[208:211], v[0:3]
	v_mfma_f32_16x16x32_bf16 v[52:55], v[172:175], v[188:191], v[52:55]
	v_mfma_f32_16x16x32_bf16 v[48:51], v[180:183], v[188:191], v[48:51]
	v_mfma_f32_16x16x32_bf16 v[36:39], v[172:175], v[196:199], v[36:39]
	v_mfma_f32_16x16x32_bf16 v[32:35], v[180:183], v[196:199], v[32:35]
	v_mfma_f32_16x16x32_bf16 v[20:23], v[172:175], v[204:207], v[20:23]
	v_mfma_f32_16x16x32_bf16 v[16:19], v[180:183], v[204:207], v[16:19]
	v_mfma_f32_16x16x32_bf16 v[4:7], v[172:175], v[212:215], v[4:7]
	v_mfma_f32_16x16x32_bf16 v[0:3], v[180:183], v[212:215], v[0:3]
	s_barrier
	s_add_i32 s56, s56, 2
	s_add_u32 s54, s54, 0x100
	s_addc_u32 s55, s55, 0
	s_cmp_gt_u32 s56, 41
	s_mov_b64 s[22:23], s[24:25]
	s_cbranch_scc0 .LBB0_1052
	s_and_b64 vcc, exec, s[10:11]
	s_cbranch_vccz .LBB0_1055
	s_barrier
